# v027 + removed the s_setprio 0 / s_setprio 1 pair in the middle of each 32-MFMA segment
# speedup vs baseline: 1.0243x; 1.0021x over previous
; #define PG8_STAGE(bufoff, gbase, voff) do { _Pragma("unroll") for (int _i = 0; _i < 2; ++_i) \
;         __builtin_amdgcn_global_load_lds((const unsigned*)((const char*)(gbase) + (voff)[_i]), (LAS unsigned*)(lds + (bufoff) + ldsw + _i * 8192), 16, 0, 0); } while (0)
; #define PG8_LDA(dst, b, h) do { _Pragma("unroll") for (int m = 0; m < 4; ++m) _Pragma("unroll") for (int k = 0; k < 2; ++k) dst[m][k] = *(const LAS bf16x8*)(lds + PG8_SA(b, h) + aoff + m * 2048 + k * 1024); } while (0)
; #define PG8_LDB(dst, b, h) do { _Pragma("unroll") for (int n = 0; n < 2; ++n) _Pragma("unroll") for (int k = 0; k < 2; ++k) dst[n][k] = *(const LAS bf16x8*)(lds + PG8_SB(b, h) + boff + n * 2048 + k * 1024); } while (0)
; #define PG8_MMA(ai, bj, At, Bt) do { __builtin_amdgcn_s_setprio(1); _Pragma("unroll") for (int m = 0; m < 4; ++m) _Pragma("unroll") for (int n = 0; n < 2; ++n) _Pragma("unroll") for (int k = 0; k < 2; ++k) \
;         acc[ai][bj][m][n] = __builtin_amdgcn_mfma_f32_16x16x32_bf16(Bt[n][k], At[m][k], acc[ai][bj][m][n], 0, 0, 0); __builtin_amdgcn_s_setprio(0); } while (0)
; #define PG8_WAIT_V(n) asm volatile("s_waitcnt vmcnt(" #n ")" ::: "memory")
; #define PG8_WAIT_L(n) asm volatile("s_waitcnt lgkmcnt(" #n ")" ::: "memory")
; #define PG8_BAR __builtin_amdgcn_s_barrier()
; #define PG8_SCHED __builtin_amdgcn_sched_barrier(0)
; template <class Epi, class Sched>
; DI void gemm_phase(LAS unsigned char* lds, const Gemm g, const Sched& S, const Epi& E) {
;     ...
;             const bool last = (t == nt - 2);
;             const char* a1 = cA + (size_t)(t + 1) * kstep;
;             const char* a2 = last ? nA : cA + (size_t)(t + 2) * kstep; const char* b2 = last ? nB : cB + (size_t)(t + 2) * kstep;
;             const char* a3 = a2 + kstep; const char* b3 = b2 + kstep;
;             PG8_LDB(B0, 0, 0); PG8_LDB(B1, 0, 1); PG8_SCHED; PG8_LDA(At, 0, 0); PG8_STAGE(PG8_SA(1, 1), a1 + hstepA, voffA);
;             PG8_WAIT_V(8); PG8_WAIT_L(0); PG8_BAR; PG8_MMA(0, 0, At, B0); PG8_MMA(0, 1, At, B1); PG8_BAR; PG8_SCHED;
;             PG8_LDA(At, 0, 1); PG8_STAGE(PG8_SB(0, 0), b2, voffB); PG8_STAGE(PG8_SB(0, 1), b2 + hstepB, voffB); PG8_STAGE(PG8_SA(0, 0), a2, voffA);
;             PG8_WAIT_V(8); PG8_WAIT_L(0); PG8_BAR; PG8_MMA(1, 0, At, B0); PG8_MMA(1, 1, At, B1); PG8_BAR; PG8_SCHED;
.LBB0_179:
	ds_read_b128 v[168:171], v162
	ds_read_b128 v[172:175], v162 offset:1024
	ds_read_b128 v[176:179], v162 offset:2048
	ds_read_b128 v[180:183], v162 offset:3072
	ds_read_b128 v[186:189], v163
	ds_read_b128 v[190:193], v163 offset:1024
	ds_read_b128 v[194:197], v163 offset:2048
	ds_read_b128 v[198:201], v163 offset:3072
	s_add_u32 s42, s40, 0xfffc0080
	s_addc_u32 s43, s41, -1
	s_cmp_eq_u32 s65, 12
	s_cselect_b32 s45, s35, s43
	s_cselect_b32 s44, s61, s42
	s_cselect_b32 s43, s21, s64
	s_cselect_b32 s42, s62, s63
	v_lshl_add_u64 v[234:235], s[40:41], 0, v[138:139]
	s_add_i32 m0, s49, 0xc000
	ds_read_b128 v[202:205], v160
	ds_read_b128 v[206:209], v160 offset:1024
	ds_read_b128 v[210:213], v160 offset:2048
	ds_read_b128 v[214:217], v160 offset:3072
	ds_read_b128 v[218:221], v160 offset:4096
	ds_read_b128 v[222:225], v160 offset:5120
	ds_read_b128 v[226:229], v160 offset:6144
	ds_read_b128 v[230:233], v160 offset:7168
	global_load_lds_dwordx4 v[234:235], off
	v_lshl_add_u64 v[234:235], s[40:41], 0, v[140:141]
	s_add_i32 m0, s49, 0xe000
	s_nop 0
	global_load_lds_dwordx4 v[234:235], off
	s_waitcnt vmcnt(8)
	s_waitcnt lgkmcnt(0)
	s_barrier
	s_setprio 1
	v_mfma_f32_16x16x32_bf16 v[126:129], v[168:171], v[202:205], v[126:129]
	v_mfma_f32_16x16x32_bf16 v[118:121], v[176:179], v[202:205], v[118:121]
	v_mfma_f32_16x16x32_bf16 v[110:113], v[168:171], v[210:213], v[110:113]
	v_mfma_f32_16x16x32_bf16 v[102:105], v[176:179], v[210:213], v[102:105]
	v_mfma_f32_16x16x32_bf16 v[94:97], v[168:171], v[218:221], v[94:97]
	v_mfma_f32_16x16x32_bf16 v[86:89], v[176:179], v[218:221], v[86:89]
	v_mfma_f32_16x16x32_bf16 v[78:81], v[168:171], v[226:229], v[78:81]
	v_mfma_f32_16x16x32_bf16 v[70:73], v[176:179], v[226:229], v[70:73]
	v_mfma_f32_16x16x32_bf16 v[126:129], v[172:175], v[206:209], v[126:129]
	v_mfma_f32_16x16x32_bf16 v[118:121], v[180:183], v[206:209], v[118:121]
	v_mfma_f32_16x16x32_bf16 v[110:113], v[172:175], v[214:217], v[110:113]
	v_mfma_f32_16x16x32_bf16 v[102:105], v[180:183], v[214:217], v[102:105]
	v_mfma_f32_16x16x32_bf16 v[94:97], v[172:175], v[222:225], v[94:97]
	v_mfma_f32_16x16x32_bf16 v[86:89], v[180:183], v[222:225], v[86:89]
	v_mfma_f32_16x16x32_bf16 v[78:81], v[172:175], v[230:233], v[78:81]
	v_mfma_f32_16x16x32_bf16 v[70:73], v[180:183], v[230:233], v[70:73]
	v_mfma_f32_16x16x32_bf16 v[122:125], v[186:189], v[202:205], v[122:125]
	v_mfma_f32_16x16x32_bf16 v[114:117], v[194:197], v[202:205], v[114:117]
	v_mfma_f32_16x16x32_bf16 v[106:109], v[186:189], v[210:213], v[106:109]
	v_mfma_f32_16x16x32_bf16 v[98:101], v[194:197], v[210:213], v[98:101]
	v_mfma_f32_16x16x32_bf16 v[90:93], v[186:189], v[218:221], v[90:93]
	v_mfma_f32_16x16x32_bf16 v[82:85], v[194:197], v[218:221], v[82:85]
	v_mfma_f32_16x16x32_bf16 v[74:77], v[186:189], v[226:229], v[74:77]
	v_mfma_f32_16x16x32_bf16 v[66:69], v[194:197], v[226:229], v[66:69]
	v_mfma_f32_16x16x32_bf16 v[122:125], v[190:193], v[206:209], v[122:125]
	v_mfma_f32_16x16x32_bf16 v[114:117], v[198:201], v[206:209], v[114:117]
	v_mfma_f32_16x16x32_bf16 v[106:109], v[190:193], v[214:217], v[106:109]
	v_mfma_f32_16x16x32_bf16 v[98:101], v[198:201], v[214:217], v[98:101]
	v_mfma_f32_16x16x32_bf16 v[90:93], v[190:193], v[222:225], v[90:93]
	v_mfma_f32_16x16x32_bf16 v[82:85], v[198:201], v[222:225], v[82:85]
	v_mfma_f32_16x16x32_bf16 v[74:77], v[190:193], v[230:233], v[74:77]
	v_mfma_f32_16x16x32_bf16 v[66:69], v[198:201], v[230:233], v[66:69]
	s_setprio 0
	s_barrier
	s_add_i32 s66, s57, s46
	v_lshl_add_u64 v[234:235], s[42:43], 0, v[134:135]
	s_mov_b32 m0, s66
	ds_read_b128 v[202:205], v160 offset:16384
	ds_read_b128 v[206:209], v160 offset:17408
	ds_read_b128 v[210:213], v160 offset:18432
	ds_read_b128 v[214:217], v160 offset:19456
	ds_read_b128 v[218:221], v160 offset:20480
	ds_read_b128 v[222:225], v160 offset:21504
	ds_read_b128 v[226:229], v160 offset:22528
	ds_read_b128 v[230:233], v160 offset:23552
	global_load_lds_dwordx4 v[234:235], off
	s_add_i32 m0, s66, 0x2000
	s_add_u32 s66, s42, 0x40000
	v_lshl_add_u64 v[236:237], s[42:43], 0, v[130:131]
	s_addc_u32 s67, s43, 0
	s_add_i32 s68, s58, s46
	global_load_lds_dwordx4 v[236:237], off
	v_lshl_add_u64 v[238:239], s[66:67], 0, v[134:135]
	s_mov_b32 m0, s68
	v_lshl_add_u64 v[240:241], s[44:45], 0, v[132:133]
	global_load_lds_dwordx4 v[238:239], off
	v_lshl_add_u64 v[238:239], s[66:67], 0, v[130:131]
	s_add_i32 m0, s68, 0x2000
	s_nop 0
	global_load_lds_dwordx4 v[238:239], off
	v_lshl_add_u64 v[238:239], s[44:45], 0, v[136:137]
	s_mov_b32 m0, s49
	s_nop 0
	global_load_lds_dwordx4 v[238:239], off
	s_mov_b32 m0, s50
	s_nop 0
	global_load_lds_dwordx4 v[240:241], off
	s_waitcnt vmcnt(8)
	s_waitcnt lgkmcnt(0)
	s_barrier
; #define PG8_STAGE(bufoff, gbase, voff) do { _Pragma("unroll") for (int _i = 0; _i < 2; ++_i) \
;         __builtin_amdgcn_global_load_lds((const unsigned*)((const char*)(gbase) + (voff)[_i]), (LAS unsigned*)(lds + (bufoff) + ldsw + _i * 8192), 16, 0, 0); } while (0)
; #define PG8_LDA(dst, b, h) do { _Pragma("unroll") for (int m = 0; m < 4; ++m) _Pragma("unroll") for (int k = 0; k < 2; ++k) dst[m][k] = *(const LAS bf16x8*)(lds + PG8_SA(b, h) + aoff + m * 2048 + k * 1024); } while (0)
; #define PG8_LDB(dst, b, h) do { _Pragma("unroll") for (int n = 0; n < 2; ++n) _Pragma("unroll") for (int k = 0; k < 2; ++k) dst[n][k] = *(const LAS bf16x8*)(lds + PG8_SB(b, h) + boff + n * 2048 + k * 1024); } while (0)
; #define PG8_MMA(ai, bj, At, Bt) do { __builtin_amdgcn_s_setprio(1); _Pragma("unroll") for (int m = 0; m < 4; ++m) _Pragma("unroll") for (int n = 0; n < 2; ++n) _Pragma("unroll") for (int k = 0; k < 2; ++k) \
;         acc[ai][bj][m][n] = __builtin_amdgcn_mfma_f32_16x16x32_bf16(Bt[n][k], At[m][k], acc[ai][bj][m][n], 0, 0, 0); __builtin_amdgcn_s_setprio(0); } while (0)
; #define PG8_WAIT_V(n) asm volatile("s_waitcnt vmcnt(" #n ")" ::: "memory")
; #define PG8_WAIT_L(n) asm volatile("s_waitcnt lgkmcnt(" #n ")" ::: "memory")
; #define PG8_BAR __builtin_amdgcn_s_barrier()
; #define PG8_SCHED __builtin_amdgcn_sched_barrier(0)
; template <class Epi, class Sched>
; DI void gemm_phase(LAS unsigned char* lds, const Gemm g, const Sched& S, const Epi& E) {
;     ...
;             PG8_WAIT_V(8); PG8_WAIT_L(0); PG8_BAR; PG8_MMA(1, 0, At, B0); PG8_MMA(1, 1, At, B1); PG8_BAR; PG8_SCHED;
;             PG8_LDB(B0, 1, 0); PG8_LDB(B1, 1, 1); PG8_SCHED; PG8_LDA(At, 1, 0); PG8_STAGE(PG8_SA(0, 1), a2 + hstepA, voffA);
;             PG8_WAIT_V(8); PG8_WAIT_L(0); PG8_BAR; PG8_MMA(0, 0, At, B0); PG8_MMA(0, 1, At, B1); PG8_BAR; PG8_SCHED;
	s_setprio 1
	v_mfma_f32_16x16x32_bf16 v[62:65], v[168:171], v[202:205], v[62:65]
	v_mfma_f32_16x16x32_bf16 v[54:57], v[176:179], v[202:205], v[54:57]
	v_mfma_f32_16x16x32_bf16 v[46:49], v[168:171], v[210:213], v[46:49]
	v_mfma_f32_16x16x32_bf16 v[38:41], v[176:179], v[210:213], v[38:41]
	v_mfma_f32_16x16x32_bf16 v[30:33], v[168:171], v[218:221], v[30:33]
	v_mfma_f32_16x16x32_bf16 v[22:25], v[176:179], v[218:221], v[22:25]
	v_mfma_f32_16x16x32_bf16 v[14:17], v[168:171], v[226:229], v[14:17]
	v_mfma_f32_16x16x32_bf16 v[6:9], v[176:179], v[226:229], v[6:9]
	v_mfma_f32_16x16x32_bf16 v[62:65], v[172:175], v[206:209], v[62:65]
	v_mfma_f32_16x16x32_bf16 v[54:57], v[180:183], v[206:209], v[54:57]
	v_mfma_f32_16x16x32_bf16 v[46:49], v[172:175], v[214:217], v[46:49]
	v_mfma_f32_16x16x32_bf16 v[38:41], v[180:183], v[214:217], v[38:41]
	v_mfma_f32_16x16x32_bf16 v[30:33], v[172:175], v[222:225], v[30:33]
	v_mfma_f32_16x16x32_bf16 v[22:25], v[180:183], v[222:225], v[22:25]
	v_mfma_f32_16x16x32_bf16 v[14:17], v[172:175], v[230:233], v[14:17]
	v_mfma_f32_16x16x32_bf16 v[6:9], v[180:183], v[230:233], v[6:9]
	v_mfma_f32_16x16x32_bf16 v[58:61], v[186:189], v[202:205], v[58:61]
	v_mfma_f32_16x16x32_bf16 v[50:53], v[194:197], v[202:205], v[50:53]
	v_mfma_f32_16x16x32_bf16 v[42:45], v[186:189], v[210:213], v[42:45]
	v_mfma_f32_16x16x32_bf16 v[34:37], v[194:197], v[210:213], v[34:37]
	v_mfma_f32_16x16x32_bf16 v[26:29], v[186:189], v[218:221], v[26:29]
	v_mfma_f32_16x16x32_bf16 v[18:21], v[194:197], v[218:221], v[18:21]
	v_mfma_f32_16x16x32_bf16 v[10:13], v[186:189], v[226:229], v[10:13]
	v_mfma_f32_16x16x32_bf16 v[2:5], v[194:197], v[226:229], v[2:5]
	v_mfma_f32_16x16x32_bf16 v[58:61], v[190:193], v[206:209], v[58:61]
	v_mfma_f32_16x16x32_bf16 v[50:53], v[198:201], v[206:209], v[50:53]
	v_mfma_f32_16x16x32_bf16 v[42:45], v[190:193], v[214:217], v[42:45]
	v_mfma_f32_16x16x32_bf16 v[34:37], v[198:201], v[214:217], v[34:37]
	v_mfma_f32_16x16x32_bf16 v[26:29], v[190:193], v[222:225], v[26:29]
	v_mfma_f32_16x16x32_bf16 v[18:21], v[198:201], v[222:225], v[18:21]
	v_mfma_f32_16x16x32_bf16 v[10:13], v[190:193], v[230:233], v[10:13]
	v_mfma_f32_16x16x32_bf16 v[2:5], v[198:201], v[230:233], v[2:5]
	s_setprio 0
	s_barrier
	s_add_i32 s66, 0, 0x18000
	v_add_u32_e32 v167, s66, v158
	s_add_i32 s67, 0, 0x1c000
	ds_read_b128 v[168:171], v167
	ds_read_b128 v[172:175], v167 offset:1024
	ds_read_b128 v[176:179], v167 offset:2048
	ds_read_b128 v[180:183], v167 offset:3072
	v_add_u32_e32 v167, s67, v158
	ds_read_b128 v[186:189], v167
	ds_read_b128 v[190:193], v167 offset:1024
	ds_read_b128 v[194:197], v167 offset:2048
	ds_read_b128 v[198:201], v167 offset:3072
	s_add_u32 s44, s44, 0x40000
	s_addc_u32 s45, s45, 0
	s_mov_b32 m0, s51
	v_lshl_add_u64 v[242:243], s[44:45], 0, v[136:137]
	ds_read_b128 v[202:205], v160 offset:32768
	ds_read_b128 v[206:209], v160 offset:33792
	ds_read_b128 v[210:213], v160 offset:34816
	ds_read_b128 v[214:217], v160 offset:35840
	ds_read_b128 v[218:221], v160 offset:36864
	ds_read_b128 v[222:225], v160 offset:37888
	ds_read_b128 v[226:229], v160 offset:38912
	ds_read_b128 v[230:233], v160 offset:39936
	global_load_lds_dwordx4 v[242:243], off
	v_lshl_add_u64 v[242:243], s[44:45], 0, v[132:133]
	s_mov_b32 m0, s52
	s_nop 0
	global_load_lds_dwordx4 v[242:243], off
	s_waitcnt vmcnt(8)
	s_waitcnt lgkmcnt(0)
	s_barrier
	s_setprio 1
	v_mfma_f32_16x16x32_bf16 v[126:129], v[168:171], v[202:205], v[126:129]
	v_mfma_f32_16x16x32_bf16 v[118:121], v[176:179], v[202:205], v[118:121]
	v_mfma_f32_16x16x32_bf16 v[110:113], v[168:171], v[210:213], v[110:113]
	v_mfma_f32_16x16x32_bf16 v[102:105], v[176:179], v[210:213], v[102:105]
	v_mfma_f32_16x16x32_bf16 v[94:97], v[168:171], v[218:221], v[94:97]
	v_mfma_f32_16x16x32_bf16 v[86:89], v[176:179], v[218:221], v[86:89]
	v_mfma_f32_16x16x32_bf16 v[78:81], v[168:171], v[226:229], v[78:81]
	v_mfma_f32_16x16x32_bf16 v[70:73], v[176:179], v[226:229], v[70:73]
	v_mfma_f32_16x16x32_bf16 v[126:129], v[172:175], v[206:209], v[126:129]
	v_mfma_f32_16x16x32_bf16 v[118:121], v[180:183], v[206:209], v[118:121]
	v_mfma_f32_16x16x32_bf16 v[110:113], v[172:175], v[214:217], v[110:113]
	v_mfma_f32_16x16x32_bf16 v[102:105], v[180:183], v[214:217], v[102:105]
	v_mfma_f32_16x16x32_bf16 v[94:97], v[172:175], v[222:225], v[94:97]
	v_mfma_f32_16x16x32_bf16 v[86:89], v[180:183], v[222:225], v[86:89]
	v_mfma_f32_16x16x32_bf16 v[78:81], v[172:175], v[230:233], v[78:81]
	v_mfma_f32_16x16x32_bf16 v[70:73], v[180:183], v[230:233], v[70:73]
	v_mfma_f32_16x16x32_bf16 v[122:125], v[186:189], v[202:205], v[122:125]
	v_mfma_f32_16x16x32_bf16 v[114:117], v[194:197], v[202:205], v[114:117]
	v_mfma_f32_16x16x32_bf16 v[106:109], v[186:189], v[210:213], v[106:109]
	v_mfma_f32_16x16x32_bf16 v[98:101], v[194:197], v[210:213], v[98:101]
	v_mfma_f32_16x16x32_bf16 v[90:93], v[186:189], v[218:221], v[90:93]
	v_mfma_f32_16x16x32_bf16 v[82:85], v[194:197], v[218:221], v[82:85]
	v_mfma_f32_16x16x32_bf16 v[74:77], v[186:189], v[226:229], v[74:77]
	v_mfma_f32_16x16x32_bf16 v[66:69], v[194:197], v[226:229], v[66:69]
	v_mfma_f32_16x16x32_bf16 v[122:125], v[190:193], v[206:209], v[122:125]
	v_mfma_f32_16x16x32_bf16 v[114:117], v[198:201], v[206:209], v[114:117]
	v_mfma_f32_16x16x32_bf16 v[106:109], v[190:193], v[214:217], v[106:109]
	v_mfma_f32_16x16x32_bf16 v[98:101], v[198:201], v[214:217], v[98:101]
	v_mfma_f32_16x16x32_bf16 v[90:93], v[190:193], v[222:225], v[90:93]
	v_mfma_f32_16x16x32_bf16 v[82:85], v[198:201], v[222:225], v[82:85]
	v_mfma_f32_16x16x32_bf16 v[74:77], v[190:193], v[230:233], v[74:77]
	v_mfma_f32_16x16x32_bf16 v[66:69], v[198:201], v[230:233], v[66:69]
	s_setprio 0
	s_barrier
; #define PG8_STAGE(bufoff, gbase, voff) do { _Pragma("unroll") for (int _i = 0; _i < 2; ++_i) \
;         __builtin_amdgcn_global_load_lds((const unsigned*)((const char*)(gbase) + (voff)[_i]), (LAS unsigned*)(lds + (bufoff) + ldsw + _i * 8192), 16, 0, 0); } while (0)
; #define PG8_LDA(dst, b, h) do { _Pragma("unroll") for (int m = 0; m < 4; ++m) _Pragma("unroll") for (int k = 0; k < 2; ++k) dst[m][k] = *(const LAS bf16x8*)(lds + PG8_SA(b, h) + aoff + m * 2048 + k * 1024); } while (0)
; #define PG8_MMA(ai, bj, At, Bt) do { __builtin_amdgcn_s_setprio(1); _Pragma("unroll") for (int m = 0; m < 4; ++m) _Pragma("unroll") for (int n = 0; n < 2; ++n) _Pragma("unroll") for (int k = 0; k < 2; ++k) \
;         acc[ai][bj][m][n] = __builtin_amdgcn_mfma_f32_16x16x32_bf16(Bt[n][k], At[m][k], acc[ai][bj][m][n], 0, 0, 0); __builtin_amdgcn_s_setprio(0); } while (0)
; #define PG8_WAIT_V(n) asm volatile("s_waitcnt vmcnt(" #n ")" ::: "memory")
; #define PG8_WAIT_L(n) asm volatile("s_waitcnt lgkmcnt(" #n ")" ::: "memory")
; #define PG8_BAR __builtin_amdgcn_s_barrier()
; #define PG8_SCHED __builtin_amdgcn_sched_barrier(0)
; template <class Epi, class Sched>
; DI void gemm_phase(LAS unsigned char* lds, const Gemm g, const Sched& S, const Epi& E) {
;     ...
;             PG8_LDA(At, 1, 1); PG8_STAGE(PG8_SB(1, 0), b3, voffB); PG8_STAGE(PG8_SB(1, 1), b3 + hstepB, voffB); PG8_STAGE(PG8_SA(1, 0), a3, voffA);
;             PG8_WAIT_V(8); PG8_WAIT_L(0); PG8_BAR; PG8_MMA(1, 0, At, B0); PG8_MMA(1, 1, At, B1); PG8_BAR; PG8_SCHED;
;         }
;         if (wr == 0) PG8_BAR;
	s_add_i32 s44, s66, s46
	v_lshl_add_u64 v[234:235], v[234:235], 0, s[16:17]
	s_mov_b32 m0, s44
	ds_read_b128 v[202:205], v160 offset:49152
	ds_read_b128 v[206:209], v160 offset:50176
	ds_read_b128 v[210:213], v160 offset:51200
	ds_read_b128 v[214:217], v160 offset:52224
	ds_read_b128 v[218:221], v160 offset:53248
	ds_read_b128 v[222:225], v160 offset:54272
	ds_read_b128 v[226:229], v160 offset:55296
	ds_read_b128 v[230:233], v160 offset:56320
	global_load_lds_dwordx4 v[234:235], off
	s_add_i32 m0, s44, 0x2000
	s_add_u32 s42, s42, 0x40080
	v_lshl_add_u64 v[234:235], v[236:237], 0, s[16:17]
	s_addc_u32 s43, s43, 0
	s_add_i32 s44, s67, s46
	global_load_lds_dwordx4 v[234:235], off
	v_lshl_add_u64 v[234:235], s[42:43], 0, v[134:135]
	s_mov_b32 m0, s44
	s_nop 0
	global_load_lds_dwordx4 v[234:235], off
	v_lshl_add_u64 v[234:235], s[42:43], 0, v[130:131]
	s_add_i32 m0, s44, 0x2000
	s_nop 0
	global_load_lds_dwordx4 v[234:235], off
	v_lshl_add_u64 v[234:235], v[238:239], 0, s[16:17]
	s_mov_b32 m0, s54
	s_nop 0
	global_load_lds_dwordx4 v[234:235], off
	v_lshl_add_u64 v[234:235], v[240:241], 0, s[16:17]
	s_mov_b32 m0, s55
	s_nop 0
	global_load_lds_dwordx4 v[234:235], off
	s_waitcnt vmcnt(8)
	s_waitcnt lgkmcnt(0)
	s_barrier
	s_setprio 1
	v_mfma_f32_16x16x32_bf16 v[62:65], v[168:171], v[202:205], v[62:65]
	v_mfma_f32_16x16x32_bf16 v[54:57], v[176:179], v[202:205], v[54:57]
	v_mfma_f32_16x16x32_bf16 v[46:49], v[168:171], v[210:213], v[46:49]
	v_mfma_f32_16x16x32_bf16 v[38:41], v[176:179], v[210:213], v[38:41]
	v_mfma_f32_16x16x32_bf16 v[30:33], v[168:171], v[218:221], v[30:33]
	v_mfma_f32_16x16x32_bf16 v[22:25], v[176:179], v[218:221], v[22:25]
	v_mfma_f32_16x16x32_bf16 v[14:17], v[168:171], v[226:229], v[14:17]
	v_mfma_f32_16x16x32_bf16 v[6:9], v[176:179], v[226:229], v[6:9]
	v_mfma_f32_16x16x32_bf16 v[62:65], v[172:175], v[206:209], v[62:65]
	v_mfma_f32_16x16x32_bf16 v[54:57], v[180:183], v[206:209], v[54:57]
	v_mfma_f32_16x16x32_bf16 v[46:49], v[172:175], v[214:217], v[46:49]
	v_mfma_f32_16x16x32_bf16 v[38:41], v[180:183], v[214:217], v[38:41]
	v_mfma_f32_16x16x32_bf16 v[30:33], v[172:175], v[222:225], v[30:33]
	v_mfma_f32_16x16x32_bf16 v[22:25], v[180:183], v[222:225], v[22:25]
	v_mfma_f32_16x16x32_bf16 v[14:17], v[172:175], v[230:233], v[14:17]
	v_mfma_f32_16x16x32_bf16 v[6:9], v[180:183], v[230:233], v[6:9]
	v_mfma_f32_16x16x32_bf16 v[58:61], v[186:189], v[202:205], v[58:61]
	v_mfma_f32_16x16x32_bf16 v[50:53], v[194:197], v[202:205], v[50:53]
	v_mfma_f32_16x16x32_bf16 v[42:45], v[186:189], v[210:213], v[42:45]
	v_mfma_f32_16x16x32_bf16 v[34:37], v[194:197], v[210:213], v[34:37]
	v_mfma_f32_16x16x32_bf16 v[26:29], v[186:189], v[218:221], v[26:29]
	v_mfma_f32_16x16x32_bf16 v[18:21], v[194:197], v[218:221], v[18:21]
	v_mfma_f32_16x16x32_bf16 v[10:13], v[186:189], v[226:229], v[10:13]
	v_mfma_f32_16x16x32_bf16 v[2:5], v[194:197], v[226:229], v[2:5]
	v_mfma_f32_16x16x32_bf16 v[58:61], v[190:193], v[206:209], v[58:61]
	v_mfma_f32_16x16x32_bf16 v[50:53], v[198:201], v[206:209], v[50:53]
	v_mfma_f32_16x16x32_bf16 v[42:45], v[190:193], v[214:217], v[42:45]
	v_mfma_f32_16x16x32_bf16 v[34:37], v[198:201], v[214:217], v[34:37]
	v_mfma_f32_16x16x32_bf16 v[26:29], v[190:193], v[222:225], v[26:29]
	v_mfma_f32_16x16x32_bf16 v[18:21], v[198:201], v[222:225], v[18:21]
	v_mfma_f32_16x16x32_bf16 v[10:13], v[190:193], v[230:233], v[10:13]
	v_mfma_f32_16x16x32_bf16 v[2:5], v[198:201], v[230:233], v[2:5]
	s_setprio 0
	s_barrier
	s_add_i32 s65, s65, 2
	s_add_u32 s40, s40, 0x100
	s_addc_u32 s41, s41, 0
	s_add_u32 s63, s63, 0x100
	s_addc_u32 s64, s64, 0
	s_cmp_gt_u32 s65, 13
	s_cbranch_scc0 .LBB0_179
	s_and_b64 vcc, exec, s[18:19]
	s_cbranch_vccz .LBB0_182
	s_barrier

; #define PG8_STAGE(bufoff, gbase, voff) do { _Pragma("unroll") for (int _i = 0; _i < 2; ++_i) \
;         __builtin_amdgcn_global_load_lds((const unsigned*)((const char*)(gbase) + (voff)[_i]), (LAS unsigned*)(lds + (bufoff) + ldsw + _i * 8192), 16, 0, 0); } while (0)
; #define PG8_LDA(dst, b, h) do { _Pragma("unroll") for (int m = 0; m < 4; ++m) _Pragma("unroll") for (int k = 0; k < 2; ++k) dst[m][k] = *(const LAS bf16x8*)(lds + PG8_SA(b, h) + aoff + m * 2048 + k * 1024); } while (0)
; #define PG8_LDB(dst, b, h) do { _Pragma("unroll") for (int n = 0; n < 2; ++n) _Pragma("unroll") for (int k = 0; k < 2; ++k) dst[n][k] = *(const LAS bf16x8*)(lds + PG8_SB(b, h) + boff + n * 2048 + k * 1024); } while (0)
; #define PG8_MMA(ai, bj, At, Bt) do { __builtin_amdgcn_s_setprio(1); _Pragma("unroll") for (int m = 0; m < 4; ++m) _Pragma("unroll") for (int n = 0; n < 2; ++n) _Pragma("unroll") for (int k = 0; k < 2; ++k) \
;         acc[ai][bj][m][n] = __builtin_amdgcn_mfma_f32_16x16x32_bf16(Bt[n][k], At[m][k], acc[ai][bj][m][n], 0, 0, 0); __builtin_amdgcn_s_setprio(0); } while (0)
; #define PG8_WAIT_V(n) asm volatile("s_waitcnt vmcnt(" #n ")" ::: "memory")
; #define PG8_WAIT_L(n) asm volatile("s_waitcnt lgkmcnt(" #n ")" ::: "memory")
; #define PG8_BAR __builtin_amdgcn_s_barrier()
; #define PG8_SCHED __builtin_amdgcn_sched_barrier(0)
; template <class Epi, class Sched>
; DI void gemm_phase(LAS unsigned char* lds, const Gemm g, const Sched& S, const Epi& E) {
;     ...
;             const bool last = (t == nt - 2);
;             const char* a1 = cA + (size_t)(t + 1) * kstep;
;             const char* a2 = last ? nA : cA + (size_t)(t + 2) * kstep; const char* b2 = last ? nB : cB + (size_t)(t + 2) * kstep;
;             const char* a3 = a2 + kstep; const char* b3 = b2 + kstep;
;             PG8_LDB(B0, 0, 0); PG8_LDB(B1, 0, 1); PG8_SCHED; PG8_LDA(At, 0, 0); PG8_STAGE(PG8_SA(1, 1), a1 + hstepA, voffA);
;             PG8_WAIT_V(8); PG8_WAIT_L(0); PG8_BAR; PG8_MMA(0, 0, At, B0); PG8_MMA(0, 1, At, B1); PG8_BAR; PG8_SCHED;
;             PG8_LDA(At, 0, 1); PG8_STAGE(PG8_SB(0, 0), b2, voffB); PG8_STAGE(PG8_SB(0, 1), b2 + hstepB, voffB); PG8_STAGE(PG8_SA(0, 0), a2, voffA);
;             PG8_WAIT_V(8); PG8_WAIT_L(0); PG8_BAR; PG8_MMA(1, 0, At, B0); PG8_MMA(1, 1, At, B1); PG8_BAR; PG8_SCHED;
.LBB0_278:
	ds_read_b128 v[148:151], v154
	ds_read_b128 v[158:161], v154 offset:1024
	ds_read_b128 v[162:165], v154 offset:2048
	ds_read_b128 v[166:169], v154 offset:3072
	ds_read_b128 v[170:173], v155
	ds_read_b128 v[174:177], v155 offset:1024
	ds_read_b128 v[178:181], v155 offset:2048
	ds_read_b128 v[186:189], v155 offset:3072
	s_add_u32 s38, s36, 0xfff50080
	s_addc_u32 s39, s37, -1
	s_cmp_eq_u32 s62, 40
	s_cselect_b32 s41, s9, s39
	s_cselect_b32 s40, s8, s38
	s_cselect_b32 s39, s35, s61
	s_cselect_b32 s38, s34, s60
	v_lshl_add_u64 v[182:183], s[36:37], 0, v[138:139]
	s_add_i32 m0, s45, 0xc000
	ds_read_b128 v[190:193], v156
	ds_read_b128 v[194:197], v156 offset:1024
	ds_read_b128 v[198:201], v156 offset:2048
	ds_read_b128 v[202:205], v156 offset:3072
	ds_read_b128 v[206:209], v156 offset:4096
	ds_read_b128 v[210:213], v156 offset:5120
	ds_read_b128 v[214:217], v156 offset:6144
	ds_read_b128 v[218:221], v156 offset:7168
	global_load_lds_dwordx4 v[182:183], off
	v_lshl_add_u64 v[182:183], s[36:37], 0, v[140:141]
	s_add_i32 m0, s45, 0xe000
	s_nop 0
	global_load_lds_dwordx4 v[182:183], off
	s_waitcnt vmcnt(8)
	s_waitcnt lgkmcnt(0)
	s_barrier
	s_setprio 1
	v_mfma_f32_16x16x32_bf16 v[126:129], v[148:151], v[190:193], v[126:129]
	v_mfma_f32_16x16x32_bf16 v[122:125], v[162:165], v[190:193], v[122:125]
	v_mfma_f32_16x16x32_bf16 v[110:113], v[148:151], v[198:201], v[110:113]
	v_mfma_f32_16x16x32_bf16 v[106:109], v[162:165], v[198:201], v[106:109]
	v_mfma_f32_16x16x32_bf16 v[94:97], v[148:151], v[206:209], v[94:97]
	v_mfma_f32_16x16x32_bf16 v[90:93], v[162:165], v[206:209], v[90:93]
	v_mfma_f32_16x16x32_bf16 v[78:81], v[148:151], v[214:217], v[78:81]
	v_mfma_f32_16x16x32_bf16 v[74:77], v[162:165], v[214:217], v[74:77]
	v_mfma_f32_16x16x32_bf16 v[126:129], v[158:161], v[194:197], v[126:129]
	v_mfma_f32_16x16x32_bf16 v[122:125], v[166:169], v[194:197], v[122:125]
	v_mfma_f32_16x16x32_bf16 v[110:113], v[158:161], v[202:205], v[110:113]
	v_mfma_f32_16x16x32_bf16 v[106:109], v[166:169], v[202:205], v[106:109]
	v_mfma_f32_16x16x32_bf16 v[94:97], v[158:161], v[210:213], v[94:97]
	v_mfma_f32_16x16x32_bf16 v[90:93], v[166:169], v[210:213], v[90:93]
	v_mfma_f32_16x16x32_bf16 v[78:81], v[158:161], v[218:221], v[78:81]
	v_mfma_f32_16x16x32_bf16 v[74:77], v[166:169], v[218:221], v[74:77]
	v_mfma_f32_16x16x32_bf16 v[118:121], v[170:173], v[190:193], v[118:121]
	v_mfma_f32_16x16x32_bf16 v[114:117], v[178:181], v[190:193], v[114:117]
	v_mfma_f32_16x16x32_bf16 v[102:105], v[170:173], v[198:201], v[102:105]
	v_mfma_f32_16x16x32_bf16 v[98:101], v[178:181], v[198:201], v[98:101]
	v_mfma_f32_16x16x32_bf16 v[86:89], v[170:173], v[206:209], v[86:89]
	v_mfma_f32_16x16x32_bf16 v[82:85], v[178:181], v[206:209], v[82:85]
	v_mfma_f32_16x16x32_bf16 v[70:73], v[170:173], v[214:217], v[70:73]
	v_mfma_f32_16x16x32_bf16 v[66:69], v[178:181], v[214:217], v[66:69]
	v_mfma_f32_16x16x32_bf16 v[118:121], v[174:177], v[194:197], v[118:121]
	v_mfma_f32_16x16x32_bf16 v[114:117], v[186:189], v[194:197], v[114:117]
	v_mfma_f32_16x16x32_bf16 v[102:105], v[174:177], v[202:205], v[102:105]
	v_mfma_f32_16x16x32_bf16 v[98:101], v[186:189], v[202:205], v[98:101]
	v_mfma_f32_16x16x32_bf16 v[86:89], v[174:177], v[210:213], v[86:89]
	v_mfma_f32_16x16x32_bf16 v[82:85], v[186:189], v[210:213], v[82:85]
	v_mfma_f32_16x16x32_bf16 v[70:73], v[174:177], v[218:221], v[70:73]
	v_mfma_f32_16x16x32_bf16 v[66:69], v[186:189], v[218:221], v[66:69]
	s_setprio 0
	s_barrier
	s_add_i32 s63, s54, s44
	v_lshl_add_u64 v[182:183], s[38:39], 0, v[132:133]
	s_mov_b32 m0, s63
	ds_read_b128 v[190:193], v156 offset:16384
	ds_read_b128 v[194:197], v156 offset:17408
	ds_read_b128 v[198:201], v156 offset:18432
	ds_read_b128 v[202:205], v156 offset:19456
	ds_read_b128 v[206:209], v156 offset:20480
	ds_read_b128 v[210:213], v156 offset:21504
	ds_read_b128 v[214:217], v156 offset:22528
	ds_read_b128 v[218:221], v156 offset:23552
	global_load_lds_dwordx4 v[182:183], off
	s_add_i32 m0, s63, 0x2000
	s_add_u32 s64, s38, 0xb0000
	v_lshl_add_u64 v[222:223], s[38:39], 0, v[136:137]
	s_addc_u32 s65, s39, 0
	s_add_i32 s63, s55, s44
	global_load_lds_dwordx4 v[222:223], off
	v_lshl_add_u64 v[224:225], s[64:65], 0, v[132:133]
	s_mov_b32 m0, s63
	v_lshl_add_u64 v[226:227], s[40:41], 0, v[134:135]
	global_load_lds_dwordx4 v[224:225], off
	v_lshl_add_u64 v[224:225], s[64:65], 0, v[136:137]
	s_add_i32 m0, s63, 0x2000
	s_nop 0
	global_load_lds_dwordx4 v[224:225], off
	v_lshl_add_u64 v[224:225], s[40:41], 0, v[130:131]
	s_mov_b32 m0, s45
	s_nop 0
	global_load_lds_dwordx4 v[224:225], off
	s_mov_b32 m0, s46
	s_nop 0
	global_load_lds_dwordx4 v[226:227], off
	s_waitcnt vmcnt(8)
	s_waitcnt lgkmcnt(0)
	s_barrier
; #define PG8_STAGE(bufoff, gbase, voff) do { _Pragma("unroll") for (int _i = 0; _i < 2; ++_i) \
;         __builtin_amdgcn_global_load_lds((const unsigned*)((const char*)(gbase) + (voff)[_i]), (LAS unsigned*)(lds + (bufoff) + ldsw + _i * 8192), 16, 0, 0); } while (0)
; #define PG8_LDA(dst, b, h) do { _Pragma("unroll") for (int m = 0; m < 4; ++m) _Pragma("unroll") for (int k = 0; k < 2; ++k) dst[m][k] = *(const LAS bf16x8*)(lds + PG8_SA(b, h) + aoff + m * 2048 + k * 1024); } while (0)
; #define PG8_LDB(dst, b, h) do { _Pragma("unroll") for (int n = 0; n < 2; ++n) _Pragma("unroll") for (int k = 0; k < 2; ++k) dst[n][k] = *(const LAS bf16x8*)(lds + PG8_SB(b, h) + boff + n * 2048 + k * 1024); } while (0)
; #define PG8_MMA(ai, bj, At, Bt) do { __builtin_amdgcn_s_setprio(1); _Pragma("unroll") for (int m = 0; m < 4; ++m) _Pragma("unroll") for (int n = 0; n < 2; ++n) _Pragma("unroll") for (int k = 0; k < 2; ++k) \
;         acc[ai][bj][m][n] = __builtin_amdgcn_mfma_f32_16x16x32_bf16(Bt[n][k], At[m][k], acc[ai][bj][m][n], 0, 0, 0); __builtin_amdgcn_s_setprio(0); } while (0)
; #define PG8_WAIT_V(n) asm volatile("s_waitcnt vmcnt(" #n ")" ::: "memory")
; #define PG8_WAIT_L(n) asm volatile("s_waitcnt lgkmcnt(" #n ")" ::: "memory")
; #define PG8_BAR __builtin_amdgcn_s_barrier()
; #define PG8_SCHED __builtin_amdgcn_sched_barrier(0)
; template <class Epi, class Sched>
; DI void gemm_phase(LAS unsigned char* lds, const Gemm g, const Sched& S, const Epi& E) {
;     ...
;             PG8_WAIT_V(8); PG8_WAIT_L(0); PG8_BAR; PG8_MMA(1, 0, At, B0); PG8_MMA(1, 1, At, B1); PG8_BAR; PG8_SCHED;
;             PG8_LDB(B0, 1, 0); PG8_LDB(B1, 1, 1); PG8_SCHED; PG8_LDA(At, 1, 0); PG8_STAGE(PG8_SA(0, 1), a2 + hstepA, voffA);
;             PG8_WAIT_V(8); PG8_WAIT_L(0); PG8_BAR; PG8_MMA(0, 0, At, B0); PG8_MMA(0, 1, At, B1); PG8_BAR; PG8_SCHED;
	s_setprio 1
	v_mfma_f32_16x16x32_bf16 v[62:65], v[148:151], v[190:193], v[62:65]
	v_mfma_f32_16x16x32_bf16 v[58:61], v[162:165], v[190:193], v[58:61]
	v_mfma_f32_16x16x32_bf16 v[46:49], v[148:151], v[198:201], v[46:49]
	v_mfma_f32_16x16x32_bf16 v[42:45], v[162:165], v[198:201], v[42:45]
	v_mfma_f32_16x16x32_bf16 v[30:33], v[148:151], v[206:209], v[30:33]
	v_mfma_f32_16x16x32_bf16 v[26:29], v[162:165], v[206:209], v[26:29]
	v_mfma_f32_16x16x32_bf16 v[14:17], v[148:151], v[214:217], v[14:17]
	v_mfma_f32_16x16x32_bf16 v[10:13], v[162:165], v[214:217], v[10:13]
	v_mfma_f32_16x16x32_bf16 v[62:65], v[158:161], v[194:197], v[62:65]
	v_mfma_f32_16x16x32_bf16 v[58:61], v[166:169], v[194:197], v[58:61]
	v_mfma_f32_16x16x32_bf16 v[46:49], v[158:161], v[202:205], v[46:49]
	v_mfma_f32_16x16x32_bf16 v[42:45], v[166:169], v[202:205], v[42:45]
	v_mfma_f32_16x16x32_bf16 v[30:33], v[158:161], v[210:213], v[30:33]
	v_mfma_f32_16x16x32_bf16 v[26:29], v[166:169], v[210:213], v[26:29]
	v_mfma_f32_16x16x32_bf16 v[14:17], v[158:161], v[218:221], v[14:17]
	v_mfma_f32_16x16x32_bf16 v[10:13], v[166:169], v[218:221], v[10:13]
	v_mfma_f32_16x16x32_bf16 v[54:57], v[170:173], v[190:193], v[54:57]
	v_mfma_f32_16x16x32_bf16 v[50:53], v[178:181], v[190:193], v[50:53]
	v_mfma_f32_16x16x32_bf16 v[38:41], v[170:173], v[198:201], v[38:41]
	v_mfma_f32_16x16x32_bf16 v[34:37], v[178:181], v[198:201], v[34:37]
	v_mfma_f32_16x16x32_bf16 v[22:25], v[170:173], v[206:209], v[22:25]
	v_mfma_f32_16x16x32_bf16 v[18:21], v[178:181], v[206:209], v[18:21]
	v_mfma_f32_16x16x32_bf16 v[6:9], v[170:173], v[214:217], v[6:9]
	v_mfma_f32_16x16x32_bf16 v[2:5], v[178:181], v[214:217], v[2:5]
	v_mfma_f32_16x16x32_bf16 v[54:57], v[174:177], v[194:197], v[54:57]
	v_mfma_f32_16x16x32_bf16 v[50:53], v[186:189], v[194:197], v[50:53]
	v_mfma_f32_16x16x32_bf16 v[38:41], v[174:177], v[202:205], v[38:41]
	v_mfma_f32_16x16x32_bf16 v[34:37], v[186:189], v[202:205], v[34:37]
	v_mfma_f32_16x16x32_bf16 v[22:25], v[174:177], v[210:213], v[22:25]
	v_mfma_f32_16x16x32_bf16 v[18:21], v[186:189], v[210:213], v[18:21]
	v_mfma_f32_16x16x32_bf16 v[6:9], v[174:177], v[218:221], v[6:9]
	v_mfma_f32_16x16x32_bf16 v[2:5], v[186:189], v[218:221], v[2:5]
	s_setprio 0
	s_barrier
	s_add_i32 s63, 0, 0x18000
	s_add_i32 s64, 0, 0x1c000
	v_add_u32_e32 v166, s63, v152
	v_add_u32_e32 v185, s64, v152
	ds_read_b128 v[148:151], v166
	ds_read_b128 v[158:161], v166 offset:1024
	ds_read_b128 v[162:165], v166 offset:2048
	ds_read_b128 v[166:169], v166 offset:3072
	ds_read_b128 v[170:173], v185
	ds_read_b128 v[174:177], v185 offset:1024
	ds_read_b128 v[178:181], v185 offset:2048
	ds_read_b128 v[186:189], v185 offset:3072
	s_add_u32 s40, s40, 0xb0000
	s_addc_u32 s41, s41, 0
	s_mov_b32 m0, s47
	v_lshl_add_u64 v[228:229], s[40:41], 0, v[130:131]
	ds_read_b128 v[190:193], v156 offset:32768
	ds_read_b128 v[194:197], v156 offset:33792
	ds_read_b128 v[198:201], v156 offset:34816
	ds_read_b128 v[202:205], v156 offset:35840
	ds_read_b128 v[206:209], v156 offset:36864
	ds_read_b128 v[210:213], v156 offset:37888
	ds_read_b128 v[214:217], v156 offset:38912
	ds_read_b128 v[218:221], v156 offset:39936
	global_load_lds_dwordx4 v[228:229], off
	v_lshl_add_u64 v[228:229], s[40:41], 0, v[134:135]
	s_mov_b32 m0, s48
	s_nop 0
	global_load_lds_dwordx4 v[228:229], off
	s_waitcnt vmcnt(8)
	s_waitcnt lgkmcnt(0)
	s_barrier
	s_setprio 1
	v_mfma_f32_16x16x32_bf16 v[126:129], v[148:151], v[190:193], v[126:129]
	v_mfma_f32_16x16x32_bf16 v[122:125], v[162:165], v[190:193], v[122:125]
	v_mfma_f32_16x16x32_bf16 v[110:113], v[148:151], v[198:201], v[110:113]
	v_mfma_f32_16x16x32_bf16 v[106:109], v[162:165], v[198:201], v[106:109]
	v_mfma_f32_16x16x32_bf16 v[94:97], v[148:151], v[206:209], v[94:97]
	v_mfma_f32_16x16x32_bf16 v[90:93], v[162:165], v[206:209], v[90:93]
	v_mfma_f32_16x16x32_bf16 v[78:81], v[148:151], v[214:217], v[78:81]
	v_mfma_f32_16x16x32_bf16 v[74:77], v[162:165], v[214:217], v[74:77]
	v_mfma_f32_16x16x32_bf16 v[126:129], v[158:161], v[194:197], v[126:129]
	v_mfma_f32_16x16x32_bf16 v[122:125], v[166:169], v[194:197], v[122:125]
	v_mfma_f32_16x16x32_bf16 v[110:113], v[158:161], v[202:205], v[110:113]
	v_mfma_f32_16x16x32_bf16 v[106:109], v[166:169], v[202:205], v[106:109]
	v_mfma_f32_16x16x32_bf16 v[94:97], v[158:161], v[210:213], v[94:97]
	v_mfma_f32_16x16x32_bf16 v[90:93], v[166:169], v[210:213], v[90:93]
	v_mfma_f32_16x16x32_bf16 v[78:81], v[158:161], v[218:221], v[78:81]
	v_mfma_f32_16x16x32_bf16 v[74:77], v[166:169], v[218:221], v[74:77]
	v_mfma_f32_16x16x32_bf16 v[118:121], v[170:173], v[190:193], v[118:121]
	v_mfma_f32_16x16x32_bf16 v[114:117], v[178:181], v[190:193], v[114:117]
	v_mfma_f32_16x16x32_bf16 v[102:105], v[170:173], v[198:201], v[102:105]
	v_mfma_f32_16x16x32_bf16 v[98:101], v[178:181], v[198:201], v[98:101]
	v_mfma_f32_16x16x32_bf16 v[86:89], v[170:173], v[206:209], v[86:89]
	v_mfma_f32_16x16x32_bf16 v[82:85], v[178:181], v[206:209], v[82:85]
	v_mfma_f32_16x16x32_bf16 v[70:73], v[170:173], v[214:217], v[70:73]
	v_mfma_f32_16x16x32_bf16 v[66:69], v[178:181], v[214:217], v[66:69]
	v_mfma_f32_16x16x32_bf16 v[118:121], v[174:177], v[194:197], v[118:121]
	v_mfma_f32_16x16x32_bf16 v[114:117], v[186:189], v[194:197], v[114:117]
	v_mfma_f32_16x16x32_bf16 v[102:105], v[174:177], v[202:205], v[102:105]
	v_mfma_f32_16x16x32_bf16 v[98:101], v[186:189], v[202:205], v[98:101]
	v_mfma_f32_16x16x32_bf16 v[86:89], v[174:177], v[210:213], v[86:89]
	v_mfma_f32_16x16x32_bf16 v[82:85], v[186:189], v[210:213], v[82:85]
	v_mfma_f32_16x16x32_bf16 v[70:73], v[174:177], v[218:221], v[70:73]
	v_mfma_f32_16x16x32_bf16 v[66:69], v[186:189], v[218:221], v[66:69]
	s_setprio 0
	s_barrier
; #define PG8_STAGE(bufoff, gbase, voff) do { _Pragma("unroll") for (int _i = 0; _i < 2; ++_i) \
;         __builtin_amdgcn_global_load_lds((const unsigned*)((const char*)(gbase) + (voff)[_i]), (LAS unsigned*)(lds + (bufoff) + ldsw + _i * 8192), 16, 0, 0); } while (0)
; #define PG8_LDA(dst, b, h) do { _Pragma("unroll") for (int m = 0; m < 4; ++m) _Pragma("unroll") for (int k = 0; k < 2; ++k) dst[m][k] = *(const LAS bf16x8*)(lds + PG8_SA(b, h) + aoff + m * 2048 + k * 1024); } while (0)
; #define PG8_MMA(ai, bj, At, Bt) do { __builtin_amdgcn_s_setprio(1); _Pragma("unroll") for (int m = 0; m < 4; ++m) _Pragma("unroll") for (int n = 0; n < 2; ++n) _Pragma("unroll") for (int k = 0; k < 2; ++k) \
;         acc[ai][bj][m][n] = __builtin_amdgcn_mfma_f32_16x16x32_bf16(Bt[n][k], At[m][k], acc[ai][bj][m][n], 0, 0, 0); __builtin_amdgcn_s_setprio(0); } while (0)
; #define PG8_WAIT_V(n) asm volatile("s_waitcnt vmcnt(" #n ")" ::: "memory")
; #define PG8_WAIT_L(n) asm volatile("s_waitcnt lgkmcnt(" #n ")" ::: "memory")
; #define PG8_BAR __builtin_amdgcn_s_barrier()
; #define PG8_SCHED __builtin_amdgcn_sched_barrier(0)
; template <class Epi, class Sched>
; DI void gemm_phase(LAS unsigned char* lds, const Gemm g, const Sched& S, const Epi& E) {
;     ...
;             PG8_LDA(At, 1, 1); PG8_STAGE(PG8_SB(1, 0), b3, voffB); PG8_STAGE(PG8_SB(1, 1), b3 + hstepB, voffB); PG8_STAGE(PG8_SA(1, 0), a3, voffA);
;             PG8_WAIT_V(8); PG8_WAIT_L(0); PG8_BAR; PG8_MMA(1, 0, At, B0); PG8_MMA(1, 1, At, B1); PG8_BAR; PG8_SCHED;
;         }
;         if (wr == 0) PG8_BAR;
	s_add_i32 s40, s63, s44
	v_lshl_add_u64 v[182:183], v[182:183], 0, s[16:17]
	s_mov_b32 m0, s40
	ds_read_b128 v[190:193], v156 offset:49152
	ds_read_b128 v[194:197], v156 offset:50176
	ds_read_b128 v[198:201], v156 offset:51200
	ds_read_b128 v[202:205], v156 offset:52224
	ds_read_b128 v[206:209], v156 offset:53248
	ds_read_b128 v[210:213], v156 offset:54272
	ds_read_b128 v[214:217], v156 offset:55296
	ds_read_b128 v[218:221], v156 offset:56320
	global_load_lds_dwordx4 v[182:183], off
	s_add_i32 m0, s40, 0x2000
	s_add_u32 s38, s38, 0xb0080
	v_lshl_add_u64 v[182:183], v[222:223], 0, s[16:17]
	s_addc_u32 s39, s39, 0
	s_add_i32 s40, s64, s44
	global_load_lds_dwordx4 v[182:183], off
	v_lshl_add_u64 v[182:183], s[38:39], 0, v[132:133]
	s_mov_b32 m0, s40
	s_nop 0
	global_load_lds_dwordx4 v[182:183], off
	v_lshl_add_u64 v[182:183], s[38:39], 0, v[136:137]
	s_add_i32 m0, s40, 0x2000
	s_nop 0
	global_load_lds_dwordx4 v[182:183], off
	v_lshl_add_u64 v[182:183], v[224:225], 0, s[16:17]
	s_mov_b32 m0, s50
	s_nop 0
	global_load_lds_dwordx4 v[182:183], off
	v_lshl_add_u64 v[182:183], v[226:227], 0, s[16:17]
	s_mov_b32 m0, s51
	s_nop 0
	global_load_lds_dwordx4 v[182:183], off
	s_waitcnt vmcnt(8)
	s_waitcnt lgkmcnt(0)
	s_barrier
	s_setprio 1
	v_mfma_f32_16x16x32_bf16 v[62:65], v[148:151], v[190:193], v[62:65]
	v_mfma_f32_16x16x32_bf16 v[58:61], v[162:165], v[190:193], v[58:61]
	v_mfma_f32_16x16x32_bf16 v[46:49], v[148:151], v[198:201], v[46:49]
	v_mfma_f32_16x16x32_bf16 v[42:45], v[162:165], v[198:201], v[42:45]
	v_mfma_f32_16x16x32_bf16 v[30:33], v[148:151], v[206:209], v[30:33]
	v_mfma_f32_16x16x32_bf16 v[26:29], v[162:165], v[206:209], v[26:29]
	v_mfma_f32_16x16x32_bf16 v[14:17], v[148:151], v[214:217], v[14:17]
	v_mfma_f32_16x16x32_bf16 v[10:13], v[162:165], v[214:217], v[10:13]
	v_mfma_f32_16x16x32_bf16 v[62:65], v[158:161], v[194:197], v[62:65]
	v_mfma_f32_16x16x32_bf16 v[58:61], v[166:169], v[194:197], v[58:61]
	v_mfma_f32_16x16x32_bf16 v[46:49], v[158:161], v[202:205], v[46:49]
	v_mfma_f32_16x16x32_bf16 v[42:45], v[166:169], v[202:205], v[42:45]
	v_mfma_f32_16x16x32_bf16 v[30:33], v[158:161], v[210:213], v[30:33]
	v_mfma_f32_16x16x32_bf16 v[26:29], v[166:169], v[210:213], v[26:29]
	v_mfma_f32_16x16x32_bf16 v[14:17], v[158:161], v[218:221], v[14:17]
	v_mfma_f32_16x16x32_bf16 v[10:13], v[166:169], v[218:221], v[10:13]
	v_mfma_f32_16x16x32_bf16 v[54:57], v[170:173], v[190:193], v[54:57]
	v_mfma_f32_16x16x32_bf16 v[50:53], v[178:181], v[190:193], v[50:53]
	v_mfma_f32_16x16x32_bf16 v[38:41], v[170:173], v[198:201], v[38:41]
	v_mfma_f32_16x16x32_bf16 v[34:37], v[178:181], v[198:201], v[34:37]
	v_mfma_f32_16x16x32_bf16 v[22:25], v[170:173], v[206:209], v[22:25]
	v_mfma_f32_16x16x32_bf16 v[18:21], v[178:181], v[206:209], v[18:21]
	v_mfma_f32_16x16x32_bf16 v[6:9], v[170:173], v[214:217], v[6:9]
	v_mfma_f32_16x16x32_bf16 v[2:5], v[178:181], v[214:217], v[2:5]
	v_mfma_f32_16x16x32_bf16 v[54:57], v[174:177], v[194:197], v[54:57]
	v_mfma_f32_16x16x32_bf16 v[50:53], v[186:189], v[194:197], v[50:53]
	v_mfma_f32_16x16x32_bf16 v[38:41], v[174:177], v[202:205], v[38:41]
	v_mfma_f32_16x16x32_bf16 v[34:37], v[186:189], v[202:205], v[34:37]
	v_mfma_f32_16x16x32_bf16 v[22:25], v[174:177], v[210:213], v[22:25]
	v_mfma_f32_16x16x32_bf16 v[18:21], v[186:189], v[210:213], v[18:21]
	v_mfma_f32_16x16x32_bf16 v[6:9], v[174:177], v[218:221], v[6:9]
	v_mfma_f32_16x16x32_bf16 v[2:5], v[186:189], v[218:221], v[2:5]
	s_setprio 0
	s_barrier
	s_add_i32 s62, s62, 2
	s_add_u32 s36, s36, 0x100
	s_addc_u32 s37, s37, 0
	s_add_u32 s60, s60, 0x100
	s_addc_u32 s61, s61, 0
	s_cmp_gt_u32 s62, 41
	s_cbranch_scc0 .LBB0_278
	s_and_b64 vcc, exec, s[18:19]
	s_cbranch_vccz .LBB0_281
	s_barrier

; #define PG8_STAGE(bufoff, gbase, voff) do { _Pragma("unroll") for (int _i = 0; _i < 2; ++_i) \
;         __builtin_amdgcn_global_load_lds((const unsigned*)((const char*)(gbase) + (voff)[_i]), (LAS unsigned*)(lds + (bufoff) + ldsw + _i * 8192), 16, 0, 0); } while (0)
; #define PG8_LDA(dst, b, h) do { _Pragma("unroll") for (int m = 0; m < 4; ++m) _Pragma("unroll") for (int k = 0; k < 2; ++k) dst[m][k] = *(const LAS bf16x8*)(lds + PG8_SA(b, h) + aoff + m * 2048 + k * 1024); } while (0)
; #define PG8_LDB(dst, b, h) do { _Pragma("unroll") for (int n = 0; n < 2; ++n) _Pragma("unroll") for (int k = 0; k < 2; ++k) dst[n][k] = *(const LAS bf16x8*)(lds + PG8_SB(b, h) + boff + n * 2048 + k * 1024); } while (0)
; #define PG8_MMA(ai, bj, At, Bt) do { __builtin_amdgcn_s_setprio(1); _Pragma("unroll") for (int m = 0; m < 4; ++m) _Pragma("unroll") for (int n = 0; n < 2; ++n) _Pragma("unroll") for (int k = 0; k < 2; ++k) \
;         acc[ai][bj][m][n] = __builtin_amdgcn_mfma_f32_16x16x32_bf16(Bt[n][k], At[m][k], acc[ai][bj][m][n], 0, 0, 0); __builtin_amdgcn_s_setprio(0); } while (0)
; #define PG8_WAIT_V(n) asm volatile("s_waitcnt vmcnt(" #n ")" ::: "memory")
; #define PG8_WAIT_L(n) asm volatile("s_waitcnt lgkmcnt(" #n ")" ::: "memory")
; #define PG8_BAR __builtin_amdgcn_s_barrier()
; #define PG8_SCHED __builtin_amdgcn_sched_barrier(0)
; template <class Epi, class Sched>
; DI void gemm_phase(LAS unsigned char* lds, const Gemm g, const Sched& S, const Epi& E) {
;     ...
;             const bool last = (t == nt - 2);
;             const char* a1 = cA + (size_t)(t + 1) * kstep;
;             const char* a2 = last ? nA : cA + (size_t)(t + 2) * kstep; const char* b2 = last ? nB : cB + (size_t)(t + 2) * kstep;
;             const char* a3 = a2 + kstep; const char* b3 = b2 + kstep;
;             PG8_LDB(B0, 0, 0); PG8_LDB(B1, 0, 1); PG8_SCHED; PG8_LDA(At, 0, 0); PG8_STAGE(PG8_SA(1, 1), a1 + hstepA, voffA);
;             PG8_WAIT_V(8); PG8_WAIT_L(0); PG8_BAR; PG8_MMA(0, 0, At, B0); PG8_MMA(0, 1, At, B1); PG8_BAR; PG8_SCHED;
;             PG8_LDA(At, 0, 1); PG8_STAGE(PG8_SB(0, 0), b2, voffB); PG8_STAGE(PG8_SB(0, 1), b2 + hstepB, voffB); PG8_STAGE(PG8_SA(0, 0), a2, voffA);
;             PG8_WAIT_V(8); PG8_WAIT_L(0); PG8_BAR; PG8_MMA(1, 0, At, B0); PG8_MMA(1, 1, At, B1); PG8_BAR; PG8_SCHED;
.LBB0_381:
	ds_read_b128 v[138:141], v188
	ds_read_b128 v[142:145], v188 offset:1024
	ds_read_b128 v[176:179], v188 offset:2048
	ds_read_b128 v[198:201], v188 offset:3072
	ds_read_b128 v[202:205], v189
	ds_read_b128 v[206:209], v189 offset:1024
	ds_read_b128 v[210:213], v189 offset:2048
	ds_read_b128 v[214:217], v189 offset:3072
	s_add_u32 s64, s10, 0xfffc0080
	s_addc_u32 s65, s11, -1
	s_cmp_eq_u32 s69, 12
	s_cselect_b32 s67, s13, s65
	s_cselect_b32 s66, s29, s64
	s_cselect_b32 s65, s36, s68
	s_cselect_b32 s64, s57, s59
	v_lshl_add_u64 v[172:173], s[10:11], 0, v[162:163]
	s_add_i32 m0, s79, 0xc000
	ds_read_b128 v[218:221], v186
	ds_read_b128 v[222:225], v186 offset:1024
	ds_read_b128 v[226:229], v186 offset:2048
	ds_read_b128 v[230:233], v186 offset:3072
	ds_read_b128 v[234:237], v186 offset:4096
	ds_read_b128 v[238:241], v186 offset:5120
	ds_read_b128 v[242:245], v186 offset:6144
	ds_read_b128 v[246:249], v186 offset:7168
	global_load_lds_dwordx4 v[172:173], off
	v_lshl_add_u64 v[172:173], s[10:11], 0, v[164:165]
	s_add_i32 m0, s79, 0xe000
	s_nop 0
	global_load_lds_dwordx4 v[172:173], off
	s_waitcnt vmcnt(8)
	s_waitcnt lgkmcnt(0)
	s_barrier
	s_setprio 1
	v_mfma_f32_16x16x32_bf16 v[126:129], v[138:141], v[218:221], v[126:129]
	v_mfma_f32_16x16x32_bf16 v[122:125], v[176:179], v[218:221], v[122:125]
	v_mfma_f32_16x16x32_bf16 v[110:113], v[138:141], v[226:229], v[110:113]
	v_mfma_f32_16x16x32_bf16 v[106:109], v[176:179], v[226:229], v[106:109]
	v_mfma_f32_16x16x32_bf16 v[94:97], v[138:141], v[234:237], v[94:97]
	v_mfma_f32_16x16x32_bf16 v[90:93], v[176:179], v[234:237], v[90:93]
	v_mfma_f32_16x16x32_bf16 v[78:81], v[138:141], v[242:245], v[78:81]
	v_mfma_f32_16x16x32_bf16 v[74:77], v[176:179], v[242:245], v[74:77]
	v_mfma_f32_16x16x32_bf16 v[126:129], v[142:145], v[222:225], v[126:129]
	v_mfma_f32_16x16x32_bf16 v[122:125], v[198:201], v[222:225], v[122:125]
	v_mfma_f32_16x16x32_bf16 v[110:113], v[142:145], v[230:233], v[110:113]
	v_mfma_f32_16x16x32_bf16 v[106:109], v[198:201], v[230:233], v[106:109]
	v_mfma_f32_16x16x32_bf16 v[94:97], v[142:145], v[238:241], v[94:97]
	v_mfma_f32_16x16x32_bf16 v[90:93], v[198:201], v[238:241], v[90:93]
	v_mfma_f32_16x16x32_bf16 v[78:81], v[142:145], v[246:249], v[78:81]
	v_mfma_f32_16x16x32_bf16 v[74:77], v[198:201], v[246:249], v[74:77]
	v_mfma_f32_16x16x32_bf16 v[118:121], v[202:205], v[218:221], v[118:121]
	v_mfma_f32_16x16x32_bf16 v[114:117], v[210:213], v[218:221], v[114:117]
	v_mfma_f32_16x16x32_bf16 v[102:105], v[202:205], v[226:229], v[102:105]
	v_mfma_f32_16x16x32_bf16 v[98:101], v[210:213], v[226:229], v[98:101]
	v_mfma_f32_16x16x32_bf16 v[86:89], v[202:205], v[234:237], v[86:89]
	v_mfma_f32_16x16x32_bf16 v[82:85], v[210:213], v[234:237], v[82:85]
	v_mfma_f32_16x16x32_bf16 v[70:73], v[202:205], v[242:245], v[70:73]
	v_mfma_f32_16x16x32_bf16 v[66:69], v[210:213], v[242:245], v[66:69]
	v_mfma_f32_16x16x32_bf16 v[118:121], v[206:209], v[222:225], v[118:121]
	v_mfma_f32_16x16x32_bf16 v[114:117], v[214:217], v[222:225], v[114:117]
	v_mfma_f32_16x16x32_bf16 v[102:105], v[206:209], v[230:233], v[102:105]
	v_mfma_f32_16x16x32_bf16 v[98:101], v[214:217], v[230:233], v[98:101]
	v_mfma_f32_16x16x32_bf16 v[86:89], v[206:209], v[238:241], v[86:89]
	v_mfma_f32_16x16x32_bf16 v[82:85], v[214:217], v[238:241], v[82:85]
	v_mfma_f32_16x16x32_bf16 v[70:73], v[206:209], v[246:249], v[70:73]
	v_mfma_f32_16x16x32_bf16 v[66:69], v[214:217], v[246:249], v[66:69]
	s_setprio 0
	s_barrier
	s_add_i32 s70, s94, s78
	v_lshl_add_u64 v[172:173], s[64:65], 0, v[150:151]
	s_mov_b32 m0, s70
	ds_read_b128 v[218:221], v186 offset:16384
	ds_read_b128 v[222:225], v186 offset:17408
	ds_read_b128 v[226:229], v186 offset:18432
	ds_read_b128 v[230:233], v186 offset:19456
	ds_read_b128 v[234:237], v186 offset:20480
	ds_read_b128 v[238:241], v186 offset:21504
	ds_read_b128 v[242:245], v186 offset:22528
	ds_read_b128 v[246:249], v186 offset:23552
	global_load_lds_dwordx4 v[172:173], off
	s_add_i32 m0, s70, 0x2000
	s_add_u32 s70, s64, 0x40000
	v_lshl_add_u64 v[180:181], s[64:65], 0, v[154:155]
	s_addc_u32 s71, s65, 0
	s_add_i32 s72, s95, s78
	global_load_lds_dwordx4 v[180:181], off
	v_lshl_add_u64 v[250:251], s[70:71], 0, v[150:151]
	s_mov_b32 m0, s72
	v_lshl_add_u64 v[252:253], s[66:67], 0, v[152:153]
	global_load_lds_dwordx4 v[250:251], off
	v_lshl_add_u64 v[250:251], s[70:71], 0, v[154:155]
	s_add_i32 m0, s72, 0x2000
	s_nop 0
	global_load_lds_dwordx4 v[250:251], off
	v_lshl_add_u64 v[250:251], s[66:67], 0, v[148:149]
	s_mov_b32 m0, s79
	s_nop 0
	global_load_lds_dwordx4 v[250:251], off
	s_mov_b32 m0, s80
	s_nop 0
	global_load_lds_dwordx4 v[252:253], off
	s_waitcnt vmcnt(8)
	s_waitcnt lgkmcnt(0)
	s_barrier
; #define PG8_STAGE(bufoff, gbase, voff) do { _Pragma("unroll") for (int _i = 0; _i < 2; ++_i) \
;         __builtin_amdgcn_global_load_lds((const unsigned*)((const char*)(gbase) + (voff)[_i]), (LAS unsigned*)(lds + (bufoff) + ldsw + _i * 8192), 16, 0, 0); } while (0)
; #define PG8_LDA(dst, b, h) do { _Pragma("unroll") for (int m = 0; m < 4; ++m) _Pragma("unroll") for (int k = 0; k < 2; ++k) dst[m][k] = *(const LAS bf16x8*)(lds + PG8_SA(b, h) + aoff + m * 2048 + k * 1024); } while (0)
; #define PG8_LDB(dst, b, h) do { _Pragma("unroll") for (int n = 0; n < 2; ++n) _Pragma("unroll") for (int k = 0; k < 2; ++k) dst[n][k] = *(const LAS bf16x8*)(lds + PG8_SB(b, h) + boff + n * 2048 + k * 1024); } while (0)
; #define PG8_MMA(ai, bj, At, Bt) do { __builtin_amdgcn_s_setprio(1); _Pragma("unroll") for (int m = 0; m < 4; ++m) _Pragma("unroll") for (int n = 0; n < 2; ++n) _Pragma("unroll") for (int k = 0; k < 2; ++k) \
;         acc[ai][bj][m][n] = __builtin_amdgcn_mfma_f32_16x16x32_bf16(Bt[n][k], At[m][k], acc[ai][bj][m][n], 0, 0, 0); __builtin_amdgcn_s_setprio(0); } while (0)
; #define PG8_WAIT_V(n) asm volatile("s_waitcnt vmcnt(" #n ")" ::: "memory")
; #define PG8_WAIT_L(n) asm volatile("s_waitcnt lgkmcnt(" #n ")" ::: "memory")
; #define PG8_BAR __builtin_amdgcn_s_barrier()
; #define PG8_SCHED __builtin_amdgcn_sched_barrier(0)
; template <class Epi, class Sched>
; DI void gemm_phase(LAS unsigned char* lds, const Gemm g, const Sched& S, const Epi& E) {
;     ...
;             PG8_WAIT_V(8); PG8_WAIT_L(0); PG8_BAR; PG8_MMA(1, 0, At, B0); PG8_MMA(1, 1, At, B1); PG8_BAR; PG8_SCHED;
;             PG8_LDB(B0, 1, 0); PG8_LDB(B1, 1, 1); PG8_SCHED; PG8_LDA(At, 1, 0); PG8_STAGE(PG8_SA(0, 1), a2 + hstepA, voffA);
;             PG8_WAIT_V(8); PG8_WAIT_L(0); PG8_BAR; PG8_MMA(0, 0, At, B0); PG8_MMA(0, 1, At, B1); PG8_BAR; PG8_SCHED;
	s_setprio 1
	v_mfma_f32_16x16x32_bf16 v[62:65], v[138:141], v[218:221], v[62:65]
	v_mfma_f32_16x16x32_bf16 v[58:61], v[176:179], v[218:221], v[58:61]
	v_mfma_f32_16x16x32_bf16 v[46:49], v[138:141], v[226:229], v[46:49]
	v_mfma_f32_16x16x32_bf16 v[42:45], v[176:179], v[226:229], v[42:45]
	v_mfma_f32_16x16x32_bf16 v[30:33], v[138:141], v[234:237], v[30:33]
	v_mfma_f32_16x16x32_bf16 v[26:29], v[176:179], v[234:237], v[26:29]
	v_mfma_f32_16x16x32_bf16 v[14:17], v[138:141], v[242:245], v[14:17]
	v_mfma_f32_16x16x32_bf16 v[10:13], v[176:179], v[242:245], v[10:13]
	v_mfma_f32_16x16x32_bf16 v[62:65], v[142:145], v[222:225], v[62:65]
	v_mfma_f32_16x16x32_bf16 v[58:61], v[198:201], v[222:225], v[58:61]
	v_mfma_f32_16x16x32_bf16 v[46:49], v[142:145], v[230:233], v[46:49]
	v_mfma_f32_16x16x32_bf16 v[42:45], v[198:201], v[230:233], v[42:45]
	v_mfma_f32_16x16x32_bf16 v[30:33], v[142:145], v[238:241], v[30:33]
	v_mfma_f32_16x16x32_bf16 v[26:29], v[198:201], v[238:241], v[26:29]
	v_mfma_f32_16x16x32_bf16 v[14:17], v[142:145], v[246:249], v[14:17]
	v_mfma_f32_16x16x32_bf16 v[10:13], v[198:201], v[246:249], v[10:13]
	v_mfma_f32_16x16x32_bf16 v[54:57], v[202:205], v[218:221], v[54:57]
	v_mfma_f32_16x16x32_bf16 v[50:53], v[210:213], v[218:221], v[50:53]
	v_mfma_f32_16x16x32_bf16 v[38:41], v[202:205], v[226:229], v[38:41]
	v_mfma_f32_16x16x32_bf16 v[34:37], v[210:213], v[226:229], v[34:37]
	v_mfma_f32_16x16x32_bf16 v[22:25], v[202:205], v[234:237], v[22:25]
	v_mfma_f32_16x16x32_bf16 v[18:21], v[210:213], v[234:237], v[18:21]
	v_mfma_f32_16x16x32_bf16 v[6:9], v[202:205], v[242:245], v[6:9]
	v_mfma_f32_16x16x32_bf16 v[2:5], v[210:213], v[242:245], v[2:5]
	v_mfma_f32_16x16x32_bf16 v[54:57], v[206:209], v[222:225], v[54:57]
	v_mfma_f32_16x16x32_bf16 v[50:53], v[214:217], v[222:225], v[50:53]
	v_mfma_f32_16x16x32_bf16 v[38:41], v[206:209], v[230:233], v[38:41]
	v_mfma_f32_16x16x32_bf16 v[34:37], v[214:217], v[230:233], v[34:37]
	v_mfma_f32_16x16x32_bf16 v[22:25], v[206:209], v[238:241], v[22:25]
	v_mfma_f32_16x16x32_bf16 v[18:21], v[214:217], v[238:241], v[18:21]
	v_mfma_f32_16x16x32_bf16 v[6:9], v[206:209], v[246:249], v[6:9]
	v_mfma_f32_16x16x32_bf16 v[2:5], v[214:217], v[246:249], v[2:5]
	s_setprio 0
	s_barrier
	s_add_i32 s70, 0, 0x18000
	v_add_u32_e32 v156, s70, v159
	s_add_i32 s71, 0, 0x1c000
	ds_read_b128 v[138:141], v156
	ds_read_b128 v[142:145], v156 offset:1024
	ds_read_b128 v[176:179], v156 offset:2048
	ds_read_b128 v[198:201], v156 offset:3072
	v_add_u32_e32 v156, s71, v159
	ds_read_b128 v[202:205], v156
	ds_read_b128 v[206:209], v156 offset:1024
	ds_read_b128 v[210:213], v156 offset:2048
	ds_read_b128 v[214:217], v156 offset:3072
	s_add_u32 s66, s66, 0x40000
	s_addc_u32 s67, s67, 0
	s_mov_b32 m0, s81
	v_lshl_add_u64 v[254:255], s[66:67], 0, v[148:149]
	ds_read_b128 v[218:221], v186 offset:32768
	ds_read_b128 v[222:225], v186 offset:33792
	ds_read_b128 v[226:229], v186 offset:34816
	ds_read_b128 v[230:233], v186 offset:35840
	ds_read_b128 v[234:237], v186 offset:36864
	ds_read_b128 v[238:241], v186 offset:37888
	ds_read_b128 v[242:245], v186 offset:38912
	ds_read_b128 v[246:249], v186 offset:39936
	global_load_lds_dwordx4 v[254:255], off
	v_lshl_add_u64 v[254:255], s[66:67], 0, v[152:153]
	s_mov_b32 m0, s82
	s_nop 0
	global_load_lds_dwordx4 v[254:255], off
	s_waitcnt vmcnt(8)
	s_waitcnt lgkmcnt(0)
	s_barrier
	s_setprio 1
	v_mfma_f32_16x16x32_bf16 v[126:129], v[138:141], v[218:221], v[126:129]
	v_mfma_f32_16x16x32_bf16 v[122:125], v[176:179], v[218:221], v[122:125]
	v_mfma_f32_16x16x32_bf16 v[110:113], v[138:141], v[226:229], v[110:113]
	v_mfma_f32_16x16x32_bf16 v[106:109], v[176:179], v[226:229], v[106:109]
	v_mfma_f32_16x16x32_bf16 v[94:97], v[138:141], v[234:237], v[94:97]
	v_mfma_f32_16x16x32_bf16 v[90:93], v[176:179], v[234:237], v[90:93]
	v_mfma_f32_16x16x32_bf16 v[78:81], v[138:141], v[242:245], v[78:81]
	v_mfma_f32_16x16x32_bf16 v[74:77], v[176:179], v[242:245], v[74:77]
	v_mfma_f32_16x16x32_bf16 v[126:129], v[142:145], v[222:225], v[126:129]
	v_mfma_f32_16x16x32_bf16 v[122:125], v[198:201], v[222:225], v[122:125]
	v_mfma_f32_16x16x32_bf16 v[110:113], v[142:145], v[230:233], v[110:113]
	v_mfma_f32_16x16x32_bf16 v[106:109], v[198:201], v[230:233], v[106:109]
	v_mfma_f32_16x16x32_bf16 v[94:97], v[142:145], v[238:241], v[94:97]
	v_mfma_f32_16x16x32_bf16 v[90:93], v[198:201], v[238:241], v[90:93]
	v_mfma_f32_16x16x32_bf16 v[78:81], v[142:145], v[246:249], v[78:81]
	v_mfma_f32_16x16x32_bf16 v[74:77], v[198:201], v[246:249], v[74:77]
	v_mfma_f32_16x16x32_bf16 v[118:121], v[202:205], v[218:221], v[118:121]
	v_mfma_f32_16x16x32_bf16 v[114:117], v[210:213], v[218:221], v[114:117]
	v_mfma_f32_16x16x32_bf16 v[102:105], v[202:205], v[226:229], v[102:105]
	v_mfma_f32_16x16x32_bf16 v[98:101], v[210:213], v[226:229], v[98:101]
	v_mfma_f32_16x16x32_bf16 v[86:89], v[202:205], v[234:237], v[86:89]
	v_mfma_f32_16x16x32_bf16 v[82:85], v[210:213], v[234:237], v[82:85]
	v_mfma_f32_16x16x32_bf16 v[70:73], v[202:205], v[242:245], v[70:73]
	v_mfma_f32_16x16x32_bf16 v[66:69], v[210:213], v[242:245], v[66:69]
	v_mfma_f32_16x16x32_bf16 v[118:121], v[206:209], v[222:225], v[118:121]
	v_mfma_f32_16x16x32_bf16 v[114:117], v[214:217], v[222:225], v[114:117]
	v_mfma_f32_16x16x32_bf16 v[102:105], v[206:209], v[230:233], v[102:105]
	v_mfma_f32_16x16x32_bf16 v[98:101], v[214:217], v[230:233], v[98:101]
	v_mfma_f32_16x16x32_bf16 v[86:89], v[206:209], v[238:241], v[86:89]
	v_mfma_f32_16x16x32_bf16 v[82:85], v[214:217], v[238:241], v[82:85]
	v_mfma_f32_16x16x32_bf16 v[70:73], v[206:209], v[246:249], v[70:73]
	v_mfma_f32_16x16x32_bf16 v[66:69], v[214:217], v[246:249], v[66:69]
	s_setprio 0
	s_barrier
; #define PG8_STAGE(bufoff, gbase, voff) do { _Pragma("unroll") for (int _i = 0; _i < 2; ++_i) \
;         __builtin_amdgcn_global_load_lds((const unsigned*)((const char*)(gbase) + (voff)[_i]), (LAS unsigned*)(lds + (bufoff) + ldsw + _i * 8192), 16, 0, 0); } while (0)
; #define PG8_LDA(dst, b, h) do { _Pragma("unroll") for (int m = 0; m < 4; ++m) _Pragma("unroll") for (int k = 0; k < 2; ++k) dst[m][k] = *(const LAS bf16x8*)(lds + PG8_SA(b, h) + aoff + m * 2048 + k * 1024); } while (0)
; #define PG8_MMA(ai, bj, At, Bt) do { __builtin_amdgcn_s_setprio(1); _Pragma("unroll") for (int m = 0; m < 4; ++m) _Pragma("unroll") for (int n = 0; n < 2; ++n) _Pragma("unroll") for (int k = 0; k < 2; ++k) \
;         acc[ai][bj][m][n] = __builtin_amdgcn_mfma_f32_16x16x32_bf16(Bt[n][k], At[m][k], acc[ai][bj][m][n], 0, 0, 0); __builtin_amdgcn_s_setprio(0); } while (0)
; #define PG8_WAIT_V(n) asm volatile("s_waitcnt vmcnt(" #n ")" ::: "memory")
; #define PG8_WAIT_L(n) asm volatile("s_waitcnt lgkmcnt(" #n ")" ::: "memory")
; #define PG8_BAR __builtin_amdgcn_s_barrier()
; #define PG8_SCHED __builtin_amdgcn_sched_barrier(0)
; template <class Epi, class Sched>
; DI void gemm_phase(LAS unsigned char* lds, const Gemm g, const Sched& S, const Epi& E) {
;     ...
;             PG8_LDA(At, 1, 1); PG8_STAGE(PG8_SB(1, 0), b3, voffB); PG8_STAGE(PG8_SB(1, 1), b3 + hstepB, voffB); PG8_STAGE(PG8_SA(1, 0), a3, voffA);
;             PG8_WAIT_V(8); PG8_WAIT_L(0); PG8_BAR; PG8_MMA(1, 0, At, B0); PG8_MMA(1, 1, At, B1); PG8_BAR; PG8_SCHED;
;         }
;         if (wr == 0) PG8_BAR;
;     DI void operator()(Acc& acc, const pg8::Unit& u, int wr, int wc, int fr, int fq, const Pre& pr) const {
;         const int pn = u.pn;
;         if (pn < 5) {
	s_add_i32 s66, s70, s78
	v_lshl_add_u64 v[172:173], v[172:173], 0, s[50:51]
	s_mov_b32 m0, s66
	ds_read_b128 v[218:221], v186 offset:49152
	ds_read_b128 v[222:225], v186 offset:50176
	ds_read_b128 v[226:229], v186 offset:51200
	ds_read_b128 v[230:233], v186 offset:52224
	ds_read_b128 v[234:237], v186 offset:53248
	ds_read_b128 v[238:241], v186 offset:54272
	ds_read_b128 v[242:245], v186 offset:55296
	ds_read_b128 v[246:249], v186 offset:56320
	global_load_lds_dwordx4 v[172:173], off
	s_add_i32 m0, s66, 0x2000
	s_add_u32 s64, s64, 0x40080
	v_lshl_add_u64 v[172:173], v[180:181], 0, s[50:51]
	s_addc_u32 s65, s65, 0
	s_add_i32 s66, s71, s78
	global_load_lds_dwordx4 v[172:173], off
	v_lshl_add_u64 v[172:173], s[64:65], 0, v[150:151]
	s_mov_b32 m0, s66
	s_nop 0
	global_load_lds_dwordx4 v[172:173], off
	v_lshl_add_u64 v[172:173], s[64:65], 0, v[154:155]
	s_add_i32 m0, s66, 0x2000
	s_nop 0
	global_load_lds_dwordx4 v[172:173], off
	v_lshl_add_u64 v[172:173], v[250:251], 0, s[50:51]
	s_mov_b32 m0, s86
	s_nop 0
	global_load_lds_dwordx4 v[172:173], off
	v_lshl_add_u64 v[172:173], v[252:253], 0, s[50:51]
	s_mov_b32 m0, s87
	s_nop 0
	global_load_lds_dwordx4 v[172:173], off
	s_waitcnt vmcnt(8)
	s_waitcnt lgkmcnt(0)
	s_barrier
	s_setprio 1
	v_mfma_f32_16x16x32_bf16 v[62:65], v[138:141], v[218:221], v[62:65]
	v_mfma_f32_16x16x32_bf16 v[58:61], v[176:179], v[218:221], v[58:61]
	v_mfma_f32_16x16x32_bf16 v[46:49], v[138:141], v[226:229], v[46:49]
	v_mfma_f32_16x16x32_bf16 v[42:45], v[176:179], v[226:229], v[42:45]
	v_mfma_f32_16x16x32_bf16 v[30:33], v[138:141], v[234:237], v[30:33]
	v_mfma_f32_16x16x32_bf16 v[26:29], v[176:179], v[234:237], v[26:29]
	v_mfma_f32_16x16x32_bf16 v[14:17], v[138:141], v[242:245], v[14:17]
	v_mfma_f32_16x16x32_bf16 v[10:13], v[176:179], v[242:245], v[10:13]
	v_mfma_f32_16x16x32_bf16 v[62:65], v[142:145], v[222:225], v[62:65]
	v_mfma_f32_16x16x32_bf16 v[58:61], v[198:201], v[222:225], v[58:61]
	v_mfma_f32_16x16x32_bf16 v[46:49], v[142:145], v[230:233], v[46:49]
	v_mfma_f32_16x16x32_bf16 v[42:45], v[198:201], v[230:233], v[42:45]
	v_mfma_f32_16x16x32_bf16 v[30:33], v[142:145], v[238:241], v[30:33]
	v_mfma_f32_16x16x32_bf16 v[26:29], v[198:201], v[238:241], v[26:29]
	v_mfma_f32_16x16x32_bf16 v[14:17], v[142:145], v[246:249], v[14:17]
	v_mfma_f32_16x16x32_bf16 v[10:13], v[198:201], v[246:249], v[10:13]
	v_mfma_f32_16x16x32_bf16 v[54:57], v[202:205], v[218:221], v[54:57]
	v_mfma_f32_16x16x32_bf16 v[50:53], v[210:213], v[218:221], v[50:53]
	v_mfma_f32_16x16x32_bf16 v[38:41], v[202:205], v[226:229], v[38:41]
	v_mfma_f32_16x16x32_bf16 v[34:37], v[210:213], v[226:229], v[34:37]
	v_mfma_f32_16x16x32_bf16 v[22:25], v[202:205], v[234:237], v[22:25]
	v_mfma_f32_16x16x32_bf16 v[18:21], v[210:213], v[234:237], v[18:21]
	v_mfma_f32_16x16x32_bf16 v[6:9], v[202:205], v[242:245], v[6:9]
	v_mfma_f32_16x16x32_bf16 v[2:5], v[210:213], v[242:245], v[2:5]
	v_mfma_f32_16x16x32_bf16 v[54:57], v[206:209], v[222:225], v[54:57]
	v_mfma_f32_16x16x32_bf16 v[50:53], v[214:217], v[222:225], v[50:53]
	v_mfma_f32_16x16x32_bf16 v[38:41], v[206:209], v[230:233], v[38:41]
	v_mfma_f32_16x16x32_bf16 v[34:37], v[214:217], v[230:233], v[34:37]
	v_mfma_f32_16x16x32_bf16 v[22:25], v[206:209], v[238:241], v[22:25]
	v_mfma_f32_16x16x32_bf16 v[18:21], v[214:217], v[238:241], v[18:21]
	v_mfma_f32_16x16x32_bf16 v[6:9], v[206:209], v[246:249], v[6:9]
	v_mfma_f32_16x16x32_bf16 v[2:5], v[214:217], v[246:249], v[2:5]
	s_setprio 0
	s_barrier
	s_add_i32 s69, s69, 2
	s_add_u32 s10, s10, 0x100
	s_addc_u32 s11, s11, 0
	s_add_u32 s59, s59, 0x100
	s_addc_u32 s68, s68, 0
	s_cmp_gt_u32 s69, 13
	s_cbranch_scc0 .LBB0_381
	s_and_b64 vcc, exec, s[52:53]
	s_cbranch_vccnz .LBB0_386
	s_cmp_gt_i32 s12, 4
	s_mov_b64 s[10:11], -1
	s_cbranch_scc1 .LBB0_387

; #define PG8_STAGE(bufoff, gbase, voff) do { _Pragma("unroll") for (int _i = 0; _i < 2; ++_i) \
;         __builtin_amdgcn_global_load_lds((const unsigned*)((const char*)(gbase) + (voff)[_i]), (LAS unsigned*)(lds + (bufoff) + ldsw + _i * 8192), 16, 0, 0); } while (0)
; #define PG8_LDA(dst, b, h) do { _Pragma("unroll") for (int m = 0; m < 4; ++m) _Pragma("unroll") for (int k = 0; k < 2; ++k) dst[m][k] = *(const LAS bf16x8*)(lds + PG8_SA(b, h) + aoff + m * 2048 + k * 1024); } while (0)
; #define PG8_LDB(dst, b, h) do { _Pragma("unroll") for (int n = 0; n < 2; ++n) _Pragma("unroll") for (int k = 0; k < 2; ++k) dst[n][k] = *(const LAS bf16x8*)(lds + PG8_SB(b, h) + boff + n * 2048 + k * 1024); } while (0)
; #define PG8_MMA(ai, bj, At, Bt) do { __builtin_amdgcn_s_setprio(1); _Pragma("unroll") for (int m = 0; m < 4; ++m) _Pragma("unroll") for (int n = 0; n < 2; ++n) _Pragma("unroll") for (int k = 0; k < 2; ++k) \
;         acc[ai][bj][m][n] = __builtin_amdgcn_mfma_f32_16x16x32_bf16(Bt[n][k], At[m][k], acc[ai][bj][m][n], 0, 0, 0); __builtin_amdgcn_s_setprio(0); } while (0)
; #define PG8_WAIT_V(n) asm volatile("s_waitcnt vmcnt(" #n ")" ::: "memory")
; #define PG8_WAIT_L(n) asm volatile("s_waitcnt lgkmcnt(" #n ")" ::: "memory")
; #define PG8_BAR __builtin_amdgcn_s_barrier()
; #define PG8_SCHED __builtin_amdgcn_sched_barrier(0)
; template <class Epi, class Sched>
; DI void gemm_phase(LAS unsigned char* lds, const Gemm g, const Sched& S, const Epi& E) {
;     ...
;             const bool last = (t == nt - 2);
;             const char* a1 = cA + (size_t)(t + 1) * kstep;
;             const char* a2 = last ? nA : cA + (size_t)(t + 2) * kstep; const char* b2 = last ? nB : cB + (size_t)(t + 2) * kstep;
;             const char* a3 = a2 + kstep; const char* b3 = b2 + kstep;
;             PG8_LDB(B0, 0, 0); PG8_LDB(B1, 0, 1); PG8_SCHED; PG8_LDA(At, 0, 0); PG8_STAGE(PG8_SA(1, 1), a1 + hstepA, voffA);
;             PG8_WAIT_V(8); PG8_WAIT_L(0); PG8_BAR; PG8_MMA(0, 0, At, B0); PG8_MMA(0, 1, At, B1); PG8_BAR; PG8_SCHED;
;             PG8_LDA(At, 0, 1); PG8_STAGE(PG8_SB(0, 0), b2, voffB); PG8_STAGE(PG8_SB(0, 1), b2 + hstepB, voffB); PG8_STAGE(PG8_SA(0, 0), a2, voffA);
;             PG8_WAIT_V(8); PG8_WAIT_L(0); PG8_BAR; PG8_MMA(1, 0, At, B0); PG8_MMA(1, 1, At, B1); PG8_BAR; PG8_SCHED;
.LBB0_579:
	ds_read_b128 v[150:153], v142
	ds_read_b128 v[154:157], v142 offset:1024
	ds_read_b128 v[158:161], v142 offset:2048
	ds_read_b128 v[162:165], v142 offset:3072
	ds_read_b128 v[166:169], v143
	ds_read_b128 v[170:173], v143 offset:1024
	ds_read_b128 v[174:177], v143 offset:2048
	ds_read_b128 v[178:181], v143 offset:3072
	s_add_u32 s16, s8, s12
	s_addc_u32 s17, s9, s13
	s_add_u32 s16, s16, 0x100
	s_addc_u32 s17, s17, 0
	s_add_u32 s52, s39, s12
	s_addc_u32 s53, s40, s13
	s_cmpk_eq_i32 s12, 0xf00
	s_cselect_b32 s19, s9, s17
	s_cselect_b32 s18, s8, s16
	s_cselect_b32 s17, s7, s53
	s_cselect_b32 s16, s6, s52
	s_mov_b32 m0, s42
	v_lshl_add_u64 v[182:183], v[138:139], 0, s[12:13]
	ds_read_b128 v[186:189], v145
	ds_read_b128 v[190:193], v145 offset:1024
	ds_read_b128 v[194:197], v145 offset:2048
	ds_read_b128 v[198:201], v145 offset:3072
	ds_read_b128 v[202:205], v145 offset:4096
	ds_read_b128 v[206:209], v145 offset:5120
	ds_read_b128 v[210:213], v145 offset:6144
	ds_read_b128 v[214:217], v145 offset:7168
	global_load_lds_dwordx4 v[182:183], off
	v_lshl_add_u64 v[182:183], v[140:141], 0, s[12:13]
	s_mov_b32 m0, s43
	s_nop 0
	global_load_lds_dwordx4 v[182:183], off
	s_waitcnt vmcnt(8)
	s_waitcnt lgkmcnt(0)
	s_barrier
	s_setprio 1
	v_mfma_f32_16x16x32_bf16 v[126:129], v[150:153], v[186:189], v[126:129]
	v_mfma_f32_16x16x32_bf16 v[122:125], v[158:161], v[186:189], v[122:125]
	v_mfma_f32_16x16x32_bf16 v[118:121], v[150:153], v[194:197], v[118:121]
	v_mfma_f32_16x16x32_bf16 v[114:117], v[158:161], v[194:197], v[114:117]
	v_mfma_f32_16x16x32_bf16 v[110:113], v[150:153], v[202:205], v[110:113]
	v_mfma_f32_16x16x32_bf16 v[106:109], v[158:161], v[202:205], v[106:109]
	v_mfma_f32_16x16x32_bf16 v[102:105], v[150:153], v[210:213], v[102:105]
	v_mfma_f32_16x16x32_bf16 v[98:101], v[158:161], v[210:213], v[98:101]
	v_mfma_f32_16x16x32_bf16 v[126:129], v[154:157], v[190:193], v[126:129]
	v_mfma_f32_16x16x32_bf16 v[122:125], v[162:165], v[190:193], v[122:125]
	v_mfma_f32_16x16x32_bf16 v[118:121], v[154:157], v[198:201], v[118:121]
	v_mfma_f32_16x16x32_bf16 v[114:117], v[162:165], v[198:201], v[114:117]
	v_mfma_f32_16x16x32_bf16 v[110:113], v[154:157], v[206:209], v[110:113]
	v_mfma_f32_16x16x32_bf16 v[106:109], v[162:165], v[206:209], v[106:109]
	v_mfma_f32_16x16x32_bf16 v[102:105], v[154:157], v[214:217], v[102:105]
	v_mfma_f32_16x16x32_bf16 v[98:101], v[162:165], v[214:217], v[98:101]
	v_mfma_f32_16x16x32_bf16 v[62:65], v[166:169], v[186:189], v[62:65]
	v_mfma_f32_16x16x32_bf16 v[58:61], v[174:177], v[186:189], v[58:61]
	v_mfma_f32_16x16x32_bf16 v[54:57], v[166:169], v[194:197], v[54:57]
	v_mfma_f32_16x16x32_bf16 v[50:53], v[174:177], v[194:197], v[50:53]
	v_mfma_f32_16x16x32_bf16 v[46:49], v[166:169], v[202:205], v[46:49]
	v_mfma_f32_16x16x32_bf16 v[42:45], v[174:177], v[202:205], v[42:45]
	v_mfma_f32_16x16x32_bf16 v[38:41], v[166:169], v[210:213], v[38:41]
	v_mfma_f32_16x16x32_bf16 v[34:37], v[174:177], v[210:213], v[34:37]
	v_mfma_f32_16x16x32_bf16 v[62:65], v[170:173], v[190:193], v[62:65]
	v_mfma_f32_16x16x32_bf16 v[58:61], v[178:181], v[190:193], v[58:61]
	v_mfma_f32_16x16x32_bf16 v[54:57], v[170:173], v[198:201], v[54:57]
	v_mfma_f32_16x16x32_bf16 v[50:53], v[178:181], v[198:201], v[50:53]
	v_mfma_f32_16x16x32_bf16 v[46:49], v[170:173], v[206:209], v[46:49]
	v_mfma_f32_16x16x32_bf16 v[42:45], v[178:181], v[206:209], v[42:45]
	v_mfma_f32_16x16x32_bf16 v[38:41], v[170:173], v[214:217], v[38:41]
	v_mfma_f32_16x16x32_bf16 v[34:37], v[178:181], v[214:217], v[34:37]
	s_setprio 0
	s_barrier
	s_mov_b32 m0, s44
	v_lshl_add_u64 v[182:183], s[16:17], 0, v[134:135]
	s_add_u32 s52, s16, 0x80000
	ds_read_b128 v[186:189], v145 offset:16384
	ds_read_b128 v[190:193], v145 offset:17408
	ds_read_b128 v[194:197], v145 offset:18432
	ds_read_b128 v[198:201], v145 offset:19456
	ds_read_b128 v[202:205], v145 offset:20480
	ds_read_b128 v[206:209], v145 offset:21504
	ds_read_b128 v[210:213], v145 offset:22528
	ds_read_b128 v[214:217], v145 offset:23552
	global_load_lds_dwordx4 v[182:183], off
	v_lshl_add_u64 v[218:219], s[16:17], 0, v[130:131]
	s_mov_b32 m0, s45
	s_addc_u32 s53, s17, 0
	global_load_lds_dwordx4 v[218:219], off
	v_lshl_add_u64 v[220:221], s[52:53], 0, v[134:135]
	s_mov_b32 m0, s46
	v_lshl_add_u64 v[222:223], s[18:19], 0, v[132:133]
	global_load_lds_dwordx4 v[220:221], off
	v_lshl_add_u64 v[220:221], s[52:53], 0, v[130:131]
	s_mov_b32 m0, s47
	s_nop 0
	global_load_lds_dwordx4 v[220:221], off
	v_lshl_add_u64 v[220:221], s[18:19], 0, v[136:137]
	s_mov_b32 m0, s28
	s_nop 0
	global_load_lds_dwordx4 v[220:221], off
	s_mov_b32 m0, s29
	s_nop 0
	global_load_lds_dwordx4 v[222:223], off
	s_waitcnt vmcnt(8)
	s_waitcnt lgkmcnt(0)
	s_barrier
; #define PG8_STAGE(bufoff, gbase, voff) do { _Pragma("unroll") for (int _i = 0; _i < 2; ++_i) \
;         __builtin_amdgcn_global_load_lds((const unsigned*)((const char*)(gbase) + (voff)[_i]), (LAS unsigned*)(lds + (bufoff) + ldsw + _i * 8192), 16, 0, 0); } while (0)
; #define PG8_LDA(dst, b, h) do { _Pragma("unroll") for (int m = 0; m < 4; ++m) _Pragma("unroll") for (int k = 0; k < 2; ++k) dst[m][k] = *(const LAS bf16x8*)(lds + PG8_SA(b, h) + aoff + m * 2048 + k * 1024); } while (0)
; #define PG8_LDB(dst, b, h) do { _Pragma("unroll") for (int n = 0; n < 2; ++n) _Pragma("unroll") for (int k = 0; k < 2; ++k) dst[n][k] = *(const LAS bf16x8*)(lds + PG8_SB(b, h) + boff + n * 2048 + k * 1024); } while (0)
; #define PG8_MMA(ai, bj, At, Bt) do { __builtin_amdgcn_s_setprio(1); _Pragma("unroll") for (int m = 0; m < 4; ++m) _Pragma("unroll") for (int n = 0; n < 2; ++n) _Pragma("unroll") for (int k = 0; k < 2; ++k) \
;         acc[ai][bj][m][n] = __builtin_amdgcn_mfma_f32_16x16x32_bf16(Bt[n][k], At[m][k], acc[ai][bj][m][n], 0, 0, 0); __builtin_amdgcn_s_setprio(0); } while (0)
; #define PG8_WAIT_V(n) asm volatile("s_waitcnt vmcnt(" #n ")" ::: "memory")
; #define PG8_WAIT_L(n) asm volatile("s_waitcnt lgkmcnt(" #n ")" ::: "memory")
; #define PG8_BAR __builtin_amdgcn_s_barrier()
; #define PG8_SCHED __builtin_amdgcn_sched_barrier(0)
; template <class Epi, class Sched>
; DI void gemm_phase(LAS unsigned char* lds, const Gemm g, const Sched& S, const Epi& E) {
;     ...
;             PG8_WAIT_V(8); PG8_WAIT_L(0); PG8_BAR; PG8_MMA(1, 0, At, B0); PG8_MMA(1, 1, At, B1); PG8_BAR; PG8_SCHED;
;             PG8_LDB(B0, 1, 0); PG8_LDB(B1, 1, 1); PG8_SCHED; PG8_LDA(At, 1, 0); PG8_STAGE(PG8_SA(0, 1), a2 + hstepA, voffA);
;             PG8_WAIT_V(8); PG8_WAIT_L(0); PG8_BAR; PG8_MMA(0, 0, At, B0); PG8_MMA(0, 1, At, B1); PG8_BAR; PG8_SCHED;
	s_setprio 1
	v_mfma_f32_16x16x32_bf16 v[94:97], v[150:153], v[186:189], v[94:97]
	v_mfma_f32_16x16x32_bf16 v[90:93], v[158:161], v[186:189], v[90:93]
	v_mfma_f32_16x16x32_bf16 v[86:89], v[150:153], v[194:197], v[86:89]
	v_mfma_f32_16x16x32_bf16 v[82:85], v[158:161], v[194:197], v[82:85]
	v_mfma_f32_16x16x32_bf16 v[78:81], v[150:153], v[202:205], v[78:81]
	v_mfma_f32_16x16x32_bf16 v[74:77], v[158:161], v[202:205], v[74:77]
	v_mfma_f32_16x16x32_bf16 v[70:73], v[150:153], v[210:213], v[70:73]
	v_mfma_f32_16x16x32_bf16 v[66:69], v[158:161], v[210:213], v[66:69]
	v_mfma_f32_16x16x32_bf16 v[94:97], v[154:157], v[190:193], v[94:97]
	v_mfma_f32_16x16x32_bf16 v[90:93], v[162:165], v[190:193], v[90:93]
	v_mfma_f32_16x16x32_bf16 v[86:89], v[154:157], v[198:201], v[86:89]
	v_mfma_f32_16x16x32_bf16 v[82:85], v[162:165], v[198:201], v[82:85]
	v_mfma_f32_16x16x32_bf16 v[78:81], v[154:157], v[206:209], v[78:81]
	v_mfma_f32_16x16x32_bf16 v[74:77], v[162:165], v[206:209], v[74:77]
	v_mfma_f32_16x16x32_bf16 v[70:73], v[154:157], v[214:217], v[70:73]
	v_mfma_f32_16x16x32_bf16 v[66:69], v[162:165], v[214:217], v[66:69]
	v_mfma_f32_16x16x32_bf16 v[30:33], v[166:169], v[186:189], v[30:33]
	v_mfma_f32_16x16x32_bf16 v[26:29], v[174:177], v[186:189], v[26:29]
	v_mfma_f32_16x16x32_bf16 v[22:25], v[166:169], v[194:197], v[22:25]
	v_mfma_f32_16x16x32_bf16 v[18:21], v[174:177], v[194:197], v[18:21]
	v_mfma_f32_16x16x32_bf16 v[14:17], v[166:169], v[202:205], v[14:17]
	v_mfma_f32_16x16x32_bf16 v[10:13], v[174:177], v[202:205], v[10:13]
	v_mfma_f32_16x16x32_bf16 v[6:9], v[166:169], v[210:213], v[6:9]
	v_mfma_f32_16x16x32_bf16 v[2:5], v[174:177], v[210:213], v[2:5]
	v_mfma_f32_16x16x32_bf16 v[30:33], v[170:173], v[190:193], v[30:33]
	v_mfma_f32_16x16x32_bf16 v[26:29], v[178:181], v[190:193], v[26:29]
	v_mfma_f32_16x16x32_bf16 v[22:25], v[170:173], v[198:201], v[22:25]
	v_mfma_f32_16x16x32_bf16 v[18:21], v[178:181], v[198:201], v[18:21]
	v_mfma_f32_16x16x32_bf16 v[14:17], v[170:173], v[206:209], v[14:17]
	v_mfma_f32_16x16x32_bf16 v[10:13], v[178:181], v[206:209], v[10:13]
	v_mfma_f32_16x16x32_bf16 v[6:9], v[170:173], v[214:217], v[6:9]
	v_mfma_f32_16x16x32_bf16 v[2:5], v[178:181], v[214:217], v[2:5]
	s_setprio 0
	s_barrier
	ds_read_b128 v[150:153], v147
	ds_read_b128 v[154:157], v147 offset:1024
	ds_read_b128 v[158:161], v147 offset:2048
	ds_read_b128 v[162:165], v147 offset:3072
	ds_read_b128 v[166:169], v148
	ds_read_b128 v[170:173], v148 offset:1024
	ds_read_b128 v[174:177], v148 offset:2048
	ds_read_b128 v[178:181], v148 offset:3072
	s_add_u32 s18, s18, 0x40000
	s_addc_u32 s19, s19, 0
	s_mov_b32 m0, s34
	v_lshl_add_u64 v[224:225], s[18:19], 0, v[136:137]
	ds_read_b128 v[186:189], v145 offset:32768
	ds_read_b128 v[190:193], v145 offset:33792
	ds_read_b128 v[194:197], v145 offset:34816
	ds_read_b128 v[198:201], v145 offset:35840
	ds_read_b128 v[202:205], v145 offset:36864
	ds_read_b128 v[206:209], v145 offset:37888
	ds_read_b128 v[210:213], v145 offset:38912
	ds_read_b128 v[214:217], v145 offset:39936
	global_load_lds_dwordx4 v[224:225], off
	v_lshl_add_u64 v[224:225], s[18:19], 0, v[132:133]
	s_mov_b32 m0, s35
	s_nop 0
	global_load_lds_dwordx4 v[224:225], off
	s_waitcnt vmcnt(8)
	s_waitcnt lgkmcnt(0)
	s_barrier
	s_setprio 1
	v_mfma_f32_16x16x32_bf16 v[126:129], v[150:153], v[186:189], v[126:129]
	v_mfma_f32_16x16x32_bf16 v[122:125], v[158:161], v[186:189], v[122:125]
	v_mfma_f32_16x16x32_bf16 v[118:121], v[150:153], v[194:197], v[118:121]
	v_mfma_f32_16x16x32_bf16 v[114:117], v[158:161], v[194:197], v[114:117]
	v_mfma_f32_16x16x32_bf16 v[110:113], v[150:153], v[202:205], v[110:113]
	v_mfma_f32_16x16x32_bf16 v[106:109], v[158:161], v[202:205], v[106:109]
	v_mfma_f32_16x16x32_bf16 v[102:105], v[150:153], v[210:213], v[102:105]
	v_mfma_f32_16x16x32_bf16 v[98:101], v[158:161], v[210:213], v[98:101]
	v_mfma_f32_16x16x32_bf16 v[126:129], v[154:157], v[190:193], v[126:129]
	v_mfma_f32_16x16x32_bf16 v[122:125], v[162:165], v[190:193], v[122:125]
	v_mfma_f32_16x16x32_bf16 v[118:121], v[154:157], v[198:201], v[118:121]
	v_mfma_f32_16x16x32_bf16 v[114:117], v[162:165], v[198:201], v[114:117]
	v_mfma_f32_16x16x32_bf16 v[110:113], v[154:157], v[206:209], v[110:113]
	v_mfma_f32_16x16x32_bf16 v[106:109], v[162:165], v[206:209], v[106:109]
	v_mfma_f32_16x16x32_bf16 v[102:105], v[154:157], v[214:217], v[102:105]
	v_mfma_f32_16x16x32_bf16 v[98:101], v[162:165], v[214:217], v[98:101]
	v_mfma_f32_16x16x32_bf16 v[62:65], v[166:169], v[186:189], v[62:65]
	v_mfma_f32_16x16x32_bf16 v[58:61], v[174:177], v[186:189], v[58:61]
	v_mfma_f32_16x16x32_bf16 v[54:57], v[166:169], v[194:197], v[54:57]
	v_mfma_f32_16x16x32_bf16 v[50:53], v[174:177], v[194:197], v[50:53]
	v_mfma_f32_16x16x32_bf16 v[46:49], v[166:169], v[202:205], v[46:49]
	v_mfma_f32_16x16x32_bf16 v[42:45], v[174:177], v[202:205], v[42:45]
	v_mfma_f32_16x16x32_bf16 v[38:41], v[166:169], v[210:213], v[38:41]
	v_mfma_f32_16x16x32_bf16 v[34:37], v[174:177], v[210:213], v[34:37]
	v_mfma_f32_16x16x32_bf16 v[62:65], v[170:173], v[190:193], v[62:65]
	v_mfma_f32_16x16x32_bf16 v[58:61], v[178:181], v[190:193], v[58:61]
	v_mfma_f32_16x16x32_bf16 v[54:57], v[170:173], v[198:201], v[54:57]
	v_mfma_f32_16x16x32_bf16 v[50:53], v[178:181], v[198:201], v[50:53]
	v_mfma_f32_16x16x32_bf16 v[46:49], v[170:173], v[206:209], v[46:49]
	v_mfma_f32_16x16x32_bf16 v[42:45], v[178:181], v[206:209], v[42:45]
	v_mfma_f32_16x16x32_bf16 v[38:41], v[170:173], v[214:217], v[38:41]
	v_mfma_f32_16x16x32_bf16 v[34:37], v[178:181], v[214:217], v[34:37]
	s_setprio 0
	s_barrier
; #define PG8_STAGE(bufoff, gbase, voff) do { _Pragma("unroll") for (int _i = 0; _i < 2; ++_i) \
;         __builtin_amdgcn_global_load_lds((const unsigned*)((const char*)(gbase) + (voff)[_i]), (LAS unsigned*)(lds + (bufoff) + ldsw + _i * 8192), 16, 0, 0); } while (0)
; #define PG8_LDA(dst, b, h) do { _Pragma("unroll") for (int m = 0; m < 4; ++m) _Pragma("unroll") for (int k = 0; k < 2; ++k) dst[m][k] = *(const LAS bf16x8*)(lds + PG8_SA(b, h) + aoff + m * 2048 + k * 1024); } while (0)
; #define PG8_MMA(ai, bj, At, Bt) do { __builtin_amdgcn_s_setprio(1); _Pragma("unroll") for (int m = 0; m < 4; ++m) _Pragma("unroll") for (int n = 0; n < 2; ++n) _Pragma("unroll") for (int k = 0; k < 2; ++k) \
;         acc[ai][bj][m][n] = __builtin_amdgcn_mfma_f32_16x16x32_bf16(Bt[n][k], At[m][k], acc[ai][bj][m][n], 0, 0, 0); __builtin_amdgcn_s_setprio(0); } while (0)
; #define PG8_WAIT_V(n) asm volatile("s_waitcnt vmcnt(" #n ")" ::: "memory")
; #define PG8_WAIT_L(n) asm volatile("s_waitcnt lgkmcnt(" #n ")" ::: "memory")
; #define PG8_BAR __builtin_amdgcn_s_barrier()
; #define PG8_SCHED __builtin_amdgcn_sched_barrier(0)
; template <class Epi, class Sched>
; DI void gemm_phase(LAS unsigned char* lds, const Gemm g, const Sched& S, const Epi& E) {
;     ...
;             PG8_LDA(At, 1, 1); PG8_STAGE(PG8_SB(1, 0), b3, voffB); PG8_STAGE(PG8_SB(1, 1), b3 + hstepB, voffB); PG8_STAGE(PG8_SA(1, 0), a3, voffA);
;             PG8_WAIT_V(8); PG8_WAIT_L(0); PG8_BAR; PG8_MMA(1, 0, At, B0); PG8_MMA(1, 1, At, B1); PG8_BAR; PG8_SCHED;
;         }
;         if (wr == 0) PG8_BAR;
	s_mov_b32 m0, s48
	v_lshl_add_u64 v[182:183], v[182:183], 0, s[10:11]
	s_add_u32 s16, s16, 0x80080
	ds_read_b128 v[186:189], v145 offset:49152
	ds_read_b128 v[190:193], v145 offset:50176
	ds_read_b128 v[194:197], v145 offset:51200
	ds_read_b128 v[198:201], v145 offset:52224
	ds_read_b128 v[202:205], v145 offset:53248
	ds_read_b128 v[206:209], v145 offset:54272
	ds_read_b128 v[210:213], v145 offset:55296
	ds_read_b128 v[214:217], v145 offset:56320
	global_load_lds_dwordx4 v[182:183], off
	v_lshl_add_u64 v[182:183], v[218:219], 0, s[10:11]
	s_mov_b32 m0, s49
	s_addc_u32 s17, s17, 0
	global_load_lds_dwordx4 v[182:183], off
	v_lshl_add_u64 v[182:183], s[16:17], 0, v[134:135]
	s_mov_b32 m0, s50
	s_nop 0
	global_load_lds_dwordx4 v[182:183], off
	v_lshl_add_u64 v[182:183], s[16:17], 0, v[130:131]
	s_mov_b32 m0, s51
	s_nop 0
	global_load_lds_dwordx4 v[182:183], off
	v_lshl_add_u64 v[182:183], v[220:221], 0, s[10:11]
	s_mov_b32 m0, s37
	s_nop 0
	global_load_lds_dwordx4 v[182:183], off
	v_lshl_add_u64 v[182:183], v[222:223], 0, s[10:11]
	s_mov_b32 m0, s38
	s_nop 0
	global_load_lds_dwordx4 v[182:183], off
	s_waitcnt vmcnt(8)
	s_waitcnt lgkmcnt(0)
	s_barrier
	s_setprio 1
	v_mfma_f32_16x16x32_bf16 v[94:97], v[150:153], v[186:189], v[94:97]
	v_mfma_f32_16x16x32_bf16 v[90:93], v[158:161], v[186:189], v[90:93]
	v_mfma_f32_16x16x32_bf16 v[86:89], v[150:153], v[194:197], v[86:89]
	v_mfma_f32_16x16x32_bf16 v[82:85], v[158:161], v[194:197], v[82:85]
	v_mfma_f32_16x16x32_bf16 v[78:81], v[150:153], v[202:205], v[78:81]
	v_mfma_f32_16x16x32_bf16 v[74:77], v[158:161], v[202:205], v[74:77]
	v_mfma_f32_16x16x32_bf16 v[70:73], v[150:153], v[210:213], v[70:73]
	v_mfma_f32_16x16x32_bf16 v[66:69], v[158:161], v[210:213], v[66:69]
	v_mfma_f32_16x16x32_bf16 v[94:97], v[154:157], v[190:193], v[94:97]
	v_mfma_f32_16x16x32_bf16 v[90:93], v[162:165], v[190:193], v[90:93]
	v_mfma_f32_16x16x32_bf16 v[86:89], v[154:157], v[198:201], v[86:89]
	v_mfma_f32_16x16x32_bf16 v[82:85], v[162:165], v[198:201], v[82:85]
	v_mfma_f32_16x16x32_bf16 v[78:81], v[154:157], v[206:209], v[78:81]
	v_mfma_f32_16x16x32_bf16 v[74:77], v[162:165], v[206:209], v[74:77]
	v_mfma_f32_16x16x32_bf16 v[70:73], v[154:157], v[214:217], v[70:73]
	v_mfma_f32_16x16x32_bf16 v[66:69], v[162:165], v[214:217], v[66:69]
	v_mfma_f32_16x16x32_bf16 v[30:33], v[166:169], v[186:189], v[30:33]
	v_mfma_f32_16x16x32_bf16 v[26:29], v[174:177], v[186:189], v[26:29]
	v_mfma_f32_16x16x32_bf16 v[22:25], v[166:169], v[194:197], v[22:25]
	v_mfma_f32_16x16x32_bf16 v[18:21], v[174:177], v[194:197], v[18:21]
	v_mfma_f32_16x16x32_bf16 v[14:17], v[166:169], v[202:205], v[14:17]
	v_mfma_f32_16x16x32_bf16 v[10:13], v[174:177], v[202:205], v[10:13]
	v_mfma_f32_16x16x32_bf16 v[6:9], v[166:169], v[210:213], v[6:9]
	v_mfma_f32_16x16x32_bf16 v[2:5], v[174:177], v[210:213], v[2:5]
	v_mfma_f32_16x16x32_bf16 v[30:33], v[170:173], v[190:193], v[30:33]
	v_mfma_f32_16x16x32_bf16 v[26:29], v[178:181], v[190:193], v[26:29]
	v_mfma_f32_16x16x32_bf16 v[22:25], v[170:173], v[198:201], v[22:25]
	v_mfma_f32_16x16x32_bf16 v[18:21], v[178:181], v[198:201], v[18:21]
	v_mfma_f32_16x16x32_bf16 v[14:17], v[170:173], v[206:209], v[14:17]
	v_mfma_f32_16x16x32_bf16 v[10:13], v[178:181], v[206:209], v[10:13]
	v_mfma_f32_16x16x32_bf16 v[6:9], v[170:173], v[214:217], v[6:9]
	v_mfma_f32_16x16x32_bf16 v[2:5], v[178:181], v[214:217], v[2:5]
	s_setprio 0
	s_barrier
	s_add_i32 s41, s41, 2
	s_add_u32 s12, s12, 0x100
	s_addc_u32 s13, s13, 0
	s_cmp_gt_u32 s41, 29
	s_cbranch_scc0 .LBB0_579
	s_cmpk_lt_u32 s21, 0x100
	s_cbranch_scc0 .LBB0_582
	s_barrier

; #define PG8_STAGE(bufoff, gbase, voff) do { _Pragma("unroll") for (int _i = 0; _i < 2; ++_i) \
;         __builtin_amdgcn_global_load_lds((const unsigned*)((const char*)(gbase) + (voff)[_i]), (LAS unsigned*)(lds + (bufoff) + ldsw + _i * 8192), 16, 0, 0); } while (0)
; #define PG8_LDA(dst, b, h) do { _Pragma("unroll") for (int m = 0; m < 4; ++m) _Pragma("unroll") for (int k = 0; k < 2; ++k) dst[m][k] = *(const LAS bf16x8*)(lds + PG8_SA(b, h) + aoff + m * 2048 + k * 1024); } while (0)
; #define PG8_LDB(dst, b, h) do { _Pragma("unroll") for (int n = 0; n < 2; ++n) _Pragma("unroll") for (int k = 0; k < 2; ++k) dst[n][k] = *(const LAS bf16x8*)(lds + PG8_SB(b, h) + boff + n * 2048 + k * 1024); } while (0)
; #define PG8_MMA(ai, bj, At, Bt) do { __builtin_amdgcn_s_setprio(1); _Pragma("unroll") for (int m = 0; m < 4; ++m) _Pragma("unroll") for (int n = 0; n < 2; ++n) _Pragma("unroll") for (int k = 0; k < 2; ++k) \
;         acc[ai][bj][m][n] = __builtin_amdgcn_mfma_f32_16x16x32_bf16(Bt[n][k], At[m][k], acc[ai][bj][m][n], 0, 0, 0); __builtin_amdgcn_s_setprio(0); } while (0)
; #define PG8_WAIT_V(n) asm volatile("s_waitcnt vmcnt(" #n ")" ::: "memory")
; #define PG8_WAIT_L(n) asm volatile("s_waitcnt lgkmcnt(" #n ")" ::: "memory")
; #define PG8_BAR __builtin_amdgcn_s_barrier()
; #define PG8_SCHED __builtin_amdgcn_sched_barrier(0)
; template <class Epi, class Sched>
; DI void gemm_phase(LAS unsigned char* lds, const Gemm g, const Sched& S, const Epi& E) {
;     ...
;             const bool last = (t == nt - 2);
;             const char* a1 = cA + (size_t)(t + 1) * kstep;
;             const char* a2 = last ? nA : cA + (size_t)(t + 2) * kstep; const char* b2 = last ? nB : cB + (size_t)(t + 2) * kstep;
;             const char* a3 = a2 + kstep; const char* b3 = b2 + kstep;
;             PG8_LDB(B0, 0, 0); PG8_LDB(B1, 0, 1); PG8_SCHED; PG8_LDA(At, 0, 0); PG8_STAGE(PG8_SA(1, 1), a1 + hstepA, voffA);
;             PG8_WAIT_V(8); PG8_WAIT_L(0); PG8_BAR; PG8_MMA(0, 0, At, B0); PG8_MMA(0, 1, At, B1); PG8_BAR; PG8_SCHED;
;             PG8_LDA(At, 0, 1); PG8_STAGE(PG8_SB(0, 0), b2, voffB); PG8_STAGE(PG8_SB(0, 1), b2 + hstepB, voffB); PG8_STAGE(PG8_SA(0, 0), a2, voffA);
;             PG8_WAIT_V(8); PG8_WAIT_L(0); PG8_BAR; PG8_MMA(1, 0, At, B0); PG8_MMA(1, 1, At, B1); PG8_BAR; PG8_SCHED;
.LBB0_972:
	v_add_u32_e32 v158, s64, v162
	v_add_u32_e32 v180, s65, v162
	ds_read_b128 v[146:149], v158
	ds_read_b128 v[150:153], v158 offset:1024
	ds_read_b128 v[154:157], v158 offset:2048
	ds_read_b128 v[158:161], v158 offset:3072
	ds_read_b128 v[168:171], v180
	ds_read_b128 v[172:175], v180 offset:1024
	ds_read_b128 v[176:179], v180 offset:2048
	ds_read_b128 v[180:183], v180 offset:3072
	s_add_u32 s46, s44, 0xfffe0080
	s_addc_u32 s47, s45, -1
	s_cmp_eq_u32 s72, 4
	s_cselect_b32 s49, s39, s47
	s_cselect_b32 s48, s68, s46
	s_cselect_b32 s47, s37, s71
	s_cselect_b32 s46, s69, s70
	v_lshl_add_u64 v[218:219], s[44:45], 0, v[138:139]
	s_add_i32 m0, s53, 0xc000
	ds_read_b128 v[186:189], v167
	ds_read_b128 v[190:193], v167 offset:1024
	ds_read_b128 v[194:197], v167 offset:2048
	ds_read_b128 v[198:201], v167 offset:3072
	ds_read_b128 v[202:205], v167 offset:4096
	ds_read_b128 v[206:209], v167 offset:5120
	ds_read_b128 v[210:213], v167 offset:6144
	ds_read_b128 v[214:217], v167 offset:7168
	global_load_lds_dwordx4 v[218:219], off
	v_lshl_add_u64 v[218:219], s[44:45], 0, v[140:141]
	s_add_i32 m0, s53, 0xe000
	s_nop 0
	global_load_lds_dwordx4 v[218:219], off
	s_waitcnt vmcnt(8)
	s_waitcnt lgkmcnt(0)
	s_barrier
	s_setprio 1
	v_mfma_f32_16x16x32_bf16 v[126:129], v[146:149], v[186:189], v[126:129]
	v_mfma_f32_16x16x32_bf16 v[122:125], v[154:157], v[186:189], v[122:125]
	v_mfma_f32_16x16x32_bf16 v[118:121], v[146:149], v[194:197], v[118:121]
	v_mfma_f32_16x16x32_bf16 v[114:117], v[154:157], v[194:197], v[114:117]
	v_mfma_f32_16x16x32_bf16 v[110:113], v[146:149], v[202:205], v[110:113]
	v_mfma_f32_16x16x32_bf16 v[106:109], v[154:157], v[202:205], v[106:109]
	v_mfma_f32_16x16x32_bf16 v[102:105], v[146:149], v[210:213], v[102:105]
	v_mfma_f32_16x16x32_bf16 v[98:101], v[154:157], v[210:213], v[98:101]
	v_mfma_f32_16x16x32_bf16 v[126:129], v[150:153], v[190:193], v[126:129]
	v_mfma_f32_16x16x32_bf16 v[122:125], v[158:161], v[190:193], v[122:125]
	v_mfma_f32_16x16x32_bf16 v[118:121], v[150:153], v[198:201], v[118:121]
	v_mfma_f32_16x16x32_bf16 v[114:117], v[158:161], v[198:201], v[114:117]
	v_mfma_f32_16x16x32_bf16 v[110:113], v[150:153], v[206:209], v[110:113]
	v_mfma_f32_16x16x32_bf16 v[106:109], v[158:161], v[206:209], v[106:109]
	v_mfma_f32_16x16x32_bf16 v[102:105], v[150:153], v[214:217], v[102:105]
	v_mfma_f32_16x16x32_bf16 v[98:101], v[158:161], v[214:217], v[98:101]
	v_mfma_f32_16x16x32_bf16 v[94:97], v[168:171], v[186:189], v[94:97]
	v_mfma_f32_16x16x32_bf16 v[90:93], v[176:179], v[186:189], v[90:93]
	v_mfma_f32_16x16x32_bf16 v[86:89], v[168:171], v[194:197], v[86:89]
	v_mfma_f32_16x16x32_bf16 v[82:85], v[176:179], v[194:197], v[82:85]
	v_mfma_f32_16x16x32_bf16 v[78:81], v[168:171], v[202:205], v[78:81]
	v_mfma_f32_16x16x32_bf16 v[74:77], v[176:179], v[202:205], v[74:77]
	v_mfma_f32_16x16x32_bf16 v[70:73], v[168:171], v[210:213], v[70:73]
	v_mfma_f32_16x16x32_bf16 v[66:69], v[176:179], v[210:213], v[66:69]
	v_mfma_f32_16x16x32_bf16 v[94:97], v[172:175], v[190:193], v[94:97]
	v_mfma_f32_16x16x32_bf16 v[90:93], v[180:183], v[190:193], v[90:93]
	v_mfma_f32_16x16x32_bf16 v[86:89], v[172:175], v[198:201], v[86:89]
	v_mfma_f32_16x16x32_bf16 v[82:85], v[180:183], v[198:201], v[82:85]
	v_mfma_f32_16x16x32_bf16 v[78:81], v[172:175], v[206:209], v[78:81]
	v_mfma_f32_16x16x32_bf16 v[74:77], v[180:183], v[206:209], v[74:77]
	v_mfma_f32_16x16x32_bf16 v[70:73], v[172:175], v[214:217], v[70:73]
	v_mfma_f32_16x16x32_bf16 v[66:69], v[180:183], v[214:217], v[66:69]
	s_setprio 0
	s_barrier
	s_add_i32 s73, s64, s52
	v_lshl_add_u64 v[218:219], s[46:47], 0, v[132:133]
	s_mov_b32 m0, s73
	ds_read_b128 v[186:189], v167 offset:16384
	ds_read_b128 v[190:193], v167 offset:17408
	ds_read_b128 v[194:197], v167 offset:18432
	ds_read_b128 v[198:201], v167 offset:19456
	ds_read_b128 v[202:205], v167 offset:20480
	ds_read_b128 v[206:209], v167 offset:21504
	ds_read_b128 v[210:213], v167 offset:22528
	ds_read_b128 v[214:217], v167 offset:23552
	global_load_lds_dwordx4 v[218:219], off
	s_add_i32 m0, s73, 0x2000
	s_add_u32 s74, s46, 0x20000
	v_lshl_add_u64 v[220:221], s[46:47], 0, v[136:137]
	s_addc_u32 s75, s47, 0
	s_add_i32 s73, s65, s52
	global_load_lds_dwordx4 v[220:221], off
	v_lshl_add_u64 v[222:223], s[74:75], 0, v[132:133]
	s_mov_b32 m0, s73
	v_lshl_add_u64 v[224:225], s[48:49], 0, v[134:135]
	global_load_lds_dwordx4 v[222:223], off
	v_lshl_add_u64 v[222:223], s[74:75], 0, v[136:137]
	s_add_i32 m0, s73, 0x2000
	s_nop 0
	global_load_lds_dwordx4 v[222:223], off
	v_lshl_add_u64 v[222:223], s[48:49], 0, v[130:131]
	s_mov_b32 m0, s53
	s_nop 0
	global_load_lds_dwordx4 v[222:223], off
	s_mov_b32 m0, s54
	s_nop 0
	global_load_lds_dwordx4 v[224:225], off
	s_waitcnt vmcnt(8)
	s_waitcnt lgkmcnt(0)
	s_barrier
; #define PG8_STAGE(bufoff, gbase, voff) do { _Pragma("unroll") for (int _i = 0; _i < 2; ++_i) \
;         __builtin_amdgcn_global_load_lds((const unsigned*)((const char*)(gbase) + (voff)[_i]), (LAS unsigned*)(lds + (bufoff) + ldsw + _i * 8192), 16, 0, 0); } while (0)
; #define PG8_LDA(dst, b, h) do { _Pragma("unroll") for (int m = 0; m < 4; ++m) _Pragma("unroll") for (int k = 0; k < 2; ++k) dst[m][k] = *(const LAS bf16x8*)(lds + PG8_SA(b, h) + aoff + m * 2048 + k * 1024); } while (0)
; #define PG8_LDB(dst, b, h) do { _Pragma("unroll") for (int n = 0; n < 2; ++n) _Pragma("unroll") for (int k = 0; k < 2; ++k) dst[n][k] = *(const LAS bf16x8*)(lds + PG8_SB(b, h) + boff + n * 2048 + k * 1024); } while (0)
; #define PG8_MMA(ai, bj, At, Bt) do { __builtin_amdgcn_s_setprio(1); _Pragma("unroll") for (int m = 0; m < 4; ++m) _Pragma("unroll") for (int n = 0; n < 2; ++n) _Pragma("unroll") for (int k = 0; k < 2; ++k) \
;         acc[ai][bj][m][n] = __builtin_amdgcn_mfma_f32_16x16x32_bf16(Bt[n][k], At[m][k], acc[ai][bj][m][n], 0, 0, 0); __builtin_amdgcn_s_setprio(0); } while (0)
; #define PG8_WAIT_V(n) asm volatile("s_waitcnt vmcnt(" #n ")" ::: "memory")
; #define PG8_WAIT_L(n) asm volatile("s_waitcnt lgkmcnt(" #n ")" ::: "memory")
; #define PG8_BAR __builtin_amdgcn_s_barrier()
; #define PG8_SCHED __builtin_amdgcn_sched_barrier(0)
; template <class Epi, class Sched>
; DI void gemm_phase(LAS unsigned char* lds, const Gemm g, const Sched& S, const Epi& E) {
;     ...
;             PG8_WAIT_V(8); PG8_WAIT_L(0); PG8_BAR; PG8_MMA(1, 0, At, B0); PG8_MMA(1, 1, At, B1); PG8_BAR; PG8_SCHED;
;             PG8_LDB(B0, 1, 0); PG8_LDB(B1, 1, 1); PG8_SCHED; PG8_LDA(At, 1, 0); PG8_STAGE(PG8_SA(0, 1), a2 + hstepA, voffA);
;             PG8_WAIT_V(8); PG8_WAIT_L(0); PG8_BAR; PG8_MMA(0, 0, At, B0); PG8_MMA(0, 1, At, B1); PG8_BAR; PG8_SCHED;
	s_setprio 1
	v_mfma_f32_16x16x32_bf16 v[62:65], v[146:149], v[186:189], v[62:65]
	v_mfma_f32_16x16x32_bf16 v[58:61], v[154:157], v[186:189], v[58:61]
	v_mfma_f32_16x16x32_bf16 v[54:57], v[146:149], v[194:197], v[54:57]
	v_mfma_f32_16x16x32_bf16 v[50:53], v[154:157], v[194:197], v[50:53]
	v_mfma_f32_16x16x32_bf16 v[46:49], v[146:149], v[202:205], v[46:49]
	v_mfma_f32_16x16x32_bf16 v[42:45], v[154:157], v[202:205], v[42:45]
	v_mfma_f32_16x16x32_bf16 v[38:41], v[146:149], v[210:213], v[38:41]
	v_mfma_f32_16x16x32_bf16 v[34:37], v[154:157], v[210:213], v[34:37]
	v_mfma_f32_16x16x32_bf16 v[62:65], v[150:153], v[190:193], v[62:65]
	v_mfma_f32_16x16x32_bf16 v[58:61], v[158:161], v[190:193], v[58:61]
	v_mfma_f32_16x16x32_bf16 v[54:57], v[150:153], v[198:201], v[54:57]
	v_mfma_f32_16x16x32_bf16 v[50:53], v[158:161], v[198:201], v[50:53]
	v_mfma_f32_16x16x32_bf16 v[46:49], v[150:153], v[206:209], v[46:49]
	v_mfma_f32_16x16x32_bf16 v[42:45], v[158:161], v[206:209], v[42:45]
	v_mfma_f32_16x16x32_bf16 v[38:41], v[150:153], v[214:217], v[38:41]
	v_mfma_f32_16x16x32_bf16 v[34:37], v[158:161], v[214:217], v[34:37]
	v_mfma_f32_16x16x32_bf16 v[30:33], v[168:171], v[186:189], v[30:33]
	v_mfma_f32_16x16x32_bf16 v[26:29], v[176:179], v[186:189], v[26:29]
	v_mfma_f32_16x16x32_bf16 v[22:25], v[168:171], v[194:197], v[22:25]
	v_mfma_f32_16x16x32_bf16 v[18:21], v[176:179], v[194:197], v[18:21]
	v_mfma_f32_16x16x32_bf16 v[14:17], v[168:171], v[202:205], v[14:17]
	v_mfma_f32_16x16x32_bf16 v[10:13], v[176:179], v[202:205], v[10:13]
	v_mfma_f32_16x16x32_bf16 v[6:9], v[168:171], v[210:213], v[6:9]
	v_mfma_f32_16x16x32_bf16 v[2:5], v[176:179], v[210:213], v[2:5]
	v_mfma_f32_16x16x32_bf16 v[30:33], v[172:175], v[190:193], v[30:33]
	v_mfma_f32_16x16x32_bf16 v[26:29], v[180:183], v[190:193], v[26:29]
	v_mfma_f32_16x16x32_bf16 v[22:25], v[172:175], v[198:201], v[22:25]
	v_mfma_f32_16x16x32_bf16 v[18:21], v[180:183], v[198:201], v[18:21]
	v_mfma_f32_16x16x32_bf16 v[14:17], v[172:175], v[206:209], v[14:17]
	v_mfma_f32_16x16x32_bf16 v[10:13], v[180:183], v[206:209], v[10:13]
	v_mfma_f32_16x16x32_bf16 v[6:9], v[172:175], v[214:217], v[6:9]
	v_mfma_f32_16x16x32_bf16 v[2:5], v[180:183], v[214:217], v[2:5]
	s_setprio 0
	s_barrier
	s_add_i32 s73, 0, 0x18000
	s_add_i32 s74, 0, 0x1c000
	v_add_u32_e32 v158, s73, v162
	v_add_u32_e32 v180, s74, v162
	ds_read_b128 v[146:149], v158
	ds_read_b128 v[150:153], v158 offset:1024
	ds_read_b128 v[154:157], v158 offset:2048
	ds_read_b128 v[158:161], v158 offset:3072
	ds_read_b128 v[168:171], v180
	ds_read_b128 v[172:175], v180 offset:1024
	ds_read_b128 v[176:179], v180 offset:2048
	ds_read_b128 v[180:183], v180 offset:3072
	s_add_u32 s48, s48, 0x20000
	s_addc_u32 s49, s49, 0
	s_mov_b32 m0, s55
	v_lshl_add_u64 v[226:227], s[48:49], 0, v[130:131]
	ds_read_b128 v[186:189], v167 offset:32768
	ds_read_b128 v[190:193], v167 offset:33792
	ds_read_b128 v[194:197], v167 offset:34816
	ds_read_b128 v[198:201], v167 offset:35840
	ds_read_b128 v[202:205], v167 offset:36864
	ds_read_b128 v[206:209], v167 offset:37888
	ds_read_b128 v[210:213], v167 offset:38912
	ds_read_b128 v[214:217], v167 offset:39936
	global_load_lds_dwordx4 v[226:227], off
	v_lshl_add_u64 v[226:227], s[48:49], 0, v[134:135]
	s_mov_b32 m0, s56
	s_nop 0
	global_load_lds_dwordx4 v[226:227], off
	s_waitcnt vmcnt(8)
	s_waitcnt lgkmcnt(0)
	s_barrier
	s_setprio 1
	v_mfma_f32_16x16x32_bf16 v[126:129], v[146:149], v[186:189], v[126:129]
	v_mfma_f32_16x16x32_bf16 v[122:125], v[154:157], v[186:189], v[122:125]
	v_mfma_f32_16x16x32_bf16 v[118:121], v[146:149], v[194:197], v[118:121]
	v_mfma_f32_16x16x32_bf16 v[114:117], v[154:157], v[194:197], v[114:117]
	v_mfma_f32_16x16x32_bf16 v[110:113], v[146:149], v[202:205], v[110:113]
	v_mfma_f32_16x16x32_bf16 v[106:109], v[154:157], v[202:205], v[106:109]
	v_mfma_f32_16x16x32_bf16 v[102:105], v[146:149], v[210:213], v[102:105]
	v_mfma_f32_16x16x32_bf16 v[98:101], v[154:157], v[210:213], v[98:101]
	v_mfma_f32_16x16x32_bf16 v[126:129], v[150:153], v[190:193], v[126:129]
	v_mfma_f32_16x16x32_bf16 v[122:125], v[158:161], v[190:193], v[122:125]
	v_mfma_f32_16x16x32_bf16 v[118:121], v[150:153], v[198:201], v[118:121]
	v_mfma_f32_16x16x32_bf16 v[114:117], v[158:161], v[198:201], v[114:117]
	v_mfma_f32_16x16x32_bf16 v[110:113], v[150:153], v[206:209], v[110:113]
	v_mfma_f32_16x16x32_bf16 v[106:109], v[158:161], v[206:209], v[106:109]
	v_mfma_f32_16x16x32_bf16 v[102:105], v[150:153], v[214:217], v[102:105]
	v_mfma_f32_16x16x32_bf16 v[98:101], v[158:161], v[214:217], v[98:101]
	v_mfma_f32_16x16x32_bf16 v[94:97], v[168:171], v[186:189], v[94:97]
	v_mfma_f32_16x16x32_bf16 v[90:93], v[176:179], v[186:189], v[90:93]
	v_mfma_f32_16x16x32_bf16 v[86:89], v[168:171], v[194:197], v[86:89]
	v_mfma_f32_16x16x32_bf16 v[82:85], v[176:179], v[194:197], v[82:85]
	v_mfma_f32_16x16x32_bf16 v[78:81], v[168:171], v[202:205], v[78:81]
	v_mfma_f32_16x16x32_bf16 v[74:77], v[176:179], v[202:205], v[74:77]
	v_mfma_f32_16x16x32_bf16 v[70:73], v[168:171], v[210:213], v[70:73]
	v_mfma_f32_16x16x32_bf16 v[66:69], v[176:179], v[210:213], v[66:69]
	v_mfma_f32_16x16x32_bf16 v[94:97], v[172:175], v[190:193], v[94:97]
	v_mfma_f32_16x16x32_bf16 v[90:93], v[180:183], v[190:193], v[90:93]
	v_mfma_f32_16x16x32_bf16 v[86:89], v[172:175], v[198:201], v[86:89]
	v_mfma_f32_16x16x32_bf16 v[82:85], v[180:183], v[198:201], v[82:85]
	v_mfma_f32_16x16x32_bf16 v[78:81], v[172:175], v[206:209], v[78:81]
	v_mfma_f32_16x16x32_bf16 v[74:77], v[180:183], v[206:209], v[74:77]
	v_mfma_f32_16x16x32_bf16 v[70:73], v[172:175], v[214:217], v[70:73]
	v_mfma_f32_16x16x32_bf16 v[66:69], v[180:183], v[214:217], v[66:69]
	s_setprio 0
	s_barrier
; #define PG8_STAGE(bufoff, gbase, voff) do { _Pragma("unroll") for (int _i = 0; _i < 2; ++_i) \
;         __builtin_amdgcn_global_load_lds((const unsigned*)((const char*)(gbase) + (voff)[_i]), (LAS unsigned*)(lds + (bufoff) + ldsw + _i * 8192), 16, 0, 0); } while (0)
; #define PG8_LDA(dst, b, h) do { _Pragma("unroll") for (int m = 0; m < 4; ++m) _Pragma("unroll") for (int k = 0; k < 2; ++k) dst[m][k] = *(const LAS bf16x8*)(lds + PG8_SA(b, h) + aoff + m * 2048 + k * 1024); } while (0)
; #define PG8_MMA(ai, bj, At, Bt) do { __builtin_amdgcn_s_setprio(1); _Pragma("unroll") for (int m = 0; m < 4; ++m) _Pragma("unroll") for (int n = 0; n < 2; ++n) _Pragma("unroll") for (int k = 0; k < 2; ++k) \
;         acc[ai][bj][m][n] = __builtin_amdgcn_mfma_f32_16x16x32_bf16(Bt[n][k], At[m][k], acc[ai][bj][m][n], 0, 0, 0); __builtin_amdgcn_s_setprio(0); } while (0)
; #define PG8_WAIT_V(n) asm volatile("s_waitcnt vmcnt(" #n ")" ::: "memory")
; #define PG8_WAIT_L(n) asm volatile("s_waitcnt lgkmcnt(" #n ")" ::: "memory")
; #define PG8_BAR __builtin_amdgcn_s_barrier()
; #define PG8_SCHED __builtin_amdgcn_sched_barrier(0)
; template <class Epi, class Sched>
; DI void gemm_phase(LAS unsigned char* lds, const Gemm g, const Sched& S, const Epi& E) {
;     ...
;             PG8_LDA(At, 1, 1); PG8_STAGE(PG8_SB(1, 0), b3, voffB); PG8_STAGE(PG8_SB(1, 1), b3 + hstepB, voffB); PG8_STAGE(PG8_SA(1, 0), a3, voffA);
;             PG8_WAIT_V(8); PG8_WAIT_L(0); PG8_BAR; PG8_MMA(1, 0, At, B0); PG8_MMA(1, 1, At, B1); PG8_BAR; PG8_SCHED;
;         }
;         if (wr == 0) PG8_BAR;
	s_add_i32 s48, s73, s52
	v_lshl_add_u64 v[218:219], v[218:219], 0, s[20:21]
	s_mov_b32 m0, s48
	ds_read_b128 v[186:189], v167 offset:49152
	ds_read_b128 v[190:193], v167 offset:50176
	ds_read_b128 v[194:197], v167 offset:51200
	ds_read_b128 v[198:201], v167 offset:52224
	ds_read_b128 v[202:205], v167 offset:53248
	ds_read_b128 v[206:209], v167 offset:54272
	ds_read_b128 v[210:213], v167 offset:55296
	ds_read_b128 v[214:217], v167 offset:56320
	global_load_lds_dwordx4 v[218:219], off
	s_add_i32 m0, s48, 0x2000
	s_add_u32 s46, s46, 0x20080
	v_lshl_add_u64 v[218:219], v[220:221], 0, s[20:21]
	s_addc_u32 s47, s47, 0
	s_add_i32 s48, s74, s52
	global_load_lds_dwordx4 v[218:219], off
	v_lshl_add_u64 v[218:219], s[46:47], 0, v[132:133]
	s_mov_b32 m0, s48
	s_nop 0
	global_load_lds_dwordx4 v[218:219], off
	v_lshl_add_u64 v[218:219], s[46:47], 0, v[136:137]
	s_add_i32 m0, s48, 0x2000
	s_nop 0
	global_load_lds_dwordx4 v[218:219], off
	v_lshl_add_u64 v[218:219], v[222:223], 0, s[20:21]
	s_mov_b32 m0, s61
	s_nop 0
	global_load_lds_dwordx4 v[218:219], off
	v_lshl_add_u64 v[218:219], v[224:225], 0, s[20:21]
	s_mov_b32 m0, s62
	s_nop 0
	global_load_lds_dwordx4 v[218:219], off
	s_waitcnt vmcnt(8)
	s_waitcnt lgkmcnt(0)
	s_barrier
	s_setprio 1
	v_mfma_f32_16x16x32_bf16 v[62:65], v[146:149], v[186:189], v[62:65]
	v_mfma_f32_16x16x32_bf16 v[58:61], v[154:157], v[186:189], v[58:61]
	v_mfma_f32_16x16x32_bf16 v[54:57], v[146:149], v[194:197], v[54:57]
	v_mfma_f32_16x16x32_bf16 v[50:53], v[154:157], v[194:197], v[50:53]
	v_mfma_f32_16x16x32_bf16 v[46:49], v[146:149], v[202:205], v[46:49]
	v_mfma_f32_16x16x32_bf16 v[42:45], v[154:157], v[202:205], v[42:45]
	v_mfma_f32_16x16x32_bf16 v[38:41], v[146:149], v[210:213], v[38:41]
	v_mfma_f32_16x16x32_bf16 v[34:37], v[154:157], v[210:213], v[34:37]
	v_mfma_f32_16x16x32_bf16 v[62:65], v[150:153], v[190:193], v[62:65]
	v_mfma_f32_16x16x32_bf16 v[58:61], v[158:161], v[190:193], v[58:61]
	v_mfma_f32_16x16x32_bf16 v[54:57], v[150:153], v[198:201], v[54:57]
	v_mfma_f32_16x16x32_bf16 v[50:53], v[158:161], v[198:201], v[50:53]
	v_mfma_f32_16x16x32_bf16 v[46:49], v[150:153], v[206:209], v[46:49]
	v_mfma_f32_16x16x32_bf16 v[42:45], v[158:161], v[206:209], v[42:45]
	v_mfma_f32_16x16x32_bf16 v[38:41], v[150:153], v[214:217], v[38:41]
	v_mfma_f32_16x16x32_bf16 v[34:37], v[158:161], v[214:217], v[34:37]
	v_mfma_f32_16x16x32_bf16 v[30:33], v[168:171], v[186:189], v[30:33]
	v_mfma_f32_16x16x32_bf16 v[26:29], v[176:179], v[186:189], v[26:29]
	v_mfma_f32_16x16x32_bf16 v[22:25], v[168:171], v[194:197], v[22:25]
	v_mfma_f32_16x16x32_bf16 v[18:21], v[176:179], v[194:197], v[18:21]
	v_mfma_f32_16x16x32_bf16 v[14:17], v[168:171], v[202:205], v[14:17]
	v_mfma_f32_16x16x32_bf16 v[10:13], v[176:179], v[202:205], v[10:13]
	v_mfma_f32_16x16x32_bf16 v[6:9], v[168:171], v[210:213], v[6:9]
	v_mfma_f32_16x16x32_bf16 v[2:5], v[176:179], v[210:213], v[2:5]
	v_mfma_f32_16x16x32_bf16 v[30:33], v[172:175], v[190:193], v[30:33]
	v_mfma_f32_16x16x32_bf16 v[26:29], v[180:183], v[190:193], v[26:29]
	v_mfma_f32_16x16x32_bf16 v[22:25], v[172:175], v[198:201], v[22:25]
	v_mfma_f32_16x16x32_bf16 v[18:21], v[180:183], v[198:201], v[18:21]
	v_mfma_f32_16x16x32_bf16 v[14:17], v[172:175], v[206:209], v[14:17]
	v_mfma_f32_16x16x32_bf16 v[10:13], v[180:183], v[206:209], v[10:13]
	v_mfma_f32_16x16x32_bf16 v[6:9], v[172:175], v[214:217], v[6:9]
	v_mfma_f32_16x16x32_bf16 v[2:5], v[180:183], v[214:217], v[2:5]
	s_setprio 0
	s_barrier
	s_add_i32 s72, s72, 2
	s_add_u32 s44, s44, 0x100
	s_addc_u32 s45, s45, 0
	s_add_u32 s70, s70, 0x100
	s_addc_u32 s71, s71, 0
	s_cmp_gt_u32 s72, 5
	s_cbranch_scc0 .LBB0_972
	s_and_b64 vcc, exec, s[34:35]
	s_cbranch_vccz .LBB0_975
	s_barrier

; #define PG8_STAGE(bufoff, gbase, voff) do { _Pragma("unroll") for (int _i = 0; _i < 2; ++_i) \
;         __builtin_amdgcn_global_load_lds((const unsigned*)((const char*)(gbase) + (voff)[_i]), (LAS unsigned*)(lds + (bufoff) + ldsw + _i * 8192), 16, 0, 0); } while (0)
; #define PG8_LDA(dst, b, h) do { _Pragma("unroll") for (int m = 0; m < 4; ++m) _Pragma("unroll") for (int k = 0; k < 2; ++k) dst[m][k] = *(const LAS bf16x8*)(lds + PG8_SA(b, h) + aoff + m * 2048 + k * 1024); } while (0)
; #define PG8_LDB(dst, b, h) do { _Pragma("unroll") for (int n = 0; n < 2; ++n) _Pragma("unroll") for (int k = 0; k < 2; ++k) dst[n][k] = *(const LAS bf16x8*)(lds + PG8_SB(b, h) + boff + n * 2048 + k * 1024); } while (0)
; #define PG8_MMA(ai, bj, At, Bt) do { __builtin_amdgcn_s_setprio(1); _Pragma("unroll") for (int m = 0; m < 4; ++m) _Pragma("unroll") for (int n = 0; n < 2; ++n) _Pragma("unroll") for (int k = 0; k < 2; ++k) \
;         acc[ai][bj][m][n] = __builtin_amdgcn_mfma_f32_16x16x32_bf16(Bt[n][k], At[m][k], acc[ai][bj][m][n], 0, 0, 0); __builtin_amdgcn_s_setprio(0); } while (0)
; #define PG8_WAIT_V(n) asm volatile("s_waitcnt vmcnt(" #n ")" ::: "memory")
; #define PG8_WAIT_L(n) asm volatile("s_waitcnt lgkmcnt(" #n ")" ::: "memory")
; #define PG8_BAR __builtin_amdgcn_s_barrier()
; #define PG8_SCHED __builtin_amdgcn_sched_barrier(0)
; template <class Epi, class Sched>
; DI void gemm_phase(LAS unsigned char* lds, const Gemm g, const Sched& S, const Epi& E) {
;     ...
;             const bool last = (t == nt - 2);
;             const char* a1 = cA + (size_t)(t + 1) * kstep;
;             const char* a2 = last ? nA : cA + (size_t)(t + 2) * kstep; const char* b2 = last ? nB : cB + (size_t)(t + 2) * kstep;
;             const char* a3 = a2 + kstep; const char* b3 = b2 + kstep;
;             PG8_LDB(B0, 0, 0); PG8_LDB(B1, 0, 1); PG8_SCHED; PG8_LDA(At, 0, 0); PG8_STAGE(PG8_SA(1, 1), a1 + hstepA, voffA);
;             PG8_WAIT_V(8); PG8_WAIT_L(0); PG8_BAR; PG8_MMA(0, 0, At, B0); PG8_MMA(0, 1, At, B1); PG8_BAR; PG8_SCHED;
;             PG8_LDA(At, 0, 1); PG8_STAGE(PG8_SB(0, 0), b2, voffB); PG8_STAGE(PG8_SB(0, 1), b2 + hstepB, voffB); PG8_STAGE(PG8_SA(0, 0), a2, voffA);
;             PG8_WAIT_V(8); PG8_WAIT_L(0); PG8_BAR; PG8_MMA(1, 0, At, B0); PG8_MMA(1, 1, At, B1); PG8_BAR; PG8_SCHED;
.LBB0_1133:
	ds_read_b128 v[146:149], v152
	ds_read_b128 v[156:159], v152 offset:1024
	ds_read_b128 v[160:163], v152 offset:2048
	ds_read_b128 v[164:167], v152 offset:3072
	ds_read_b128 v[168:171], v153
	ds_read_b128 v[172:175], v153 offset:1024
	ds_read_b128 v[176:179], v153 offset:2048
	ds_read_b128 v[180:183], v153 offset:3072
	s_add_u32 s46, s44, 0xfffc0080
	s_addc_u32 s47, s45, -1
	s_cmp_eq_u32 s66, 12
	s_cselect_b32 s49, s35, s47
	s_cselect_b32 s48, s41, s46
	s_cselect_b32 s47, s21, s65
	s_cselect_b32 s46, s63, s64
	v_lshl_add_u64 v[218:219], s[44:45], 0, v[138:139]
	s_add_i32 m0, s43, 0xc000
	ds_read_b128 v[186:189], v154
	ds_read_b128 v[190:193], v154 offset:1024
	ds_read_b128 v[194:197], v154 offset:2048
	ds_read_b128 v[198:201], v154 offset:3072
	ds_read_b128 v[202:205], v154 offset:4096
	ds_read_b128 v[206:209], v154 offset:5120
	ds_read_b128 v[210:213], v154 offset:6144
	ds_read_b128 v[214:217], v154 offset:7168
	global_load_lds_dwordx4 v[218:219], off
	v_lshl_add_u64 v[218:219], s[44:45], 0, v[140:141]
	s_add_i32 m0, s43, 0xe000
	s_nop 0
	global_load_lds_dwordx4 v[218:219], off
	s_waitcnt vmcnt(8)
	s_waitcnt lgkmcnt(0)
	s_barrier
	s_setprio 1
	v_mfma_f32_16x16x32_bf16 v[126:129], v[146:149], v[186:189], v[126:129]
	v_mfma_f32_16x16x32_bf16 v[122:125], v[160:163], v[186:189], v[122:125]
	v_mfma_f32_16x16x32_bf16 v[110:113], v[146:149], v[194:197], v[110:113]
	v_mfma_f32_16x16x32_bf16 v[106:109], v[160:163], v[194:197], v[106:109]
	v_mfma_f32_16x16x32_bf16 v[94:97], v[146:149], v[202:205], v[94:97]
	v_mfma_f32_16x16x32_bf16 v[90:93], v[160:163], v[202:205], v[90:93]
	v_mfma_f32_16x16x32_bf16 v[78:81], v[146:149], v[210:213], v[78:81]
	v_mfma_f32_16x16x32_bf16 v[74:77], v[160:163], v[210:213], v[74:77]
	v_mfma_f32_16x16x32_bf16 v[126:129], v[156:159], v[190:193], v[126:129]
	v_mfma_f32_16x16x32_bf16 v[122:125], v[164:167], v[190:193], v[122:125]
	v_mfma_f32_16x16x32_bf16 v[110:113], v[156:159], v[198:201], v[110:113]
	v_mfma_f32_16x16x32_bf16 v[106:109], v[164:167], v[198:201], v[106:109]
	v_mfma_f32_16x16x32_bf16 v[94:97], v[156:159], v[206:209], v[94:97]
	v_mfma_f32_16x16x32_bf16 v[90:93], v[164:167], v[206:209], v[90:93]
	v_mfma_f32_16x16x32_bf16 v[78:81], v[156:159], v[214:217], v[78:81]
	v_mfma_f32_16x16x32_bf16 v[74:77], v[164:167], v[214:217], v[74:77]
	v_mfma_f32_16x16x32_bf16 v[118:121], v[168:171], v[186:189], v[118:121]
	v_mfma_f32_16x16x32_bf16 v[114:117], v[176:179], v[186:189], v[114:117]
	v_mfma_f32_16x16x32_bf16 v[102:105], v[168:171], v[194:197], v[102:105]
	v_mfma_f32_16x16x32_bf16 v[98:101], v[176:179], v[194:197], v[98:101]
	v_mfma_f32_16x16x32_bf16 v[86:89], v[168:171], v[202:205], v[86:89]
	v_mfma_f32_16x16x32_bf16 v[82:85], v[176:179], v[202:205], v[82:85]
	v_mfma_f32_16x16x32_bf16 v[70:73], v[168:171], v[210:213], v[70:73]
	v_mfma_f32_16x16x32_bf16 v[66:69], v[176:179], v[210:213], v[66:69]
	v_mfma_f32_16x16x32_bf16 v[118:121], v[172:175], v[190:193], v[118:121]
	v_mfma_f32_16x16x32_bf16 v[114:117], v[180:183], v[190:193], v[114:117]
	v_mfma_f32_16x16x32_bf16 v[102:105], v[172:175], v[198:201], v[102:105]
	v_mfma_f32_16x16x32_bf16 v[98:101], v[180:183], v[198:201], v[98:101]
	v_mfma_f32_16x16x32_bf16 v[86:89], v[172:175], v[206:209], v[86:89]
	v_mfma_f32_16x16x32_bf16 v[82:85], v[180:183], v[206:209], v[82:85]
	v_mfma_f32_16x16x32_bf16 v[70:73], v[172:175], v[214:217], v[70:73]
	v_mfma_f32_16x16x32_bf16 v[66:69], v[180:183], v[214:217], v[66:69]
	s_setprio 0
	s_barrier
	s_add_i32 s67, s61, s52
	v_lshl_add_u64 v[218:219], s[46:47], 0, v[132:133]
	s_mov_b32 m0, s67
	ds_read_b128 v[186:189], v154 offset:16384
	ds_read_b128 v[190:193], v154 offset:17408
	ds_read_b128 v[194:197], v154 offset:18432
	ds_read_b128 v[198:201], v154 offset:19456
	ds_read_b128 v[202:205], v154 offset:20480
	ds_read_b128 v[206:209], v154 offset:21504
	ds_read_b128 v[210:213], v154 offset:22528
	ds_read_b128 v[214:217], v154 offset:23552
	global_load_lds_dwordx4 v[218:219], off
	s_add_i32 m0, s67, 0x2000
	s_add_u32 s68, s46, 0x40000
	v_lshl_add_u64 v[220:221], s[46:47], 0, v[136:137]
	s_addc_u32 s69, s47, 0
	s_add_i32 s67, s62, s52
	global_load_lds_dwordx4 v[220:221], off
	v_lshl_add_u64 v[222:223], s[68:69], 0, v[132:133]
	s_mov_b32 m0, s67
	v_lshl_add_u64 v[224:225], s[48:49], 0, v[134:135]
	global_load_lds_dwordx4 v[222:223], off
	v_lshl_add_u64 v[222:223], s[68:69], 0, v[136:137]
	s_add_i32 m0, s67, 0x2000
	s_nop 0
	global_load_lds_dwordx4 v[222:223], off
	v_lshl_add_u64 v[222:223], s[48:49], 0, v[130:131]
	s_mov_b32 m0, s43
	s_nop 0
	global_load_lds_dwordx4 v[222:223], off
	s_mov_b32 m0, s53
	s_nop 0
	global_load_lds_dwordx4 v[224:225], off
	s_waitcnt vmcnt(8)
	s_waitcnt lgkmcnt(0)
	s_barrier
; #define PG8_STAGE(bufoff, gbase, voff) do { _Pragma("unroll") for (int _i = 0; _i < 2; ++_i) \
;         __builtin_amdgcn_global_load_lds((const unsigned*)((const char*)(gbase) + (voff)[_i]), (LAS unsigned*)(lds + (bufoff) + ldsw + _i * 8192), 16, 0, 0); } while (0)
; #define PG8_LDA(dst, b, h) do { _Pragma("unroll") for (int m = 0; m < 4; ++m) _Pragma("unroll") for (int k = 0; k < 2; ++k) dst[m][k] = *(const LAS bf16x8*)(lds + PG8_SA(b, h) + aoff + m * 2048 + k * 1024); } while (0)
; #define PG8_LDB(dst, b, h) do { _Pragma("unroll") for (int n = 0; n < 2; ++n) _Pragma("unroll") for (int k = 0; k < 2; ++k) dst[n][k] = *(const LAS bf16x8*)(lds + PG8_SB(b, h) + boff + n * 2048 + k * 1024); } while (0)
; #define PG8_MMA(ai, bj, At, Bt) do { __builtin_amdgcn_s_setprio(1); _Pragma("unroll") for (int m = 0; m < 4; ++m) _Pragma("unroll") for (int n = 0; n < 2; ++n) _Pragma("unroll") for (int k = 0; k < 2; ++k) \
;         acc[ai][bj][m][n] = __builtin_amdgcn_mfma_f32_16x16x32_bf16(Bt[n][k], At[m][k], acc[ai][bj][m][n], 0, 0, 0); __builtin_amdgcn_s_setprio(0); } while (0)
; #define PG8_WAIT_V(n) asm volatile("s_waitcnt vmcnt(" #n ")" ::: "memory")
; #define PG8_WAIT_L(n) asm volatile("s_waitcnt lgkmcnt(" #n ")" ::: "memory")
; #define PG8_BAR __builtin_amdgcn_s_barrier()
; #define PG8_SCHED __builtin_amdgcn_sched_barrier(0)
; template <class Epi, class Sched>
; DI void gemm_phase(LAS unsigned char* lds, const Gemm g, const Sched& S, const Epi& E) {
;     ...
;             PG8_WAIT_V(8); PG8_WAIT_L(0); PG8_BAR; PG8_MMA(1, 0, At, B0); PG8_MMA(1, 1, At, B1); PG8_BAR; PG8_SCHED;
;             PG8_LDB(B0, 1, 0); PG8_LDB(B1, 1, 1); PG8_SCHED; PG8_LDA(At, 1, 0); PG8_STAGE(PG8_SA(0, 1), a2 + hstepA, voffA);
;             PG8_WAIT_V(8); PG8_WAIT_L(0); PG8_BAR; PG8_MMA(0, 0, At, B0); PG8_MMA(0, 1, At, B1); PG8_BAR; PG8_SCHED;
	s_setprio 1
	v_mfma_f32_16x16x32_bf16 v[62:65], v[146:149], v[186:189], v[62:65]
	v_mfma_f32_16x16x32_bf16 v[58:61], v[160:163], v[186:189], v[58:61]
	v_mfma_f32_16x16x32_bf16 v[46:49], v[146:149], v[194:197], v[46:49]
	v_mfma_f32_16x16x32_bf16 v[42:45], v[160:163], v[194:197], v[42:45]
	v_mfma_f32_16x16x32_bf16 v[30:33], v[146:149], v[202:205], v[30:33]
	v_mfma_f32_16x16x32_bf16 v[26:29], v[160:163], v[202:205], v[26:29]
	v_mfma_f32_16x16x32_bf16 v[14:17], v[146:149], v[210:213], v[14:17]
	v_mfma_f32_16x16x32_bf16 v[10:13], v[160:163], v[210:213], v[10:13]
	v_mfma_f32_16x16x32_bf16 v[62:65], v[156:159], v[190:193], v[62:65]
	v_mfma_f32_16x16x32_bf16 v[58:61], v[164:167], v[190:193], v[58:61]
	v_mfma_f32_16x16x32_bf16 v[46:49], v[156:159], v[198:201], v[46:49]
	v_mfma_f32_16x16x32_bf16 v[42:45], v[164:167], v[198:201], v[42:45]
	v_mfma_f32_16x16x32_bf16 v[30:33], v[156:159], v[206:209], v[30:33]
	v_mfma_f32_16x16x32_bf16 v[26:29], v[164:167], v[206:209], v[26:29]
	v_mfma_f32_16x16x32_bf16 v[14:17], v[156:159], v[214:217], v[14:17]
	v_mfma_f32_16x16x32_bf16 v[10:13], v[164:167], v[214:217], v[10:13]
	v_mfma_f32_16x16x32_bf16 v[54:57], v[168:171], v[186:189], v[54:57]
	v_mfma_f32_16x16x32_bf16 v[50:53], v[176:179], v[186:189], v[50:53]
	v_mfma_f32_16x16x32_bf16 v[38:41], v[168:171], v[194:197], v[38:41]
	v_mfma_f32_16x16x32_bf16 v[34:37], v[176:179], v[194:197], v[34:37]
	v_mfma_f32_16x16x32_bf16 v[22:25], v[168:171], v[202:205], v[22:25]
	v_mfma_f32_16x16x32_bf16 v[18:21], v[176:179], v[202:205], v[18:21]
	v_mfma_f32_16x16x32_bf16 v[6:9], v[168:171], v[210:213], v[6:9]
	v_mfma_f32_16x16x32_bf16 v[2:5], v[176:179], v[210:213], v[2:5]
	v_mfma_f32_16x16x32_bf16 v[54:57], v[172:175], v[190:193], v[54:57]
	v_mfma_f32_16x16x32_bf16 v[50:53], v[180:183], v[190:193], v[50:53]
	v_mfma_f32_16x16x32_bf16 v[38:41], v[172:175], v[198:201], v[38:41]
	v_mfma_f32_16x16x32_bf16 v[34:37], v[180:183], v[198:201], v[34:37]
	v_mfma_f32_16x16x32_bf16 v[22:25], v[172:175], v[206:209], v[22:25]
	v_mfma_f32_16x16x32_bf16 v[18:21], v[180:183], v[206:209], v[18:21]
	v_mfma_f32_16x16x32_bf16 v[6:9], v[172:175], v[214:217], v[6:9]
	v_mfma_f32_16x16x32_bf16 v[2:5], v[180:183], v[214:217], v[2:5]
	s_setprio 0
	s_barrier
	s_add_i32 s67, 0, 0x18000
	s_add_i32 s68, 0, 0x1c000
	v_add_u32_e32 v164, s67, v150
	v_add_u32_e32 v180, s68, v150
	ds_read_b128 v[146:149], v164
	ds_read_b128 v[156:159], v164 offset:1024
	ds_read_b128 v[160:163], v164 offset:2048
	ds_read_b128 v[164:167], v164 offset:3072
	ds_read_b128 v[168:171], v180
	ds_read_b128 v[172:175], v180 offset:1024
	ds_read_b128 v[176:179], v180 offset:2048
	ds_read_b128 v[180:183], v180 offset:3072
	s_add_u32 s48, s48, 0x40000
	s_addc_u32 s49, s49, 0
	s_mov_b32 m0, s54
	v_lshl_add_u64 v[226:227], s[48:49], 0, v[130:131]
	ds_read_b128 v[186:189], v154 offset:32768
	ds_read_b128 v[190:193], v154 offset:33792
	ds_read_b128 v[194:197], v154 offset:34816
	ds_read_b128 v[198:201], v154 offset:35840
	ds_read_b128 v[202:205], v154 offset:36864
	ds_read_b128 v[206:209], v154 offset:37888
	ds_read_b128 v[210:213], v154 offset:38912
	ds_read_b128 v[214:217], v154 offset:39936
	global_load_lds_dwordx4 v[226:227], off
	v_lshl_add_u64 v[226:227], s[48:49], 0, v[134:135]
	s_mov_b32 m0, s55
	s_nop 0
	global_load_lds_dwordx4 v[226:227], off
	s_waitcnt vmcnt(8)
	s_waitcnt lgkmcnt(0)
	s_barrier
	s_setprio 1
	v_mfma_f32_16x16x32_bf16 v[126:129], v[146:149], v[186:189], v[126:129]
	v_mfma_f32_16x16x32_bf16 v[122:125], v[160:163], v[186:189], v[122:125]
	v_mfma_f32_16x16x32_bf16 v[110:113], v[146:149], v[194:197], v[110:113]
	v_mfma_f32_16x16x32_bf16 v[106:109], v[160:163], v[194:197], v[106:109]
	v_mfma_f32_16x16x32_bf16 v[94:97], v[146:149], v[202:205], v[94:97]
	v_mfma_f32_16x16x32_bf16 v[90:93], v[160:163], v[202:205], v[90:93]
	v_mfma_f32_16x16x32_bf16 v[78:81], v[146:149], v[210:213], v[78:81]
	v_mfma_f32_16x16x32_bf16 v[74:77], v[160:163], v[210:213], v[74:77]
	v_mfma_f32_16x16x32_bf16 v[126:129], v[156:159], v[190:193], v[126:129]
	v_mfma_f32_16x16x32_bf16 v[122:125], v[164:167], v[190:193], v[122:125]
	v_mfma_f32_16x16x32_bf16 v[110:113], v[156:159], v[198:201], v[110:113]
	v_mfma_f32_16x16x32_bf16 v[106:109], v[164:167], v[198:201], v[106:109]
	v_mfma_f32_16x16x32_bf16 v[94:97], v[156:159], v[206:209], v[94:97]
	v_mfma_f32_16x16x32_bf16 v[90:93], v[164:167], v[206:209], v[90:93]
	v_mfma_f32_16x16x32_bf16 v[78:81], v[156:159], v[214:217], v[78:81]
	v_mfma_f32_16x16x32_bf16 v[74:77], v[164:167], v[214:217], v[74:77]
	v_mfma_f32_16x16x32_bf16 v[118:121], v[168:171], v[186:189], v[118:121]
	v_mfma_f32_16x16x32_bf16 v[114:117], v[176:179], v[186:189], v[114:117]
	v_mfma_f32_16x16x32_bf16 v[102:105], v[168:171], v[194:197], v[102:105]
	v_mfma_f32_16x16x32_bf16 v[98:101], v[176:179], v[194:197], v[98:101]
	v_mfma_f32_16x16x32_bf16 v[86:89], v[168:171], v[202:205], v[86:89]
	v_mfma_f32_16x16x32_bf16 v[82:85], v[176:179], v[202:205], v[82:85]
	v_mfma_f32_16x16x32_bf16 v[70:73], v[168:171], v[210:213], v[70:73]
	v_mfma_f32_16x16x32_bf16 v[66:69], v[176:179], v[210:213], v[66:69]
	v_mfma_f32_16x16x32_bf16 v[118:121], v[172:175], v[190:193], v[118:121]
	v_mfma_f32_16x16x32_bf16 v[114:117], v[180:183], v[190:193], v[114:117]
	v_mfma_f32_16x16x32_bf16 v[102:105], v[172:175], v[198:201], v[102:105]
	v_mfma_f32_16x16x32_bf16 v[98:101], v[180:183], v[198:201], v[98:101]
	v_mfma_f32_16x16x32_bf16 v[86:89], v[172:175], v[206:209], v[86:89]
	v_mfma_f32_16x16x32_bf16 v[82:85], v[180:183], v[206:209], v[82:85]
	v_mfma_f32_16x16x32_bf16 v[70:73], v[172:175], v[214:217], v[70:73]
	v_mfma_f32_16x16x32_bf16 v[66:69], v[180:183], v[214:217], v[66:69]
	s_setprio 0
	s_barrier
; #define PG8_STAGE(bufoff, gbase, voff) do { _Pragma("unroll") for (int _i = 0; _i < 2; ++_i) \
;         __builtin_amdgcn_global_load_lds((const unsigned*)((const char*)(gbase) + (voff)[_i]), (LAS unsigned*)(lds + (bufoff) + ldsw + _i * 8192), 16, 0, 0); } while (0)
; #define PG8_LDA(dst, b, h) do { _Pragma("unroll") for (int m = 0; m < 4; ++m) _Pragma("unroll") for (int k = 0; k < 2; ++k) dst[m][k] = *(const LAS bf16x8*)(lds + PG8_SA(b, h) + aoff + m * 2048 + k * 1024); } while (0)
; #define PG8_MMA(ai, bj, At, Bt) do { __builtin_amdgcn_s_setprio(1); _Pragma("unroll") for (int m = 0; m < 4; ++m) _Pragma("unroll") for (int n = 0; n < 2; ++n) _Pragma("unroll") for (int k = 0; k < 2; ++k) \
;         acc[ai][bj][m][n] = __builtin_amdgcn_mfma_f32_16x16x32_bf16(Bt[n][k], At[m][k], acc[ai][bj][m][n], 0, 0, 0); __builtin_amdgcn_s_setprio(0); } while (0)
; #define PG8_WAIT_V(n) asm volatile("s_waitcnt vmcnt(" #n ")" ::: "memory")
; #define PG8_WAIT_L(n) asm volatile("s_waitcnt lgkmcnt(" #n ")" ::: "memory")
; #define PG8_BAR __builtin_amdgcn_s_barrier()
; #define PG8_SCHED __builtin_amdgcn_sched_barrier(0)
; template <class Epi, class Sched>
; DI void gemm_phase(LAS unsigned char* lds, const Gemm g, const Sched& S, const Epi& E) {
;     ...
;             PG8_LDA(At, 1, 1); PG8_STAGE(PG8_SB(1, 0), b3, voffB); PG8_STAGE(PG8_SB(1, 1), b3 + hstepB, voffB); PG8_STAGE(PG8_SA(1, 0), a3, voffA);
;             PG8_WAIT_V(8); PG8_WAIT_L(0); PG8_BAR; PG8_MMA(1, 0, At, B0); PG8_MMA(1, 1, At, B1); PG8_BAR; PG8_SCHED;
;         }
;         if (wr == 0) PG8_BAR;
	s_add_i32 s48, s67, s52
	v_lshl_add_u64 v[218:219], v[218:219], 0, s[16:17]
	s_mov_b32 m0, s48
	ds_read_b128 v[186:189], v154 offset:49152
	ds_read_b128 v[190:193], v154 offset:50176
	ds_read_b128 v[194:197], v154 offset:51200
	ds_read_b128 v[198:201], v154 offset:52224
	ds_read_b128 v[202:205], v154 offset:53248
	ds_read_b128 v[206:209], v154 offset:54272
	ds_read_b128 v[210:213], v154 offset:55296
	ds_read_b128 v[214:217], v154 offset:56320
	global_load_lds_dwordx4 v[218:219], off
	s_add_i32 m0, s48, 0x2000
	s_add_u32 s46, s46, 0x40080
	v_lshl_add_u64 v[218:219], v[220:221], 0, s[16:17]
	s_addc_u32 s47, s47, 0
	s_add_i32 s48, s68, s52
	global_load_lds_dwordx4 v[218:219], off
	v_lshl_add_u64 v[218:219], s[46:47], 0, v[132:133]
	s_mov_b32 m0, s48
	s_nop 0
	global_load_lds_dwordx4 v[218:219], off
	v_lshl_add_u64 v[218:219], s[46:47], 0, v[136:137]
	s_add_i32 m0, s48, 0x2000
	s_nop 0
	global_load_lds_dwordx4 v[218:219], off
	v_lshl_add_u64 v[218:219], v[222:223], 0, s[16:17]
	s_mov_b32 m0, s57
	s_nop 0
	global_load_lds_dwordx4 v[218:219], off
	v_lshl_add_u64 v[218:219], v[224:225], 0, s[16:17]
	s_mov_b32 m0, s58
	s_nop 0
	global_load_lds_dwordx4 v[218:219], off
	s_waitcnt vmcnt(8)
	s_waitcnt lgkmcnt(0)
	s_barrier
	s_setprio 1
	v_mfma_f32_16x16x32_bf16 v[62:65], v[146:149], v[186:189], v[62:65]
	v_mfma_f32_16x16x32_bf16 v[58:61], v[160:163], v[186:189], v[58:61]
	v_mfma_f32_16x16x32_bf16 v[46:49], v[146:149], v[194:197], v[46:49]
	v_mfma_f32_16x16x32_bf16 v[42:45], v[160:163], v[194:197], v[42:45]
	v_mfma_f32_16x16x32_bf16 v[30:33], v[146:149], v[202:205], v[30:33]
	v_mfma_f32_16x16x32_bf16 v[26:29], v[160:163], v[202:205], v[26:29]
	v_mfma_f32_16x16x32_bf16 v[14:17], v[146:149], v[210:213], v[14:17]
	v_mfma_f32_16x16x32_bf16 v[10:13], v[160:163], v[210:213], v[10:13]
	v_mfma_f32_16x16x32_bf16 v[62:65], v[156:159], v[190:193], v[62:65]
	v_mfma_f32_16x16x32_bf16 v[58:61], v[164:167], v[190:193], v[58:61]
	v_mfma_f32_16x16x32_bf16 v[46:49], v[156:159], v[198:201], v[46:49]
	v_mfma_f32_16x16x32_bf16 v[42:45], v[164:167], v[198:201], v[42:45]
	v_mfma_f32_16x16x32_bf16 v[30:33], v[156:159], v[206:209], v[30:33]
	v_mfma_f32_16x16x32_bf16 v[26:29], v[164:167], v[206:209], v[26:29]
	v_mfma_f32_16x16x32_bf16 v[14:17], v[156:159], v[214:217], v[14:17]
	v_mfma_f32_16x16x32_bf16 v[10:13], v[164:167], v[214:217], v[10:13]
	v_mfma_f32_16x16x32_bf16 v[54:57], v[168:171], v[186:189], v[54:57]
	v_mfma_f32_16x16x32_bf16 v[50:53], v[176:179], v[186:189], v[50:53]
	v_mfma_f32_16x16x32_bf16 v[38:41], v[168:171], v[194:197], v[38:41]
	v_mfma_f32_16x16x32_bf16 v[34:37], v[176:179], v[194:197], v[34:37]
	v_mfma_f32_16x16x32_bf16 v[22:25], v[168:171], v[202:205], v[22:25]
	v_mfma_f32_16x16x32_bf16 v[18:21], v[176:179], v[202:205], v[18:21]
	v_mfma_f32_16x16x32_bf16 v[6:9], v[168:171], v[210:213], v[6:9]
	v_mfma_f32_16x16x32_bf16 v[2:5], v[176:179], v[210:213], v[2:5]
	v_mfma_f32_16x16x32_bf16 v[54:57], v[172:175], v[190:193], v[54:57]
	v_mfma_f32_16x16x32_bf16 v[50:53], v[180:183], v[190:193], v[50:53]
	v_mfma_f32_16x16x32_bf16 v[38:41], v[172:175], v[198:201], v[38:41]
	v_mfma_f32_16x16x32_bf16 v[34:37], v[180:183], v[198:201], v[34:37]
	v_mfma_f32_16x16x32_bf16 v[22:25], v[172:175], v[206:209], v[22:25]
	v_mfma_f32_16x16x32_bf16 v[18:21], v[180:183], v[206:209], v[18:21]
	v_mfma_f32_16x16x32_bf16 v[6:9], v[172:175], v[214:217], v[6:9]
	v_mfma_f32_16x16x32_bf16 v[2:5], v[180:183], v[214:217], v[2:5]
	s_setprio 0
	s_barrier
	s_add_i32 s66, s66, 2
	s_add_u32 s44, s44, 0x100
	s_addc_u32 s45, s45, 0
	s_add_u32 s64, s64, 0x100
	s_addc_u32 s65, s65, 0
	s_cmp_gt_u32 s66, 13
	s_cbranch_scc0 .LBB0_1133
	s_and_b64 vcc, exec, s[18:19]
	s_cbranch_vccz .LBB0_1136
	s_barrier

; #define PG8_STAGE(bufoff, gbase, voff) do { _Pragma("unroll") for (int _i = 0; _i < 2; ++_i) \
;         __builtin_amdgcn_global_load_lds((const unsigned*)((const char*)(gbase) + (voff)[_i]), (LAS unsigned*)(lds + (bufoff) + ldsw + _i * 8192), 16, 0, 0); } while (0)
; #define PG8_LDA(dst, b, h) do { _Pragma("unroll") for (int m = 0; m < 4; ++m) _Pragma("unroll") for (int k = 0; k < 2; ++k) dst[m][k] = *(const LAS bf16x8*)(lds + PG8_SA(b, h) + aoff + m * 2048 + k * 1024); } while (0)
; #define PG8_LDB(dst, b, h) do { _Pragma("unroll") for (int n = 0; n < 2; ++n) _Pragma("unroll") for (int k = 0; k < 2; ++k) dst[n][k] = *(const LAS bf16x8*)(lds + PG8_SB(b, h) + boff + n * 2048 + k * 1024); } while (0)
; #define PG8_MMA(ai, bj, At, Bt) do { __builtin_amdgcn_s_setprio(1); _Pragma("unroll") for (int m = 0; m < 4; ++m) _Pragma("unroll") for (int n = 0; n < 2; ++n) _Pragma("unroll") for (int k = 0; k < 2; ++k) \
;         acc[ai][bj][m][n] = __builtin_amdgcn_mfma_f32_16x16x32_bf16(Bt[n][k], At[m][k], acc[ai][bj][m][n], 0, 0, 0); __builtin_amdgcn_s_setprio(0); } while (0)
; #define PG8_WAIT_V(n) asm volatile("s_waitcnt vmcnt(" #n ")" ::: "memory")
; #define PG8_WAIT_L(n) asm volatile("s_waitcnt lgkmcnt(" #n ")" ::: "memory")
; #define PG8_BAR __builtin_amdgcn_s_barrier()
; #define PG8_SCHED __builtin_amdgcn_sched_barrier(0)
; template <class Epi, class Sched>
; DI void gemm_phase(LAS unsigned char* lds, const Gemm g, const Sched& S, const Epi& E) {
;     ...
;             const bool last = (t == nt - 2);
;             const char* a1 = cA + (size_t)(t + 1) * kstep;
;             const char* a2 = last ? nA : cA + (size_t)(t + 2) * kstep; const char* b2 = last ? nB : cB + (size_t)(t + 2) * kstep;
;             const char* a3 = a2 + kstep; const char* b3 = b2 + kstep;
;             PG8_LDB(B0, 0, 0); PG8_LDB(B1, 0, 1); PG8_SCHED; PG8_LDA(At, 0, 0); PG8_STAGE(PG8_SA(1, 1), a1 + hstepA, voffA);
;             PG8_WAIT_V(8); PG8_WAIT_L(0); PG8_BAR; PG8_MMA(0, 0, At, B0); PG8_MMA(0, 1, At, B1); PG8_BAR; PG8_SCHED;
;             PG8_LDA(At, 0, 1); PG8_STAGE(PG8_SB(0, 0), b2, voffB); PG8_STAGE(PG8_SB(0, 1), b2 + hstepB, voffB); PG8_STAGE(PG8_SA(0, 0), a2, voffA);
;             PG8_WAIT_V(8); PG8_WAIT_L(0); PG8_BAR; PG8_MMA(1, 0, At, B0); PG8_MMA(1, 1, At, B1); PG8_BAR; PG8_SCHED;
.LBB0_1234:
	ds_read_b128 v[166:169], v160
	ds_read_b128 v[170:173], v160 offset:1024
	ds_read_b128 v[174:177], v160 offset:2048
	ds_read_b128 v[178:181], v160 offset:3072
	ds_read_b128 v[186:189], v161
	ds_read_b128 v[190:193], v161 offset:1024
	ds_read_b128 v[194:197], v161 offset:2048
	ds_read_b128 v[198:201], v161 offset:3072
	s_add_u32 s42, s40, 0xfffc0080
	s_addc_u32 s43, s41, -1
	s_cmp_eq_u32 s65, 12
	s_cselect_b32 s45, s35, s43
	s_cselect_b32 s44, s61, s42
	s_cselect_b32 s43, s21, s64
	s_cselect_b32 s42, s62, s63
	v_lshl_add_u64 v[182:183], s[40:41], 0, v[138:139]
	s_add_i32 m0, s49, 0xc000
	ds_read_b128 v[202:205], v158
	ds_read_b128 v[206:209], v158 offset:1024
	ds_read_b128 v[210:213], v158 offset:2048
	ds_read_b128 v[214:217], v158 offset:3072
	ds_read_b128 v[218:221], v158 offset:4096
	ds_read_b128 v[222:225], v158 offset:5120
	ds_read_b128 v[226:229], v158 offset:6144
	ds_read_b128 v[230:233], v158 offset:7168
	global_load_lds_dwordx4 v[182:183], off
	v_lshl_add_u64 v[182:183], s[40:41], 0, v[140:141]
	s_add_i32 m0, s49, 0xe000
	s_nop 0
	global_load_lds_dwordx4 v[182:183], off
	s_waitcnt vmcnt(8)
	s_waitcnt lgkmcnt(0)
	s_barrier
	s_setprio 1
	v_mfma_f32_16x16x32_bf16 v[126:129], v[166:169], v[202:205], v[126:129]
	v_mfma_f32_16x16x32_bf16 v[118:121], v[174:177], v[202:205], v[118:121]
	v_mfma_f32_16x16x32_bf16 v[110:113], v[166:169], v[210:213], v[110:113]
	v_mfma_f32_16x16x32_bf16 v[102:105], v[174:177], v[210:213], v[102:105]
	v_mfma_f32_16x16x32_bf16 v[94:97], v[166:169], v[218:221], v[94:97]
	v_mfma_f32_16x16x32_bf16 v[86:89], v[174:177], v[218:221], v[86:89]
	v_mfma_f32_16x16x32_bf16 v[78:81], v[166:169], v[226:229], v[78:81]
	v_mfma_f32_16x16x32_bf16 v[70:73], v[174:177], v[226:229], v[70:73]
	v_mfma_f32_16x16x32_bf16 v[126:129], v[170:173], v[206:209], v[126:129]
	v_mfma_f32_16x16x32_bf16 v[118:121], v[178:181], v[206:209], v[118:121]
	v_mfma_f32_16x16x32_bf16 v[110:113], v[170:173], v[214:217], v[110:113]
	v_mfma_f32_16x16x32_bf16 v[102:105], v[178:181], v[214:217], v[102:105]
	v_mfma_f32_16x16x32_bf16 v[94:97], v[170:173], v[222:225], v[94:97]
	v_mfma_f32_16x16x32_bf16 v[86:89], v[178:181], v[222:225], v[86:89]
	v_mfma_f32_16x16x32_bf16 v[78:81], v[170:173], v[230:233], v[78:81]
	v_mfma_f32_16x16x32_bf16 v[70:73], v[178:181], v[230:233], v[70:73]
	v_mfma_f32_16x16x32_bf16 v[122:125], v[186:189], v[202:205], v[122:125]
	v_mfma_f32_16x16x32_bf16 v[114:117], v[194:197], v[202:205], v[114:117]
	v_mfma_f32_16x16x32_bf16 v[106:109], v[186:189], v[210:213], v[106:109]
	v_mfma_f32_16x16x32_bf16 v[98:101], v[194:197], v[210:213], v[98:101]
	v_mfma_f32_16x16x32_bf16 v[90:93], v[186:189], v[218:221], v[90:93]
	v_mfma_f32_16x16x32_bf16 v[82:85], v[194:197], v[218:221], v[82:85]
	v_mfma_f32_16x16x32_bf16 v[74:77], v[186:189], v[226:229], v[74:77]
	v_mfma_f32_16x16x32_bf16 v[66:69], v[194:197], v[226:229], v[66:69]
	v_mfma_f32_16x16x32_bf16 v[122:125], v[190:193], v[206:209], v[122:125]
	v_mfma_f32_16x16x32_bf16 v[114:117], v[198:201], v[206:209], v[114:117]
	v_mfma_f32_16x16x32_bf16 v[106:109], v[190:193], v[214:217], v[106:109]
	v_mfma_f32_16x16x32_bf16 v[98:101], v[198:201], v[214:217], v[98:101]
	v_mfma_f32_16x16x32_bf16 v[90:93], v[190:193], v[222:225], v[90:93]
	v_mfma_f32_16x16x32_bf16 v[82:85], v[198:201], v[222:225], v[82:85]
	v_mfma_f32_16x16x32_bf16 v[74:77], v[190:193], v[230:233], v[74:77]
	v_mfma_f32_16x16x32_bf16 v[66:69], v[198:201], v[230:233], v[66:69]
	s_setprio 0
	s_barrier
	s_add_i32 s66, s57, s46
	v_lshl_add_u64 v[182:183], s[42:43], 0, v[134:135]
	s_mov_b32 m0, s66
	ds_read_b128 v[202:205], v158 offset:16384
	ds_read_b128 v[206:209], v158 offset:17408
	ds_read_b128 v[210:213], v158 offset:18432
	ds_read_b128 v[214:217], v158 offset:19456
	ds_read_b128 v[218:221], v158 offset:20480
	ds_read_b128 v[222:225], v158 offset:21504
	ds_read_b128 v[226:229], v158 offset:22528
	ds_read_b128 v[230:233], v158 offset:23552
	global_load_lds_dwordx4 v[182:183], off
	s_add_i32 m0, s66, 0x2000
	s_add_u32 s66, s42, 0x40000
	v_lshl_add_u64 v[234:235], s[42:43], 0, v[130:131]
	s_addc_u32 s67, s43, 0
	s_add_i32 s68, s58, s46
	global_load_lds_dwordx4 v[234:235], off
	v_lshl_add_u64 v[236:237], s[66:67], 0, v[134:135]
	s_mov_b32 m0, s68
	v_lshl_add_u64 v[238:239], s[44:45], 0, v[132:133]
	global_load_lds_dwordx4 v[236:237], off
	v_lshl_add_u64 v[236:237], s[66:67], 0, v[130:131]
	s_add_i32 m0, s68, 0x2000
	s_nop 0
	global_load_lds_dwordx4 v[236:237], off
	v_lshl_add_u64 v[236:237], s[44:45], 0, v[136:137]
	s_mov_b32 m0, s49
	s_nop 0
	global_load_lds_dwordx4 v[236:237], off
	s_mov_b32 m0, s50
	s_nop 0
	global_load_lds_dwordx4 v[238:239], off
	s_waitcnt vmcnt(8)
	s_waitcnt lgkmcnt(0)
	s_barrier
; #define PG8_STAGE(bufoff, gbase, voff) do { _Pragma("unroll") for (int _i = 0; _i < 2; ++_i) \
;         __builtin_amdgcn_global_load_lds((const unsigned*)((const char*)(gbase) + (voff)[_i]), (LAS unsigned*)(lds + (bufoff) + ldsw + _i * 8192), 16, 0, 0); } while (0)
; #define PG8_LDA(dst, b, h) do { _Pragma("unroll") for (int m = 0; m < 4; ++m) _Pragma("unroll") for (int k = 0; k < 2; ++k) dst[m][k] = *(const LAS bf16x8*)(lds + PG8_SA(b, h) + aoff + m * 2048 + k * 1024); } while (0)
; #define PG8_LDB(dst, b, h) do { _Pragma("unroll") for (int n = 0; n < 2; ++n) _Pragma("unroll") for (int k = 0; k < 2; ++k) dst[n][k] = *(const LAS bf16x8*)(lds + PG8_SB(b, h) + boff + n * 2048 + k * 1024); } while (0)
; #define PG8_MMA(ai, bj, At, Bt) do { __builtin_amdgcn_s_setprio(1); _Pragma("unroll") for (int m = 0; m < 4; ++m) _Pragma("unroll") for (int n = 0; n < 2; ++n) _Pragma("unroll") for (int k = 0; k < 2; ++k) \
;         acc[ai][bj][m][n] = __builtin_amdgcn_mfma_f32_16x16x32_bf16(Bt[n][k], At[m][k], acc[ai][bj][m][n], 0, 0, 0); __builtin_amdgcn_s_setprio(0); } while (0)
; #define PG8_WAIT_V(n) asm volatile("s_waitcnt vmcnt(" #n ")" ::: "memory")
; #define PG8_WAIT_L(n) asm volatile("s_waitcnt lgkmcnt(" #n ")" ::: "memory")
; #define PG8_BAR __builtin_amdgcn_s_barrier()
; #define PG8_SCHED __builtin_amdgcn_sched_barrier(0)
; template <class Epi, class Sched>
; DI void gemm_phase(LAS unsigned char* lds, const Gemm g, const Sched& S, const Epi& E) {
;     ...
;             PG8_WAIT_V(8); PG8_WAIT_L(0); PG8_BAR; PG8_MMA(1, 0, At, B0); PG8_MMA(1, 1, At, B1); PG8_BAR; PG8_SCHED;
;             PG8_LDB(B0, 1, 0); PG8_LDB(B1, 1, 1); PG8_SCHED; PG8_LDA(At, 1, 0); PG8_STAGE(PG8_SA(0, 1), a2 + hstepA, voffA);
;             PG8_WAIT_V(8); PG8_WAIT_L(0); PG8_BAR; PG8_MMA(0, 0, At, B0); PG8_MMA(0, 1, At, B1); PG8_BAR; PG8_SCHED;
	s_setprio 1
	v_mfma_f32_16x16x32_bf16 v[62:65], v[166:169], v[202:205], v[62:65]
	v_mfma_f32_16x16x32_bf16 v[54:57], v[174:177], v[202:205], v[54:57]
	v_mfma_f32_16x16x32_bf16 v[46:49], v[166:169], v[210:213], v[46:49]
	v_mfma_f32_16x16x32_bf16 v[38:41], v[174:177], v[210:213], v[38:41]
	v_mfma_f32_16x16x32_bf16 v[30:33], v[166:169], v[218:221], v[30:33]
	v_mfma_f32_16x16x32_bf16 v[22:25], v[174:177], v[218:221], v[22:25]
	v_mfma_f32_16x16x32_bf16 v[14:17], v[166:169], v[226:229], v[14:17]
	v_mfma_f32_16x16x32_bf16 v[6:9], v[174:177], v[226:229], v[6:9]
	v_mfma_f32_16x16x32_bf16 v[62:65], v[170:173], v[206:209], v[62:65]
	v_mfma_f32_16x16x32_bf16 v[54:57], v[178:181], v[206:209], v[54:57]
	v_mfma_f32_16x16x32_bf16 v[46:49], v[170:173], v[214:217], v[46:49]
	v_mfma_f32_16x16x32_bf16 v[38:41], v[178:181], v[214:217], v[38:41]
	v_mfma_f32_16x16x32_bf16 v[30:33], v[170:173], v[222:225], v[30:33]
	v_mfma_f32_16x16x32_bf16 v[22:25], v[178:181], v[222:225], v[22:25]
	v_mfma_f32_16x16x32_bf16 v[14:17], v[170:173], v[230:233], v[14:17]
	v_mfma_f32_16x16x32_bf16 v[6:9], v[178:181], v[230:233], v[6:9]
	v_mfma_f32_16x16x32_bf16 v[58:61], v[186:189], v[202:205], v[58:61]
	v_mfma_f32_16x16x32_bf16 v[50:53], v[194:197], v[202:205], v[50:53]
	v_mfma_f32_16x16x32_bf16 v[42:45], v[186:189], v[210:213], v[42:45]
	v_mfma_f32_16x16x32_bf16 v[34:37], v[194:197], v[210:213], v[34:37]
	v_mfma_f32_16x16x32_bf16 v[26:29], v[186:189], v[218:221], v[26:29]
	v_mfma_f32_16x16x32_bf16 v[18:21], v[194:197], v[218:221], v[18:21]
	v_mfma_f32_16x16x32_bf16 v[10:13], v[186:189], v[226:229], v[10:13]
	v_mfma_f32_16x16x32_bf16 v[2:5], v[194:197], v[226:229], v[2:5]
	v_mfma_f32_16x16x32_bf16 v[58:61], v[190:193], v[206:209], v[58:61]
	v_mfma_f32_16x16x32_bf16 v[50:53], v[198:201], v[206:209], v[50:53]
	v_mfma_f32_16x16x32_bf16 v[42:45], v[190:193], v[214:217], v[42:45]
	v_mfma_f32_16x16x32_bf16 v[34:37], v[198:201], v[214:217], v[34:37]
	v_mfma_f32_16x16x32_bf16 v[26:29], v[190:193], v[222:225], v[26:29]
	v_mfma_f32_16x16x32_bf16 v[18:21], v[198:201], v[222:225], v[18:21]
	v_mfma_f32_16x16x32_bf16 v[10:13], v[190:193], v[230:233], v[10:13]
	v_mfma_f32_16x16x32_bf16 v[2:5], v[198:201], v[230:233], v[2:5]
	s_setprio 0
	s_barrier
	s_add_i32 s66, 0, 0x18000
	v_add_u32_e32 v165, s66, v156
	s_add_i32 s67, 0, 0x1c000
	ds_read_b128 v[166:169], v165
	ds_read_b128 v[170:173], v165 offset:1024
	ds_read_b128 v[174:177], v165 offset:2048
	ds_read_b128 v[178:181], v165 offset:3072
	v_add_u32_e32 v165, s67, v156
	ds_read_b128 v[186:189], v165
	ds_read_b128 v[190:193], v165 offset:1024
	ds_read_b128 v[194:197], v165 offset:2048
	ds_read_b128 v[198:201], v165 offset:3072
	s_add_u32 s44, s44, 0x40000
	s_addc_u32 s45, s45, 0
	s_mov_b32 m0, s51
	v_lshl_add_u64 v[240:241], s[44:45], 0, v[136:137]
	ds_read_b128 v[202:205], v158 offset:32768
	ds_read_b128 v[206:209], v158 offset:33792
	ds_read_b128 v[210:213], v158 offset:34816
	ds_read_b128 v[214:217], v158 offset:35840
	ds_read_b128 v[218:221], v158 offset:36864
	ds_read_b128 v[222:225], v158 offset:37888
	ds_read_b128 v[226:229], v158 offset:38912
	ds_read_b128 v[230:233], v158 offset:39936
	global_load_lds_dwordx4 v[240:241], off
	v_lshl_add_u64 v[240:241], s[44:45], 0, v[132:133]
	s_mov_b32 m0, s52
	s_nop 0
	global_load_lds_dwordx4 v[240:241], off
	s_waitcnt vmcnt(8)
	s_waitcnt lgkmcnt(0)
	s_barrier
	s_setprio 1
	v_mfma_f32_16x16x32_bf16 v[126:129], v[166:169], v[202:205], v[126:129]
	v_mfma_f32_16x16x32_bf16 v[118:121], v[174:177], v[202:205], v[118:121]
	v_mfma_f32_16x16x32_bf16 v[110:113], v[166:169], v[210:213], v[110:113]
	v_mfma_f32_16x16x32_bf16 v[102:105], v[174:177], v[210:213], v[102:105]
	v_mfma_f32_16x16x32_bf16 v[94:97], v[166:169], v[218:221], v[94:97]
	v_mfma_f32_16x16x32_bf16 v[86:89], v[174:177], v[218:221], v[86:89]
	v_mfma_f32_16x16x32_bf16 v[78:81], v[166:169], v[226:229], v[78:81]
	v_mfma_f32_16x16x32_bf16 v[70:73], v[174:177], v[226:229], v[70:73]
	v_mfma_f32_16x16x32_bf16 v[126:129], v[170:173], v[206:209], v[126:129]
	v_mfma_f32_16x16x32_bf16 v[118:121], v[178:181], v[206:209], v[118:121]
	v_mfma_f32_16x16x32_bf16 v[110:113], v[170:173], v[214:217], v[110:113]
	v_mfma_f32_16x16x32_bf16 v[102:105], v[178:181], v[214:217], v[102:105]
	v_mfma_f32_16x16x32_bf16 v[94:97], v[170:173], v[222:225], v[94:97]
	v_mfma_f32_16x16x32_bf16 v[86:89], v[178:181], v[222:225], v[86:89]
	v_mfma_f32_16x16x32_bf16 v[78:81], v[170:173], v[230:233], v[78:81]
	v_mfma_f32_16x16x32_bf16 v[70:73], v[178:181], v[230:233], v[70:73]
	v_mfma_f32_16x16x32_bf16 v[122:125], v[186:189], v[202:205], v[122:125]
	v_mfma_f32_16x16x32_bf16 v[114:117], v[194:197], v[202:205], v[114:117]
	v_mfma_f32_16x16x32_bf16 v[106:109], v[186:189], v[210:213], v[106:109]
	v_mfma_f32_16x16x32_bf16 v[98:101], v[194:197], v[210:213], v[98:101]
	v_mfma_f32_16x16x32_bf16 v[90:93], v[186:189], v[218:221], v[90:93]
	v_mfma_f32_16x16x32_bf16 v[82:85], v[194:197], v[218:221], v[82:85]
	v_mfma_f32_16x16x32_bf16 v[74:77], v[186:189], v[226:229], v[74:77]
	v_mfma_f32_16x16x32_bf16 v[66:69], v[194:197], v[226:229], v[66:69]
	v_mfma_f32_16x16x32_bf16 v[122:125], v[190:193], v[206:209], v[122:125]
	v_mfma_f32_16x16x32_bf16 v[114:117], v[198:201], v[206:209], v[114:117]
	v_mfma_f32_16x16x32_bf16 v[106:109], v[190:193], v[214:217], v[106:109]
	v_mfma_f32_16x16x32_bf16 v[98:101], v[198:201], v[214:217], v[98:101]
	v_mfma_f32_16x16x32_bf16 v[90:93], v[190:193], v[222:225], v[90:93]
	v_mfma_f32_16x16x32_bf16 v[82:85], v[198:201], v[222:225], v[82:85]
	v_mfma_f32_16x16x32_bf16 v[74:77], v[190:193], v[230:233], v[74:77]
	v_mfma_f32_16x16x32_bf16 v[66:69], v[198:201], v[230:233], v[66:69]
	s_setprio 0
	s_barrier
; #define PG8_STAGE(bufoff, gbase, voff) do { _Pragma("unroll") for (int _i = 0; _i < 2; ++_i) \
;         __builtin_amdgcn_global_load_lds((const unsigned*)((const char*)(gbase) + (voff)[_i]), (LAS unsigned*)(lds + (bufoff) + ldsw + _i * 8192), 16, 0, 0); } while (0)
; #define PG8_LDA(dst, b, h) do { _Pragma("unroll") for (int m = 0; m < 4; ++m) _Pragma("unroll") for (int k = 0; k < 2; ++k) dst[m][k] = *(const LAS bf16x8*)(lds + PG8_SA(b, h) + aoff + m * 2048 + k * 1024); } while (0)
; #define PG8_MMA(ai, bj, At, Bt) do { __builtin_amdgcn_s_setprio(1); _Pragma("unroll") for (int m = 0; m < 4; ++m) _Pragma("unroll") for (int n = 0; n < 2; ++n) _Pragma("unroll") for (int k = 0; k < 2; ++k) \
;         acc[ai][bj][m][n] = __builtin_amdgcn_mfma_f32_16x16x32_bf16(Bt[n][k], At[m][k], acc[ai][bj][m][n], 0, 0, 0); __builtin_amdgcn_s_setprio(0); } while (0)
; #define PG8_WAIT_V(n) asm volatile("s_waitcnt vmcnt(" #n ")" ::: "memory")
; #define PG8_WAIT_L(n) asm volatile("s_waitcnt lgkmcnt(" #n ")" ::: "memory")
; #define PG8_BAR __builtin_amdgcn_s_barrier()
; #define PG8_SCHED __builtin_amdgcn_sched_barrier(0)
; template <class Epi, class Sched>
; DI void gemm_phase(LAS unsigned char* lds, const Gemm g, const Sched& S, const Epi& E) {
;     ...
;             PG8_LDA(At, 1, 1); PG8_STAGE(PG8_SB(1, 0), b3, voffB); PG8_STAGE(PG8_SB(1, 1), b3 + hstepB, voffB); PG8_STAGE(PG8_SA(1, 0), a3, voffA);
;             PG8_WAIT_V(8); PG8_WAIT_L(0); PG8_BAR; PG8_MMA(1, 0, At, B0); PG8_MMA(1, 1, At, B1); PG8_BAR; PG8_SCHED;
;         }
;         if (wr == 0) PG8_BAR;
	s_add_i32 s44, s66, s46
	v_lshl_add_u64 v[182:183], v[182:183], 0, s[16:17]
	s_mov_b32 m0, s44
	ds_read_b128 v[202:205], v158 offset:49152
	ds_read_b128 v[206:209], v158 offset:50176
	ds_read_b128 v[210:213], v158 offset:51200
	ds_read_b128 v[214:217], v158 offset:52224
	ds_read_b128 v[218:221], v158 offset:53248
	ds_read_b128 v[222:225], v158 offset:54272
	ds_read_b128 v[226:229], v158 offset:55296
	ds_read_b128 v[230:233], v158 offset:56320
	global_load_lds_dwordx4 v[182:183], off
	s_add_i32 m0, s44, 0x2000
	s_add_u32 s42, s42, 0x40080
	v_lshl_add_u64 v[182:183], v[234:235], 0, s[16:17]
	s_addc_u32 s43, s43, 0
	s_add_i32 s44, s67, s46
	global_load_lds_dwordx4 v[182:183], off
	v_lshl_add_u64 v[182:183], s[42:43], 0, v[134:135]
	s_mov_b32 m0, s44
	s_nop 0
	global_load_lds_dwordx4 v[182:183], off
	v_lshl_add_u64 v[182:183], s[42:43], 0, v[130:131]
	s_add_i32 m0, s44, 0x2000
	s_nop 0
	global_load_lds_dwordx4 v[182:183], off
	v_lshl_add_u64 v[182:183], v[236:237], 0, s[16:17]
	s_mov_b32 m0, s54
	s_nop 0
	global_load_lds_dwordx4 v[182:183], off
	v_lshl_add_u64 v[182:183], v[238:239], 0, s[16:17]
	s_mov_b32 m0, s55
	s_nop 0
	global_load_lds_dwordx4 v[182:183], off
	s_waitcnt vmcnt(8)
	s_waitcnt lgkmcnt(0)
	s_barrier
	s_setprio 1
	v_mfma_f32_16x16x32_bf16 v[62:65], v[166:169], v[202:205], v[62:65]
	v_mfma_f32_16x16x32_bf16 v[54:57], v[174:177], v[202:205], v[54:57]
	v_mfma_f32_16x16x32_bf16 v[46:49], v[166:169], v[210:213], v[46:49]
	v_mfma_f32_16x16x32_bf16 v[38:41], v[174:177], v[210:213], v[38:41]
	v_mfma_f32_16x16x32_bf16 v[30:33], v[166:169], v[218:221], v[30:33]
	v_mfma_f32_16x16x32_bf16 v[22:25], v[174:177], v[218:221], v[22:25]
	v_mfma_f32_16x16x32_bf16 v[14:17], v[166:169], v[226:229], v[14:17]
	v_mfma_f32_16x16x32_bf16 v[6:9], v[174:177], v[226:229], v[6:9]
	v_mfma_f32_16x16x32_bf16 v[62:65], v[170:173], v[206:209], v[62:65]
	v_mfma_f32_16x16x32_bf16 v[54:57], v[178:181], v[206:209], v[54:57]
	v_mfma_f32_16x16x32_bf16 v[46:49], v[170:173], v[214:217], v[46:49]
	v_mfma_f32_16x16x32_bf16 v[38:41], v[178:181], v[214:217], v[38:41]
	v_mfma_f32_16x16x32_bf16 v[30:33], v[170:173], v[222:225], v[30:33]
	v_mfma_f32_16x16x32_bf16 v[22:25], v[178:181], v[222:225], v[22:25]
	v_mfma_f32_16x16x32_bf16 v[14:17], v[170:173], v[230:233], v[14:17]
	v_mfma_f32_16x16x32_bf16 v[6:9], v[178:181], v[230:233], v[6:9]
	v_mfma_f32_16x16x32_bf16 v[58:61], v[186:189], v[202:205], v[58:61]
	v_mfma_f32_16x16x32_bf16 v[50:53], v[194:197], v[202:205], v[50:53]
	v_mfma_f32_16x16x32_bf16 v[42:45], v[186:189], v[210:213], v[42:45]
	v_mfma_f32_16x16x32_bf16 v[34:37], v[194:197], v[210:213], v[34:37]
	v_mfma_f32_16x16x32_bf16 v[26:29], v[186:189], v[218:221], v[26:29]
	v_mfma_f32_16x16x32_bf16 v[18:21], v[194:197], v[218:221], v[18:21]
	v_mfma_f32_16x16x32_bf16 v[10:13], v[186:189], v[226:229], v[10:13]
	v_mfma_f32_16x16x32_bf16 v[2:5], v[194:197], v[226:229], v[2:5]
	v_mfma_f32_16x16x32_bf16 v[58:61], v[190:193], v[206:209], v[58:61]
	v_mfma_f32_16x16x32_bf16 v[50:53], v[198:201], v[206:209], v[50:53]
	v_mfma_f32_16x16x32_bf16 v[42:45], v[190:193], v[214:217], v[42:45]
	v_mfma_f32_16x16x32_bf16 v[34:37], v[198:201], v[214:217], v[34:37]
	v_mfma_f32_16x16x32_bf16 v[26:29], v[190:193], v[222:225], v[26:29]
	v_mfma_f32_16x16x32_bf16 v[18:21], v[198:201], v[222:225], v[18:21]
	v_mfma_f32_16x16x32_bf16 v[10:13], v[190:193], v[230:233], v[10:13]
	v_mfma_f32_16x16x32_bf16 v[2:5], v[198:201], v[230:233], v[2:5]
	s_setprio 0
	s_barrier
	s_add_i32 s65, s65, 2
	s_add_u32 s40, s40, 0x100
	s_addc_u32 s41, s41, 0
	s_add_u32 s63, s63, 0x100
	s_addc_u32 s64, s64, 0
	s_cmp_gt_u32 s65, 13
	s_cbranch_scc0 .LBB0_1234
	s_and_b64 vcc, exec, s[18:19]
	s_cbranch_vccz .LBB0_1237
	s_barrier

; #define PG8_STAGE(bufoff, gbase, voff) do { _Pragma("unroll") for (int _i = 0; _i < 2; ++_i) \
;         __builtin_amdgcn_global_load_lds((const unsigned*)((const char*)(gbase) + (voff)[_i]), (LAS unsigned*)(lds + (bufoff) + ldsw + _i * 8192), 16, 0, 0); } while (0)
; #define PG8_LDA(dst, b, h) do { _Pragma("unroll") for (int m = 0; m < 4; ++m) _Pragma("unroll") for (int k = 0; k < 2; ++k) dst[m][k] = *(const LAS bf16x8*)(lds + PG8_SA(b, h) + aoff + m * 2048 + k * 1024); } while (0)
; #define PG8_LDB(dst, b, h) do { _Pragma("unroll") for (int n = 0; n < 2; ++n) _Pragma("unroll") for (int k = 0; k < 2; ++k) dst[n][k] = *(const LAS bf16x8*)(lds + PG8_SB(b, h) + boff + n * 2048 + k * 1024); } while (0)
; #define PG8_MMA(ai, bj, At, Bt) do { __builtin_amdgcn_s_setprio(1); _Pragma("unroll") for (int m = 0; m < 4; ++m) _Pragma("unroll") for (int n = 0; n < 2; ++n) _Pragma("unroll") for (int k = 0; k < 2; ++k) \
;         acc[ai][bj][m][n] = __builtin_amdgcn_mfma_f32_16x16x32_bf16(Bt[n][k], At[m][k], acc[ai][bj][m][n], 0, 0, 0); __builtin_amdgcn_s_setprio(0); } while (0)
; #define PG8_WAIT_V(n) asm volatile("s_waitcnt vmcnt(" #n ")" ::: "memory")
; #define PG8_WAIT_L(n) asm volatile("s_waitcnt lgkmcnt(" #n ")" ::: "memory")
; #define PG8_BAR __builtin_amdgcn_s_barrier()
; #define PG8_SCHED __builtin_amdgcn_sched_barrier(0)
; template <class Epi, class Sched>
; DI void gemm_phase(LAS unsigned char* lds, const Gemm g, const Sched& S, const Epi& E) {
;     ...
;             const bool last = (t == nt - 2);
;             const char* a1 = cA + (size_t)(t + 1) * kstep;
;             const char* a2 = last ? nA : cA + (size_t)(t + 2) * kstep; const char* b2 = last ? nB : cB + (size_t)(t + 2) * kstep;
;             const char* a3 = a2 + kstep; const char* b3 = b2 + kstep;
;             PG8_LDB(B0, 0, 0); PG8_LDB(B1, 0, 1); PG8_SCHED; PG8_LDA(At, 0, 0); PG8_STAGE(PG8_SA(1, 1), a1 + hstepA, voffA);
;             PG8_WAIT_V(8); PG8_WAIT_L(0); PG8_BAR; PG8_MMA(0, 0, At, B0); PG8_MMA(0, 1, At, B1); PG8_BAR; PG8_SCHED;
;             PG8_LDA(At, 0, 1); PG8_STAGE(PG8_SB(0, 0), b2, voffB); PG8_STAGE(PG8_SB(0, 1), b2 + hstepB, voffB); PG8_STAGE(PG8_SA(0, 0), a2, voffA);
;             PG8_WAIT_V(8); PG8_WAIT_L(0); PG8_BAR; PG8_MMA(1, 0, At, B0); PG8_MMA(1, 1, At, B1); PG8_BAR; PG8_SCHED;
.LBB0_1331:
	ds_read_b128 v[144:147], v151
	ds_read_b128 v[154:157], v151 offset:1024
	ds_read_b128 v[158:161], v151 offset:2048
	ds_read_b128 v[162:165], v151 offset:3072
	ds_read_b128 v[166:169], v152
	ds_read_b128 v[170:173], v152 offset:1024
	ds_read_b128 v[174:177], v152 offset:2048
	ds_read_b128 v[178:181], v152 offset:3072
	s_add_u32 s18, s16, 0xfff50080
	s_addc_u32 s19, s17, -1
	s_cmp_eq_u32 s47, 40
	s_cselect_b32 s21, s5, s19
	s_cselect_b32 s20, s4, s18
	s_cselect_b32 s19, s15, s46
	s_cselect_b32 s18, s14, s45
	v_lshl_add_u64 v[214:215], s[16:17], 0, v[136:137]
	s_add_i32 m0, s28, 0xc000
	ds_read_b128 v[182:185], v153
	ds_read_b128 v[186:189], v153 offset:1024
	ds_read_b128 v[190:193], v153 offset:2048
	ds_read_b128 v[194:197], v153 offset:3072
	ds_read_b128 v[198:201], v153 offset:4096
	ds_read_b128 v[202:205], v153 offset:5120
	ds_read_b128 v[206:209], v153 offset:6144
	ds_read_b128 v[210:213], v153 offset:7168
	global_load_lds_dwordx4 v[214:215], off
	v_lshl_add_u64 v[214:215], s[16:17], 0, v[138:139]
	s_add_i32 m0, s28, 0xe000
	s_nop 0
	global_load_lds_dwordx4 v[214:215], off
	s_waitcnt vmcnt(8)
	s_waitcnt lgkmcnt(0)
	s_barrier
	s_setprio 1
	v_mfma_f32_16x16x32_bf16 v[124:127], v[144:147], v[182:185], v[124:127]
	v_mfma_f32_16x16x32_bf16 v[120:123], v[158:161], v[182:185], v[120:123]
	v_mfma_f32_16x16x32_bf16 v[108:111], v[144:147], v[190:193], v[108:111]
	v_mfma_f32_16x16x32_bf16 v[104:107], v[158:161], v[190:193], v[104:107]
	v_mfma_f32_16x16x32_bf16 v[92:95], v[144:147], v[198:201], v[92:95]
	v_mfma_f32_16x16x32_bf16 v[88:91], v[158:161], v[198:201], v[88:91]
	v_mfma_f32_16x16x32_bf16 v[76:79], v[144:147], v[206:209], v[76:79]
	v_mfma_f32_16x16x32_bf16 v[72:75], v[158:161], v[206:209], v[72:75]
	v_mfma_f32_16x16x32_bf16 v[124:127], v[154:157], v[186:189], v[124:127]
	v_mfma_f32_16x16x32_bf16 v[120:123], v[162:165], v[186:189], v[120:123]
	v_mfma_f32_16x16x32_bf16 v[108:111], v[154:157], v[194:197], v[108:111]
	v_mfma_f32_16x16x32_bf16 v[104:107], v[162:165], v[194:197], v[104:107]
	v_mfma_f32_16x16x32_bf16 v[92:95], v[154:157], v[202:205], v[92:95]
	v_mfma_f32_16x16x32_bf16 v[88:91], v[162:165], v[202:205], v[88:91]
	v_mfma_f32_16x16x32_bf16 v[76:79], v[154:157], v[210:213], v[76:79]
	v_mfma_f32_16x16x32_bf16 v[72:75], v[162:165], v[210:213], v[72:75]
	v_mfma_f32_16x16x32_bf16 v[116:119], v[166:169], v[182:185], v[116:119]
	v_mfma_f32_16x16x32_bf16 v[112:115], v[174:177], v[182:185], v[112:115]
	v_mfma_f32_16x16x32_bf16 v[100:103], v[166:169], v[190:193], v[100:103]
	v_mfma_f32_16x16x32_bf16 v[96:99], v[174:177], v[190:193], v[96:99]
	v_mfma_f32_16x16x32_bf16 v[84:87], v[166:169], v[198:201], v[84:87]
	v_mfma_f32_16x16x32_bf16 v[80:83], v[174:177], v[198:201], v[80:83]
	v_mfma_f32_16x16x32_bf16 v[68:71], v[166:169], v[206:209], v[68:71]
	v_mfma_f32_16x16x32_bf16 v[64:67], v[174:177], v[206:209], v[64:67]
	v_mfma_f32_16x16x32_bf16 v[116:119], v[170:173], v[186:189], v[116:119]
	v_mfma_f32_16x16x32_bf16 v[112:115], v[178:181], v[186:189], v[112:115]
	v_mfma_f32_16x16x32_bf16 v[100:103], v[170:173], v[194:197], v[100:103]
	v_mfma_f32_16x16x32_bf16 v[96:99], v[178:181], v[194:197], v[96:99]
	v_mfma_f32_16x16x32_bf16 v[84:87], v[170:173], v[202:205], v[84:87]
	v_mfma_f32_16x16x32_bf16 v[80:83], v[178:181], v[202:205], v[80:83]
	v_mfma_f32_16x16x32_bf16 v[68:71], v[170:173], v[210:213], v[68:71]
	v_mfma_f32_16x16x32_bf16 v[64:67], v[178:181], v[210:213], v[64:67]
	s_setprio 0
	s_barrier
	s_add_i32 s48, s39, s27
	v_lshl_add_u64 v[214:215], s[18:19], 0, v[130:131]
	s_mov_b32 m0, s48
	ds_read_b128 v[182:185], v153 offset:16384
	ds_read_b128 v[186:189], v153 offset:17408
	ds_read_b128 v[190:193], v153 offset:18432
	ds_read_b128 v[194:197], v153 offset:19456
	ds_read_b128 v[198:201], v153 offset:20480
	ds_read_b128 v[202:205], v153 offset:21504
	ds_read_b128 v[206:209], v153 offset:22528
	ds_read_b128 v[210:213], v153 offset:23552
	global_load_lds_dwordx4 v[214:215], off
	s_add_i32 m0, s48, 0x2000
	s_add_u32 s48, s18, 0xb0000
	v_lshl_add_u64 v[216:217], s[18:19], 0, v[134:135]
	s_addc_u32 s49, s19, 0
	s_add_i32 s50, s40, s27
	global_load_lds_dwordx4 v[216:217], off
	v_lshl_add_u64 v[218:219], s[48:49], 0, v[130:131]
	s_mov_b32 m0, s50
	v_lshl_add_u64 v[220:221], s[20:21], 0, v[132:133]
	global_load_lds_dwordx4 v[218:219], off
	v_lshl_add_u64 v[218:219], s[48:49], 0, v[134:135]
	s_add_i32 m0, s50, 0x2000
	s_nop 0
	global_load_lds_dwordx4 v[218:219], off
	v_lshl_add_u64 v[218:219], s[20:21], 0, v[128:129]
	s_mov_b32 m0, s28
	s_nop 0
	global_load_lds_dwordx4 v[218:219], off
	s_mov_b32 m0, s29
	s_nop 0
	global_load_lds_dwordx4 v[220:221], off
	s_waitcnt vmcnt(8)
	s_waitcnt lgkmcnt(0)
	s_barrier
; #define PG8_STAGE(bufoff, gbase, voff) do { _Pragma("unroll") for (int _i = 0; _i < 2; ++_i) \
;         __builtin_amdgcn_global_load_lds((const unsigned*)((const char*)(gbase) + (voff)[_i]), (LAS unsigned*)(lds + (bufoff) + ldsw + _i * 8192), 16, 0, 0); } while (0)
; #define PG8_LDA(dst, b, h) do { _Pragma("unroll") for (int m = 0; m < 4; ++m) _Pragma("unroll") for (int k = 0; k < 2; ++k) dst[m][k] = *(const LAS bf16x8*)(lds + PG8_SA(b, h) + aoff + m * 2048 + k * 1024); } while (0)
; #define PG8_LDB(dst, b, h) do { _Pragma("unroll") for (int n = 0; n < 2; ++n) _Pragma("unroll") for (int k = 0; k < 2; ++k) dst[n][k] = *(const LAS bf16x8*)(lds + PG8_SB(b, h) + boff + n * 2048 + k * 1024); } while (0)
; #define PG8_MMA(ai, bj, At, Bt) do { __builtin_amdgcn_s_setprio(1); _Pragma("unroll") for (int m = 0; m < 4; ++m) _Pragma("unroll") for (int n = 0; n < 2; ++n) _Pragma("unroll") for (int k = 0; k < 2; ++k) \
;         acc[ai][bj][m][n] = __builtin_amdgcn_mfma_f32_16x16x32_bf16(Bt[n][k], At[m][k], acc[ai][bj][m][n], 0, 0, 0); __builtin_amdgcn_s_setprio(0); } while (0)
; #define PG8_WAIT_V(n) asm volatile("s_waitcnt vmcnt(" #n ")" ::: "memory")
; #define PG8_WAIT_L(n) asm volatile("s_waitcnt lgkmcnt(" #n ")" ::: "memory")
; #define PG8_BAR __builtin_amdgcn_s_barrier()
; #define PG8_SCHED __builtin_amdgcn_sched_barrier(0)
; template <class Epi, class Sched>
; DI void gemm_phase(LAS unsigned char* lds, const Gemm g, const Sched& S, const Epi& E) {
;     ...
;             PG8_WAIT_V(8); PG8_WAIT_L(0); PG8_BAR; PG8_MMA(1, 0, At, B0); PG8_MMA(1, 1, At, B1); PG8_BAR; PG8_SCHED;
;             PG8_LDB(B0, 1, 0); PG8_LDB(B1, 1, 1); PG8_SCHED; PG8_LDA(At, 1, 0); PG8_STAGE(PG8_SA(0, 1), a2 + hstepA, voffA);
;             PG8_WAIT_V(8); PG8_WAIT_L(0); PG8_BAR; PG8_MMA(0, 0, At, B0); PG8_MMA(0, 1, At, B1); PG8_BAR; PG8_SCHED;
	s_setprio 1
	v_mfma_f32_16x16x32_bf16 v[60:63], v[144:147], v[182:185], v[60:63]
	v_mfma_f32_16x16x32_bf16 v[56:59], v[158:161], v[182:185], v[56:59]
	v_mfma_f32_16x16x32_bf16 v[44:47], v[144:147], v[190:193], v[44:47]
	v_mfma_f32_16x16x32_bf16 v[40:43], v[158:161], v[190:193], v[40:43]
	v_mfma_f32_16x16x32_bf16 v[28:31], v[144:147], v[198:201], v[28:31]
	v_mfma_f32_16x16x32_bf16 v[24:27], v[158:161], v[198:201], v[24:27]
	v_mfma_f32_16x16x32_bf16 v[12:15], v[144:147], v[206:209], v[12:15]
	v_mfma_f32_16x16x32_bf16 v[8:11], v[158:161], v[206:209], v[8:11]
	v_mfma_f32_16x16x32_bf16 v[60:63], v[154:157], v[186:189], v[60:63]
	v_mfma_f32_16x16x32_bf16 v[56:59], v[162:165], v[186:189], v[56:59]
	v_mfma_f32_16x16x32_bf16 v[44:47], v[154:157], v[194:197], v[44:47]
	v_mfma_f32_16x16x32_bf16 v[40:43], v[162:165], v[194:197], v[40:43]
	v_mfma_f32_16x16x32_bf16 v[28:31], v[154:157], v[202:205], v[28:31]
	v_mfma_f32_16x16x32_bf16 v[24:27], v[162:165], v[202:205], v[24:27]
	v_mfma_f32_16x16x32_bf16 v[12:15], v[154:157], v[210:213], v[12:15]
	v_mfma_f32_16x16x32_bf16 v[8:11], v[162:165], v[210:213], v[8:11]
	v_mfma_f32_16x16x32_bf16 v[52:55], v[166:169], v[182:185], v[52:55]
	v_mfma_f32_16x16x32_bf16 v[48:51], v[174:177], v[182:185], v[48:51]
	v_mfma_f32_16x16x32_bf16 v[36:39], v[166:169], v[190:193], v[36:39]
	v_mfma_f32_16x16x32_bf16 v[32:35], v[174:177], v[190:193], v[32:35]
	v_mfma_f32_16x16x32_bf16 v[20:23], v[166:169], v[198:201], v[20:23]
	v_mfma_f32_16x16x32_bf16 v[16:19], v[174:177], v[198:201], v[16:19]
	v_mfma_f32_16x16x32_bf16 v[4:7], v[166:169], v[206:209], v[4:7]
	v_mfma_f32_16x16x32_bf16 v[0:3], v[174:177], v[206:209], v[0:3]
	v_mfma_f32_16x16x32_bf16 v[52:55], v[170:173], v[186:189], v[52:55]
	v_mfma_f32_16x16x32_bf16 v[48:51], v[178:181], v[186:189], v[48:51]
	v_mfma_f32_16x16x32_bf16 v[36:39], v[170:173], v[194:197], v[36:39]
	v_mfma_f32_16x16x32_bf16 v[32:35], v[178:181], v[194:197], v[32:35]
	v_mfma_f32_16x16x32_bf16 v[20:23], v[170:173], v[202:205], v[20:23]
	v_mfma_f32_16x16x32_bf16 v[16:19], v[178:181], v[202:205], v[16:19]
	v_mfma_f32_16x16x32_bf16 v[4:7], v[170:173], v[210:213], v[4:7]
	v_mfma_f32_16x16x32_bf16 v[0:3], v[178:181], v[210:213], v[0:3]
	s_setprio 0
	s_barrier
	s_add_i32 s48, 0, 0x18000
	s_add_i32 s49, 0, 0x1c000
	v_add_u32_e32 v162, s48, v149
	v_add_u32_e32 v178, s49, v149
	ds_read_b128 v[144:147], v162
	ds_read_b128 v[154:157], v162 offset:1024
	ds_read_b128 v[158:161], v162 offset:2048
	ds_read_b128 v[162:165], v162 offset:3072
	ds_read_b128 v[166:169], v178
	ds_read_b128 v[170:173], v178 offset:1024
	ds_read_b128 v[174:177], v178 offset:2048
	ds_read_b128 v[178:181], v178 offset:3072
	s_add_u32 s20, s20, 0xb0000
	s_addc_u32 s21, s21, 0
	s_mov_b32 m0, s33
	v_lshl_add_u64 v[222:223], s[20:21], 0, v[128:129]
	ds_read_b128 v[182:185], v153 offset:32768
	ds_read_b128 v[186:189], v153 offset:33792
	ds_read_b128 v[190:193], v153 offset:34816
	ds_read_b128 v[194:197], v153 offset:35840
	ds_read_b128 v[198:201], v153 offset:36864
	ds_read_b128 v[202:205], v153 offset:37888
	ds_read_b128 v[206:209], v153 offset:38912
	ds_read_b128 v[210:213], v153 offset:39936
	global_load_lds_dwordx4 v[222:223], off
	v_lshl_add_u64 v[222:223], s[20:21], 0, v[132:133]
	s_mov_b32 m0, s34
	s_nop 0
	global_load_lds_dwordx4 v[222:223], off
	s_waitcnt vmcnt(8)
	s_waitcnt lgkmcnt(0)
	s_barrier
	s_setprio 1
	v_mfma_f32_16x16x32_bf16 v[124:127], v[144:147], v[182:185], v[124:127]
	v_mfma_f32_16x16x32_bf16 v[120:123], v[158:161], v[182:185], v[120:123]
	v_mfma_f32_16x16x32_bf16 v[108:111], v[144:147], v[190:193], v[108:111]
	v_mfma_f32_16x16x32_bf16 v[104:107], v[158:161], v[190:193], v[104:107]
	v_mfma_f32_16x16x32_bf16 v[92:95], v[144:147], v[198:201], v[92:95]
	v_mfma_f32_16x16x32_bf16 v[88:91], v[158:161], v[198:201], v[88:91]
	v_mfma_f32_16x16x32_bf16 v[76:79], v[144:147], v[206:209], v[76:79]
	v_mfma_f32_16x16x32_bf16 v[72:75], v[158:161], v[206:209], v[72:75]
	v_mfma_f32_16x16x32_bf16 v[124:127], v[154:157], v[186:189], v[124:127]
	v_mfma_f32_16x16x32_bf16 v[120:123], v[162:165], v[186:189], v[120:123]
	v_mfma_f32_16x16x32_bf16 v[108:111], v[154:157], v[194:197], v[108:111]
	v_mfma_f32_16x16x32_bf16 v[104:107], v[162:165], v[194:197], v[104:107]
	v_mfma_f32_16x16x32_bf16 v[92:95], v[154:157], v[202:205], v[92:95]
	v_mfma_f32_16x16x32_bf16 v[88:91], v[162:165], v[202:205], v[88:91]
	v_mfma_f32_16x16x32_bf16 v[76:79], v[154:157], v[210:213], v[76:79]
	v_mfma_f32_16x16x32_bf16 v[72:75], v[162:165], v[210:213], v[72:75]
	v_mfma_f32_16x16x32_bf16 v[116:119], v[166:169], v[182:185], v[116:119]
	v_mfma_f32_16x16x32_bf16 v[112:115], v[174:177], v[182:185], v[112:115]
	v_mfma_f32_16x16x32_bf16 v[100:103], v[166:169], v[190:193], v[100:103]
	v_mfma_f32_16x16x32_bf16 v[96:99], v[174:177], v[190:193], v[96:99]
	v_mfma_f32_16x16x32_bf16 v[84:87], v[166:169], v[198:201], v[84:87]
	v_mfma_f32_16x16x32_bf16 v[80:83], v[174:177], v[198:201], v[80:83]
	v_mfma_f32_16x16x32_bf16 v[68:71], v[166:169], v[206:209], v[68:71]
	v_mfma_f32_16x16x32_bf16 v[64:67], v[174:177], v[206:209], v[64:67]
	v_mfma_f32_16x16x32_bf16 v[116:119], v[170:173], v[186:189], v[116:119]
	v_mfma_f32_16x16x32_bf16 v[112:115], v[178:181], v[186:189], v[112:115]
	v_mfma_f32_16x16x32_bf16 v[100:103], v[170:173], v[194:197], v[100:103]
	v_mfma_f32_16x16x32_bf16 v[96:99], v[178:181], v[194:197], v[96:99]
	v_mfma_f32_16x16x32_bf16 v[84:87], v[170:173], v[202:205], v[84:87]
	v_mfma_f32_16x16x32_bf16 v[80:83], v[178:181], v[202:205], v[80:83]
	v_mfma_f32_16x16x32_bf16 v[68:71], v[170:173], v[210:213], v[68:71]
	v_mfma_f32_16x16x32_bf16 v[64:67], v[178:181], v[210:213], v[64:67]
	s_setprio 0
	s_barrier
; #define PG8_STAGE(bufoff, gbase, voff) do { _Pragma("unroll") for (int _i = 0; _i < 2; ++_i) \
;         __builtin_amdgcn_global_load_lds((const unsigned*)((const char*)(gbase) + (voff)[_i]), (LAS unsigned*)(lds + (bufoff) + ldsw + _i * 8192), 16, 0, 0); } while (0)
; #define PG8_LDA(dst, b, h) do { _Pragma("unroll") for (int m = 0; m < 4; ++m) _Pragma("unroll") for (int k = 0; k < 2; ++k) dst[m][k] = *(const LAS bf16x8*)(lds + PG8_SA(b, h) + aoff + m * 2048 + k * 1024); } while (0)
; #define PG8_MMA(ai, bj, At, Bt) do { __builtin_amdgcn_s_setprio(1); _Pragma("unroll") for (int m = 0; m < 4; ++m) _Pragma("unroll") for (int n = 0; n < 2; ++n) _Pragma("unroll") for (int k = 0; k < 2; ++k) \
;         acc[ai][bj][m][n] = __builtin_amdgcn_mfma_f32_16x16x32_bf16(Bt[n][k], At[m][k], acc[ai][bj][m][n], 0, 0, 0); __builtin_amdgcn_s_setprio(0); } while (0)
; #define PG8_WAIT_V(n) asm volatile("s_waitcnt vmcnt(" #n ")" ::: "memory")
; #define PG8_WAIT_L(n) asm volatile("s_waitcnt lgkmcnt(" #n ")" ::: "memory")
; #define PG8_BAR __builtin_amdgcn_s_barrier()
; #define PG8_SCHED __builtin_amdgcn_sched_barrier(0)
; template <class Epi, class Sched>
; DI void gemm_phase(LAS unsigned char* lds, const Gemm g, const Sched& S, const Epi& E) {
;     ...
;             PG8_LDA(At, 1, 1); PG8_STAGE(PG8_SB(1, 0), b3, voffB); PG8_STAGE(PG8_SB(1, 1), b3 + hstepB, voffB); PG8_STAGE(PG8_SA(1, 0), a3, voffA);
;             PG8_WAIT_V(8); PG8_WAIT_L(0); PG8_BAR; PG8_MMA(1, 0, At, B0); PG8_MMA(1, 1, At, B1); PG8_BAR; PG8_SCHED;
;         }
;         if (wr == 0) PG8_BAR;
	s_add_i32 s20, s48, s27
	v_lshl_add_u64 v[214:215], v[214:215], 0, s[10:11]
	s_mov_b32 m0, s20
	ds_read_b128 v[182:185], v153 offset:49152
	ds_read_b128 v[186:189], v153 offset:50176
	ds_read_b128 v[190:193], v153 offset:51200
	ds_read_b128 v[194:197], v153 offset:52224
	ds_read_b128 v[198:201], v153 offset:53248
	ds_read_b128 v[202:205], v153 offset:54272
	ds_read_b128 v[206:209], v153 offset:55296
	ds_read_b128 v[210:213], v153 offset:56320
	global_load_lds_dwordx4 v[214:215], off
	s_add_i32 m0, s20, 0x2000
	s_add_u32 s18, s18, 0xb0080
	v_lshl_add_u64 v[214:215], v[216:217], 0, s[10:11]
	s_addc_u32 s19, s19, 0
	s_add_i32 s20, s49, s27
	global_load_lds_dwordx4 v[214:215], off
	v_lshl_add_u64 v[214:215], s[18:19], 0, v[130:131]
	s_mov_b32 m0, s20
	s_nop 0
	global_load_lds_dwordx4 v[214:215], off
	v_lshl_add_u64 v[214:215], s[18:19], 0, v[134:135]
	s_add_i32 m0, s20, 0x2000
	s_nop 0
	global_load_lds_dwordx4 v[214:215], off
	v_lshl_add_u64 v[214:215], v[218:219], 0, s[10:11]
	s_mov_b32 m0, s36
	s_nop 0
	global_load_lds_dwordx4 v[214:215], off
	v_lshl_add_u64 v[214:215], v[220:221], 0, s[10:11]
	s_mov_b32 m0, s37
	s_nop 0
	global_load_lds_dwordx4 v[214:215], off
	s_waitcnt vmcnt(8)
	s_waitcnt lgkmcnt(0)
	s_barrier
	s_setprio 1
	v_mfma_f32_16x16x32_bf16 v[60:63], v[144:147], v[182:185], v[60:63]
	v_mfma_f32_16x16x32_bf16 v[56:59], v[158:161], v[182:185], v[56:59]
	v_mfma_f32_16x16x32_bf16 v[44:47], v[144:147], v[190:193], v[44:47]
	v_mfma_f32_16x16x32_bf16 v[40:43], v[158:161], v[190:193], v[40:43]
	v_mfma_f32_16x16x32_bf16 v[28:31], v[144:147], v[198:201], v[28:31]
	v_mfma_f32_16x16x32_bf16 v[24:27], v[158:161], v[198:201], v[24:27]
	v_mfma_f32_16x16x32_bf16 v[12:15], v[144:147], v[206:209], v[12:15]
	v_mfma_f32_16x16x32_bf16 v[8:11], v[158:161], v[206:209], v[8:11]
	v_mfma_f32_16x16x32_bf16 v[60:63], v[154:157], v[186:189], v[60:63]
	v_mfma_f32_16x16x32_bf16 v[56:59], v[162:165], v[186:189], v[56:59]
	v_mfma_f32_16x16x32_bf16 v[44:47], v[154:157], v[194:197], v[44:47]
	v_mfma_f32_16x16x32_bf16 v[40:43], v[162:165], v[194:197], v[40:43]
	v_mfma_f32_16x16x32_bf16 v[28:31], v[154:157], v[202:205], v[28:31]
	v_mfma_f32_16x16x32_bf16 v[24:27], v[162:165], v[202:205], v[24:27]
	v_mfma_f32_16x16x32_bf16 v[12:15], v[154:157], v[210:213], v[12:15]
	v_mfma_f32_16x16x32_bf16 v[8:11], v[162:165], v[210:213], v[8:11]
	v_mfma_f32_16x16x32_bf16 v[52:55], v[166:169], v[182:185], v[52:55]
	v_mfma_f32_16x16x32_bf16 v[48:51], v[174:177], v[182:185], v[48:51]
	v_mfma_f32_16x16x32_bf16 v[36:39], v[166:169], v[190:193], v[36:39]
	v_mfma_f32_16x16x32_bf16 v[32:35], v[174:177], v[190:193], v[32:35]
	v_mfma_f32_16x16x32_bf16 v[20:23], v[166:169], v[198:201], v[20:23]
	v_mfma_f32_16x16x32_bf16 v[16:19], v[174:177], v[198:201], v[16:19]
	v_mfma_f32_16x16x32_bf16 v[4:7], v[166:169], v[206:209], v[4:7]
	v_mfma_f32_16x16x32_bf16 v[0:3], v[174:177], v[206:209], v[0:3]
	v_mfma_f32_16x16x32_bf16 v[52:55], v[170:173], v[186:189], v[52:55]
	v_mfma_f32_16x16x32_bf16 v[48:51], v[178:181], v[186:189], v[48:51]
	v_mfma_f32_16x16x32_bf16 v[36:39], v[170:173], v[194:197], v[36:39]
	v_mfma_f32_16x16x32_bf16 v[32:35], v[178:181], v[194:197], v[32:35]
	v_mfma_f32_16x16x32_bf16 v[20:23], v[170:173], v[202:205], v[20:23]
	v_mfma_f32_16x16x32_bf16 v[16:19], v[178:181], v[202:205], v[16:19]
	v_mfma_f32_16x16x32_bf16 v[4:7], v[170:173], v[210:213], v[4:7]
	v_mfma_f32_16x16x32_bf16 v[0:3], v[178:181], v[210:213], v[0:3]
	s_setprio 0
	s_barrier
	s_add_i32 s47, s47, 2
	s_add_u32 s16, s16, 0x100
	s_addc_u32 s17, s17, 0
	s_add_u32 s45, s45, 0x100
	s_addc_u32 s46, s46, 0
	s_cmp_gt_u32 s47, 41
	s_cbranch_scc0 .LBB0_1331
	s_and_b64 vcc, exec, s[12:13]
	s_cbranch_vccz .LBB0_1334
	s_barrier
